# v31 + gated o-proj epilogues: IEEE-division Newton steps as packed f32 on element pairs (as in the FFN-up epilogue), same arithmetic
# baseline (speedup 1.0000x reference)
.Lepi3:
	v_mul_u32_u24_e32 v176, 0x1800, v150
	v_lshl_add_u32 v176, v148, 1, v176
	v_add_u32_e32 v176, 0x800, v176
	v_lshlrev_b32_e32 v184, 11, v150
	v_lshl_add_u32 v184, v148, 1, v184
	v_add_u32_e32 v177, 0x18000, v176
	v_add_u32_e32 v185, 0x8000, v184
	v_add_u32_e32 v178, 0x30000, v176
	v_add_u32_e32 v186, 0x10000, v184
	v_add_u32_e32 v179, 0x48000, v176
	v_add_u32_e32 v187, 0x18000, v184
	v_add_u32_e32 v180, 0xc0000, v176
	v_add_u32_e32 v188, 0x40000, v184
	v_add_u32_e32 v181, 0xd8000, v176
	v_add_u32_e32 v189, 0x48000, v184
	v_add_u32_e32 v182, 0xf0000, v176
	v_add_u32_e32 v190, 0x50000, v184
	v_add_u32_e32 v183, 0x108000, v176
	v_add_u32_e32 v191, 0x58000, v184
	global_load_dwordx4 v[192:195], v176, s[64:65]
	global_load_dwordx4 v[200:203], v176, s[64:65] offset:256
	global_load_dwordx4 v[208:211], v177, s[64:65]
	global_load_dwordx4 v[216:219], v177, s[64:65] offset:256
	s_waitcnt vmcnt(3)
	v_lshlrev_b32_e32 v152, 16, v192
	v_and_b32_e32 v153, 0xffff0000, v192
	v_lshlrev_b32_e32 v154, 16, v193
	v_and_b32_e32 v155, 0xffff0000, v193
	v_lshlrev_b32_e32 v156, 16, v194
	v_and_b32_e32 v157, 0xffff0000, v194
	v_lshlrev_b32_e32 v158, 16, v195
	v_and_b32_e32 v159, 0xffff0000, v195
	v_mul_f32_e32 v152, 0xbfb8aa3b, v152
	v_mul_f32_e32 v153, 0xbfb8aa3b, v153
	v_mul_f32_e32 v154, 0xbfb8aa3b, v154
	v_mul_f32_e32 v155, 0xbfb8aa3b, v155
	v_mul_f32_e32 v156, 0xbfb8aa3b, v156
	v_mul_f32_e32 v157, 0xbfb8aa3b, v157
	v_mul_f32_e32 v158, 0xbfb8aa3b, v158
	v_mul_f32_e32 v159, 0xbfb8aa3b, v159
	v_exp_f32_e32 v152, v152
	v_exp_f32_e32 v153, v153
	v_exp_f32_e32 v154, v154
	v_exp_f32_e32 v155, v155
	v_exp_f32_e32 v156, v156
	v_exp_f32_e32 v157, v157
	v_exp_f32_e32 v158, v158
	v_exp_f32_e32 v159, v159
	v_pk_add_f32 v[152:153], v[152:153], 1.0 op_sel_hi:[1,0]
	v_pk_add_f32 v[154:155], v[154:155], 1.0 op_sel_hi:[1,0]
	v_pk_add_f32 v[156:157], v[156:157], 1.0 op_sel_hi:[1,0]
	v_pk_add_f32 v[158:159], v[158:159], 1.0 op_sel_hi:[1,0]
	v_div_scale_f32 v160, s[38:39], v152, v152, 1.0
	v_div_scale_f32 v161, s[38:39], v153, v153, 1.0
	v_div_scale_f32 v162, s[38:39], v154, v154, 1.0
	v_div_scale_f32 v163, s[38:39], v155, v155, 1.0
	v_rcp_f32_e32 v164, v160
	v_rcp_f32_e32 v165, v161
	v_rcp_f32_e32 v166, v162
	v_rcp_f32_e32 v167, v163
	v_pk_fma_f32 v[148:149], v[160:161], v[164:165], 1.0 op_sel_hi:[1,1,0] neg_lo:[1,0,0] neg_hi:[1,0,0]
	v_pk_fma_f32 v[150:151], v[162:163], v[166:167], 1.0 op_sel_hi:[1,1,0] neg_lo:[1,0,0] neg_hi:[1,0,0]
	v_pk_fma_f32 v[164:165], v[148:149], v[164:165], v[164:165]
	v_pk_fma_f32 v[166:167], v[150:151], v[166:167], v[166:167]
	v_div_scale_f32 v168, s[2:3], 1.0, v152, 1.0
	v_div_scale_f32 v169, s[26:27], 1.0, v153, 1.0
	v_div_scale_f32 v170, s[28:29], 1.0, v154, 1.0
	v_div_scale_f32 v171, vcc, 1.0, v155, 1.0
	v_pk_mul_f32 v[128:129], v[168:169], v[164:165]
	v_pk_mul_f32 v[130:131], v[170:171], v[166:167]
	v_pk_fma_f32 v[148:149], v[160:161], v[128:129], v[168:169] neg_lo:[1,0,0] neg_hi:[1,0,0]
	v_pk_fma_f32 v[150:151], v[162:163], v[130:131], v[170:171] neg_lo:[1,0,0] neg_hi:[1,0,0]
	v_pk_fma_f32 v[128:129], v[148:149], v[164:165], v[128:129]
	v_pk_fma_f32 v[130:131], v[150:151], v[166:167], v[130:131]
	v_pk_fma_f32 v[160:161], v[160:161], v[128:129], v[168:169] neg_lo:[1,0,0] neg_hi:[1,0,0]
	v_pk_fma_f32 v[162:163], v[162:163], v[130:131], v[170:171] neg_lo:[1,0,0] neg_hi:[1,0,0]
	v_div_fmas_f32 v163, v163, v167, v131
	s_mov_b64 vcc, s[28:29]
	v_div_fmas_f32 v162, v162, v166, v130
	s_mov_b64 vcc, s[26:27]
	v_div_fmas_f32 v161, v161, v165, v129
	s_mov_b64 vcc, s[2:3]
	v_div_fmas_f32 v160, v160, v164, v128
	v_div_fixup_f32 v152, v160, v152, 1.0
	v_div_fixup_f32 v153, v161, v153, 1.0
	v_div_fixup_f32 v154, v162, v154, 1.0
	v_div_fixup_f32 v155, v163, v155, 1.0
	v_div_scale_f32 v160, s[38:39], v156, v156, 1.0
	v_div_scale_f32 v161, s[38:39], v157, v157, 1.0
	v_div_scale_f32 v162, s[38:39], v158, v158, 1.0
	v_div_scale_f32 v163, s[38:39], v159, v159, 1.0
	v_rcp_f32_e32 v164, v160
	v_rcp_f32_e32 v165, v161
	v_rcp_f32_e32 v166, v162
	v_rcp_f32_e32 v167, v163
	v_pk_fma_f32 v[148:149], v[160:161], v[164:165], 1.0 op_sel_hi:[1,1,0] neg_lo:[1,0,0] neg_hi:[1,0,0]
	v_pk_fma_f32 v[150:151], v[162:163], v[166:167], 1.0 op_sel_hi:[1,1,0] neg_lo:[1,0,0] neg_hi:[1,0,0]
	v_pk_fma_f32 v[164:165], v[148:149], v[164:165], v[164:165]
	v_pk_fma_f32 v[166:167], v[150:151], v[166:167], v[166:167]
	v_div_scale_f32 v168, s[2:3], 1.0, v156, 1.0
	v_div_scale_f32 v169, s[26:27], 1.0, v157, 1.0
	v_div_scale_f32 v170, s[28:29], 1.0, v158, 1.0
	v_div_scale_f32 v171, vcc, 1.0, v159, 1.0
	v_pk_mul_f32 v[128:129], v[168:169], v[164:165]
	v_pk_mul_f32 v[130:131], v[170:171], v[166:167]
	v_pk_fma_f32 v[148:149], v[160:161], v[128:129], v[168:169] neg_lo:[1,0,0] neg_hi:[1,0,0]
	v_pk_fma_f32 v[150:151], v[162:163], v[130:131], v[170:171] neg_lo:[1,0,0] neg_hi:[1,0,0]
	v_pk_fma_f32 v[128:129], v[148:149], v[164:165], v[128:129]
	v_pk_fma_f32 v[130:131], v[150:151], v[166:167], v[130:131]
	v_pk_fma_f32 v[160:161], v[160:161], v[128:129], v[168:169] neg_lo:[1,0,0] neg_hi:[1,0,0]
	v_pk_fma_f32 v[162:163], v[162:163], v[130:131], v[170:171] neg_lo:[1,0,0] neg_hi:[1,0,0]
	v_div_fmas_f32 v163, v163, v167, v131
	s_mov_b64 vcc, s[28:29]
	v_div_fmas_f32 v162, v162, v166, v130
	s_mov_b64 vcc, s[26:27]
	v_div_fmas_f32 v161, v161, v165, v129
	s_mov_b64 vcc, s[2:3]
	v_div_fmas_f32 v160, v160, v164, v128
	v_div_fixup_f32 v156, v160, v156, 1.0
	v_div_fixup_f32 v157, v161, v157, 1.0
	v_div_fixup_f32 v158, v162, v158, 1.0
	v_div_fixup_f32 v159, v163, v159, 1.0
	v_pk_mul_f32 v[152:153], v[124:125], v[152:153]
	v_pk_mul_f32 v[154:155], v[126:127], v[154:155]
	v_pk_mul_f32 v[156:157], v[120:121], v[156:157]
	v_pk_mul_f32 v[158:159], v[122:123], v[158:159]
	v_cvt_pk_bf16_f32 v168, v152, v153
	v_cvt_pk_bf16_f32 v169, v154, v155
	v_cvt_pk_bf16_f32 v170, v156, v157
	v_cvt_pk_bf16_f32 v171, v158, v159
	global_store_dwordx4 v184, v[168:171], s[68:69]
	global_load_dwordx4 v[124:127], v178, s[64:65]
	s_waitcnt vmcnt(4)
	v_lshlrev_b32_e32 v152, 16, v200
	v_and_b32_e32 v153, 0xffff0000, v200
	v_lshlrev_b32_e32 v154, 16, v201
	v_and_b32_e32 v155, 0xffff0000, v201
	v_lshlrev_b32_e32 v156, 16, v202
	v_and_b32_e32 v157, 0xffff0000, v202
	v_lshlrev_b32_e32 v158, 16, v203
	v_and_b32_e32 v159, 0xffff0000, v203
	v_mul_f32_e32 v152, 0xbfb8aa3b, v152
	v_mul_f32_e32 v153, 0xbfb8aa3b, v153
	v_mul_f32_e32 v154, 0xbfb8aa3b, v154
	v_mul_f32_e32 v155, 0xbfb8aa3b, v155
	v_mul_f32_e32 v156, 0xbfb8aa3b, v156
	v_mul_f32_e32 v157, 0xbfb8aa3b, v157
	v_mul_f32_e32 v158, 0xbfb8aa3b, v158
	v_mul_f32_e32 v159, 0xbfb8aa3b, v159
	v_exp_f32_e32 v152, v152
	v_exp_f32_e32 v153, v153
	v_exp_f32_e32 v154, v154
	v_exp_f32_e32 v155, v155
	v_exp_f32_e32 v156, v156
	v_exp_f32_e32 v157, v157
	v_exp_f32_e32 v158, v158
	v_exp_f32_e32 v159, v159
	v_pk_add_f32 v[152:153], v[152:153], 1.0 op_sel_hi:[1,0]
	v_pk_add_f32 v[154:155], v[154:155], 1.0 op_sel_hi:[1,0]
	v_pk_add_f32 v[156:157], v[156:157], 1.0 op_sel_hi:[1,0]
	v_pk_add_f32 v[158:159], v[158:159], 1.0 op_sel_hi:[1,0]
	v_div_scale_f32 v160, s[38:39], v152, v152, 1.0
	v_div_scale_f32 v161, s[38:39], v153, v153, 1.0
	v_div_scale_f32 v162, s[38:39], v154, v154, 1.0
	v_div_scale_f32 v163, s[38:39], v155, v155, 1.0
	v_rcp_f32_e32 v164, v160
	v_rcp_f32_e32 v165, v161
	v_rcp_f32_e32 v166, v162
	v_rcp_f32_e32 v167, v163
	v_pk_fma_f32 v[148:149], v[160:161], v[164:165], 1.0 op_sel_hi:[1,1,0] neg_lo:[1,0,0] neg_hi:[1,0,0]
	v_pk_fma_f32 v[150:151], v[162:163], v[166:167], 1.0 op_sel_hi:[1,1,0] neg_lo:[1,0,0] neg_hi:[1,0,0]
	v_pk_fma_f32 v[164:165], v[148:149], v[164:165], v[164:165]
	v_pk_fma_f32 v[166:167], v[150:151], v[166:167], v[166:167]
	v_div_scale_f32 v168, s[2:3], 1.0, v152, 1.0
	v_div_scale_f32 v169, s[26:27], 1.0, v153, 1.0
	v_div_scale_f32 v170, s[28:29], 1.0, v154, 1.0
	v_div_scale_f32 v171, vcc, 1.0, v155, 1.0
	v_pk_mul_f32 v[128:129], v[168:169], v[164:165]
	v_pk_mul_f32 v[130:131], v[170:171], v[166:167]
	v_pk_fma_f32 v[148:149], v[160:161], v[128:129], v[168:169] neg_lo:[1,0,0] neg_hi:[1,0,0]
	v_pk_fma_f32 v[150:151], v[162:163], v[130:131], v[170:171] neg_lo:[1,0,0] neg_hi:[1,0,0]
	v_pk_fma_f32 v[128:129], v[148:149], v[164:165], v[128:129]
	v_pk_fma_f32 v[130:131], v[150:151], v[166:167], v[130:131]
	v_pk_fma_f32 v[160:161], v[160:161], v[128:129], v[168:169] neg_lo:[1,0,0] neg_hi:[1,0,0]
	v_pk_fma_f32 v[162:163], v[162:163], v[130:131], v[170:171] neg_lo:[1,0,0] neg_hi:[1,0,0]
	v_div_fmas_f32 v163, v163, v167, v131
	s_mov_b64 vcc, s[28:29]
	v_div_fmas_f32 v162, v162, v166, v130
	s_mov_b64 vcc, s[26:27]
	v_div_fmas_f32 v161, v161, v165, v129
	s_mov_b64 vcc, s[2:3]
	v_div_fmas_f32 v160, v160, v164, v128
	v_div_fixup_f32 v152, v160, v152, 1.0
	v_div_fixup_f32 v153, v161, v153, 1.0
	v_div_fixup_f32 v154, v162, v154, 1.0
	v_div_fixup_f32 v155, v163, v155, 1.0
	v_div_scale_f32 v160, s[38:39], v156, v156, 1.0
	v_div_scale_f32 v161, s[38:39], v157, v157, 1.0
	v_div_scale_f32 v162, s[38:39], v158, v158, 1.0
	v_div_scale_f32 v163, s[38:39], v159, v159, 1.0
	v_rcp_f32_e32 v164, v160
	v_rcp_f32_e32 v165, v161
	v_rcp_f32_e32 v166, v162
	v_rcp_f32_e32 v167, v163
	v_pk_fma_f32 v[148:149], v[160:161], v[164:165], 1.0 op_sel_hi:[1,1,0] neg_lo:[1,0,0] neg_hi:[1,0,0]
	v_pk_fma_f32 v[150:151], v[162:163], v[166:167], 1.0 op_sel_hi:[1,1,0] neg_lo:[1,0,0] neg_hi:[1,0,0]
	v_pk_fma_f32 v[164:165], v[148:149], v[164:165], v[164:165]
	v_pk_fma_f32 v[166:167], v[150:151], v[166:167], v[166:167]
	v_div_scale_f32 v168, s[2:3], 1.0, v156, 1.0
	v_div_scale_f32 v169, s[26:27], 1.0, v157, 1.0
	v_div_scale_f32 v170, s[28:29], 1.0, v158, 1.0
	v_div_scale_f32 v171, vcc, 1.0, v159, 1.0
	v_pk_mul_f32 v[128:129], v[168:169], v[164:165]
	v_pk_mul_f32 v[130:131], v[170:171], v[166:167]
	v_pk_fma_f32 v[148:149], v[160:161], v[128:129], v[168:169] neg_lo:[1,0,0] neg_hi:[1,0,0]
	v_pk_fma_f32 v[150:151], v[162:163], v[130:131], v[170:171] neg_lo:[1,0,0] neg_hi:[1,0,0]
	v_pk_fma_f32 v[128:129], v[148:149], v[164:165], v[128:129]
	v_pk_fma_f32 v[130:131], v[150:151], v[166:167], v[130:131]
	v_pk_fma_f32 v[160:161], v[160:161], v[128:129], v[168:169] neg_lo:[1,0,0] neg_hi:[1,0,0]
	v_pk_fma_f32 v[162:163], v[162:163], v[130:131], v[170:171] neg_lo:[1,0,0] neg_hi:[1,0,0]
	v_div_fmas_f32 v163, v163, v167, v131
	s_mov_b64 vcc, s[28:29]
	v_div_fmas_f32 v162, v162, v166, v130
	s_mov_b64 vcc, s[26:27]
	v_div_fmas_f32 v161, v161, v165, v129
	s_mov_b64 vcc, s[2:3]
	v_div_fmas_f32 v160, v160, v164, v128
	v_div_fixup_f32 v156, v160, v156, 1.0
	v_div_fixup_f32 v157, v161, v157, 1.0
	v_div_fixup_f32 v158, v162, v158, 1.0
	v_div_fixup_f32 v159, v163, v159, 1.0
	v_pk_mul_f32 v[152:153], v[116:117], v[152:153]
	v_pk_mul_f32 v[154:155], v[118:119], v[154:155]
	v_pk_mul_f32 v[156:157], v[112:113], v[156:157]
	v_pk_mul_f32 v[158:159], v[114:115], v[158:159]
	v_cvt_pk_bf16_f32 v168, v152, v153
	v_cvt_pk_bf16_f32 v169, v154, v155
	v_cvt_pk_bf16_f32 v170, v156, v157
	v_cvt_pk_bf16_f32 v171, v158, v159
	global_store_dwordx4 v184, v[168:171], s[68:69] offset:256
	global_load_dwordx4 v[116:119], v178, s[64:65] offset:256
	s_waitcnt vmcnt(5)
	v_lshlrev_b32_e32 v152, 16, v208
	v_and_b32_e32 v153, 0xffff0000, v208
	v_lshlrev_b32_e32 v154, 16, v209
	v_and_b32_e32 v155, 0xffff0000, v209
	v_lshlrev_b32_e32 v156, 16, v210
	v_and_b32_e32 v157, 0xffff0000, v210
	v_lshlrev_b32_e32 v158, 16, v211
	v_and_b32_e32 v159, 0xffff0000, v211
	v_mul_f32_e32 v152, 0xbfb8aa3b, v152
	v_mul_f32_e32 v153, 0xbfb8aa3b, v153
	v_mul_f32_e32 v154, 0xbfb8aa3b, v154
	v_mul_f32_e32 v155, 0xbfb8aa3b, v155
	v_mul_f32_e32 v156, 0xbfb8aa3b, v156
	v_mul_f32_e32 v157, 0xbfb8aa3b, v157
	v_mul_f32_e32 v158, 0xbfb8aa3b, v158
	v_mul_f32_e32 v159, 0xbfb8aa3b, v159
	v_exp_f32_e32 v152, v152
	v_exp_f32_e32 v153, v153
	v_exp_f32_e32 v154, v154
	v_exp_f32_e32 v155, v155
	v_exp_f32_e32 v156, v156
	v_exp_f32_e32 v157, v157
	v_exp_f32_e32 v158, v158
	v_exp_f32_e32 v159, v159
	v_pk_add_f32 v[152:153], v[152:153], 1.0 op_sel_hi:[1,0]
	v_pk_add_f32 v[154:155], v[154:155], 1.0 op_sel_hi:[1,0]
	v_pk_add_f32 v[156:157], v[156:157], 1.0 op_sel_hi:[1,0]
	v_pk_add_f32 v[158:159], v[158:159], 1.0 op_sel_hi:[1,0]
	v_div_scale_f32 v160, s[38:39], v152, v152, 1.0
	v_div_scale_f32 v161, s[38:39], v153, v153, 1.0
	v_div_scale_f32 v162, s[38:39], v154, v154, 1.0
	v_div_scale_f32 v163, s[38:39], v155, v155, 1.0
	v_rcp_f32_e32 v164, v160
	v_rcp_f32_e32 v165, v161
	v_rcp_f32_e32 v166, v162
	v_rcp_f32_e32 v167, v163
	v_pk_fma_f32 v[148:149], v[160:161], v[164:165], 1.0 op_sel_hi:[1,1,0] neg_lo:[1,0,0] neg_hi:[1,0,0]
	v_pk_fma_f32 v[150:151], v[162:163], v[166:167], 1.0 op_sel_hi:[1,1,0] neg_lo:[1,0,0] neg_hi:[1,0,0]
	v_pk_fma_f32 v[164:165], v[148:149], v[164:165], v[164:165]
	v_pk_fma_f32 v[166:167], v[150:151], v[166:167], v[166:167]
	v_div_scale_f32 v168, s[2:3], 1.0, v152, 1.0
	v_div_scale_f32 v169, s[26:27], 1.0, v153, 1.0
	v_div_scale_f32 v170, s[28:29], 1.0, v154, 1.0
	v_div_scale_f32 v171, vcc, 1.0, v155, 1.0
	v_pk_mul_f32 v[128:129], v[168:169], v[164:165]
	v_pk_mul_f32 v[130:131], v[170:171], v[166:167]
	v_pk_fma_f32 v[148:149], v[160:161], v[128:129], v[168:169] neg_lo:[1,0,0] neg_hi:[1,0,0]
	v_pk_fma_f32 v[150:151], v[162:163], v[130:131], v[170:171] neg_lo:[1,0,0] neg_hi:[1,0,0]
	v_pk_fma_f32 v[128:129], v[148:149], v[164:165], v[128:129]
	v_pk_fma_f32 v[130:131], v[150:151], v[166:167], v[130:131]
	v_pk_fma_f32 v[160:161], v[160:161], v[128:129], v[168:169] neg_lo:[1,0,0] neg_hi:[1,0,0]
	v_pk_fma_f32 v[162:163], v[162:163], v[130:131], v[170:171] neg_lo:[1,0,0] neg_hi:[1,0,0]
	v_div_fmas_f32 v163, v163, v167, v131
	s_mov_b64 vcc, s[28:29]
	v_div_fmas_f32 v162, v162, v166, v130
	s_mov_b64 vcc, s[26:27]
	v_div_fmas_f32 v161, v161, v165, v129
	s_mov_b64 vcc, s[2:3]
	v_div_fmas_f32 v160, v160, v164, v128
	v_div_fixup_f32 v152, v160, v152, 1.0
	v_div_fixup_f32 v153, v161, v153, 1.0
	v_div_fixup_f32 v154, v162, v154, 1.0
	v_div_fixup_f32 v155, v163, v155, 1.0
	v_div_scale_f32 v160, s[38:39], v156, v156, 1.0
	v_div_scale_f32 v161, s[38:39], v157, v157, 1.0
	v_div_scale_f32 v162, s[38:39], v158, v158, 1.0
	v_div_scale_f32 v163, s[38:39], v159, v159, 1.0
	v_rcp_f32_e32 v164, v160
	v_rcp_f32_e32 v165, v161
	v_rcp_f32_e32 v166, v162
	v_rcp_f32_e32 v167, v163
	v_pk_fma_f32 v[148:149], v[160:161], v[164:165], 1.0 op_sel_hi:[1,1,0] neg_lo:[1,0,0] neg_hi:[1,0,0]
	v_pk_fma_f32 v[150:151], v[162:163], v[166:167], 1.0 op_sel_hi:[1,1,0] neg_lo:[1,0,0] neg_hi:[1,0,0]
	v_pk_fma_f32 v[164:165], v[148:149], v[164:165], v[164:165]
	v_pk_fma_f32 v[166:167], v[150:151], v[166:167], v[166:167]
	v_div_scale_f32 v168, s[2:3], 1.0, v156, 1.0
	v_div_scale_f32 v169, s[26:27], 1.0, v157, 1.0
	v_div_scale_f32 v170, s[28:29], 1.0, v158, 1.0
	v_div_scale_f32 v171, vcc, 1.0, v159, 1.0
	v_pk_mul_f32 v[128:129], v[168:169], v[164:165]
	v_pk_mul_f32 v[130:131], v[170:171], v[166:167]
	v_pk_fma_f32 v[148:149], v[160:161], v[128:129], v[168:169] neg_lo:[1,0,0] neg_hi:[1,0,0]
	v_pk_fma_f32 v[150:151], v[162:163], v[130:131], v[170:171] neg_lo:[1,0,0] neg_hi:[1,0,0]
	v_pk_fma_f32 v[128:129], v[148:149], v[164:165], v[128:129]
	v_pk_fma_f32 v[130:131], v[150:151], v[166:167], v[130:131]
	v_pk_fma_f32 v[160:161], v[160:161], v[128:129], v[168:169] neg_lo:[1,0,0] neg_hi:[1,0,0]
	v_pk_fma_f32 v[162:163], v[162:163], v[130:131], v[170:171] neg_lo:[1,0,0] neg_hi:[1,0,0]
	v_div_fmas_f32 v163, v163, v167, v131
	s_mov_b64 vcc, s[28:29]
	v_div_fmas_f32 v162, v162, v166, v130
	s_mov_b64 vcc, s[26:27]
	v_div_fmas_f32 v161, v161, v165, v129
	s_mov_b64 vcc, s[2:3]
	v_div_fmas_f32 v160, v160, v164, v128
	v_div_fixup_f32 v156, v160, v156, 1.0
	v_div_fixup_f32 v157, v161, v157, 1.0
	v_div_fixup_f32 v158, v162, v158, 1.0
	v_div_fixup_f32 v159, v163, v159, 1.0
	v_pk_mul_f32 v[152:153], v[108:109], v[152:153]
	v_pk_mul_f32 v[154:155], v[110:111], v[154:155]
	v_pk_mul_f32 v[156:157], v[104:105], v[156:157]
	v_pk_mul_f32 v[158:159], v[106:107], v[158:159]
	v_cvt_pk_bf16_f32 v168, v152, v153
	v_cvt_pk_bf16_f32 v169, v154, v155
	v_cvt_pk_bf16_f32 v170, v156, v157
	v_cvt_pk_bf16_f32 v171, v158, v159
	global_store_dwordx4 v185, v[168:171], s[68:69]
	global_load_dwordx4 v[108:111], v179, s[64:65]
	s_waitcnt vmcnt(6)
	v_lshlrev_b32_e32 v152, 16, v216
	v_and_b32_e32 v153, 0xffff0000, v216
	v_lshlrev_b32_e32 v154, 16, v217
	v_and_b32_e32 v155, 0xffff0000, v217
	v_lshlrev_b32_e32 v156, 16, v218
	v_and_b32_e32 v157, 0xffff0000, v218
	v_lshlrev_b32_e32 v158, 16, v219
	v_and_b32_e32 v159, 0xffff0000, v219
	v_mul_f32_e32 v152, 0xbfb8aa3b, v152
	v_mul_f32_e32 v153, 0xbfb8aa3b, v153
	v_mul_f32_e32 v154, 0xbfb8aa3b, v154
	v_mul_f32_e32 v155, 0xbfb8aa3b, v155
	v_mul_f32_e32 v156, 0xbfb8aa3b, v156
	v_mul_f32_e32 v157, 0xbfb8aa3b, v157
	v_mul_f32_e32 v158, 0xbfb8aa3b, v158
	v_mul_f32_e32 v159, 0xbfb8aa3b, v159
	v_exp_f32_e32 v152, v152
	v_exp_f32_e32 v153, v153
	v_exp_f32_e32 v154, v154
	v_exp_f32_e32 v155, v155
	v_exp_f32_e32 v156, v156
	v_exp_f32_e32 v157, v157
	v_exp_f32_e32 v158, v158
	v_exp_f32_e32 v159, v159
	v_pk_add_f32 v[152:153], v[152:153], 1.0 op_sel_hi:[1,0]
	v_pk_add_f32 v[154:155], v[154:155], 1.0 op_sel_hi:[1,0]
	v_pk_add_f32 v[156:157], v[156:157], 1.0 op_sel_hi:[1,0]
	v_pk_add_f32 v[158:159], v[158:159], 1.0 op_sel_hi:[1,0]
	v_div_scale_f32 v160, s[38:39], v152, v152, 1.0
	v_div_scale_f32 v161, s[38:39], v153, v153, 1.0
	v_div_scale_f32 v162, s[38:39], v154, v154, 1.0
	v_div_scale_f32 v163, s[38:39], v155, v155, 1.0
	v_rcp_f32_e32 v164, v160
	v_rcp_f32_e32 v165, v161
	v_rcp_f32_e32 v166, v162
	v_rcp_f32_e32 v167, v163
	v_pk_fma_f32 v[148:149], v[160:161], v[164:165], 1.0 op_sel_hi:[1,1,0] neg_lo:[1,0,0] neg_hi:[1,0,0]
	v_pk_fma_f32 v[150:151], v[162:163], v[166:167], 1.0 op_sel_hi:[1,1,0] neg_lo:[1,0,0] neg_hi:[1,0,0]
	v_pk_fma_f32 v[164:165], v[148:149], v[164:165], v[164:165]
	v_pk_fma_f32 v[166:167], v[150:151], v[166:167], v[166:167]
	v_div_scale_f32 v168, s[2:3], 1.0, v152, 1.0
	v_div_scale_f32 v169, s[26:27], 1.0, v153, 1.0
	v_div_scale_f32 v170, s[28:29], 1.0, v154, 1.0
	v_div_scale_f32 v171, vcc, 1.0, v155, 1.0
	v_pk_mul_f32 v[128:129], v[168:169], v[164:165]
	v_pk_mul_f32 v[130:131], v[170:171], v[166:167]
	v_pk_fma_f32 v[148:149], v[160:161], v[128:129], v[168:169] neg_lo:[1,0,0] neg_hi:[1,0,0]
	v_pk_fma_f32 v[150:151], v[162:163], v[130:131], v[170:171] neg_lo:[1,0,0] neg_hi:[1,0,0]
	v_pk_fma_f32 v[128:129], v[148:149], v[164:165], v[128:129]
	v_pk_fma_f32 v[130:131], v[150:151], v[166:167], v[130:131]
	v_pk_fma_f32 v[160:161], v[160:161], v[128:129], v[168:169] neg_lo:[1,0,0] neg_hi:[1,0,0]
	v_pk_fma_f32 v[162:163], v[162:163], v[130:131], v[170:171] neg_lo:[1,0,0] neg_hi:[1,0,0]
	v_div_fmas_f32 v163, v163, v167, v131
	s_mov_b64 vcc, s[28:29]
	v_div_fmas_f32 v162, v162, v166, v130
	s_mov_b64 vcc, s[26:27]
	v_div_fmas_f32 v161, v161, v165, v129
	s_mov_b64 vcc, s[2:3]
	v_div_fmas_f32 v160, v160, v164, v128
	v_div_fixup_f32 v152, v160, v152, 1.0
	v_div_fixup_f32 v153, v161, v153, 1.0
	v_div_fixup_f32 v154, v162, v154, 1.0
	v_div_fixup_f32 v155, v163, v155, 1.0
	v_div_scale_f32 v160, s[38:39], v156, v156, 1.0
	v_div_scale_f32 v161, s[38:39], v157, v157, 1.0
	v_div_scale_f32 v162, s[38:39], v158, v158, 1.0
	v_div_scale_f32 v163, s[38:39], v159, v159, 1.0
	v_rcp_f32_e32 v164, v160
	v_rcp_f32_e32 v165, v161
	v_rcp_f32_e32 v166, v162
	v_rcp_f32_e32 v167, v163
	v_pk_fma_f32 v[148:149], v[160:161], v[164:165], 1.0 op_sel_hi:[1,1,0] neg_lo:[1,0,0] neg_hi:[1,0,0]
	v_pk_fma_f32 v[150:151], v[162:163], v[166:167], 1.0 op_sel_hi:[1,1,0] neg_lo:[1,0,0] neg_hi:[1,0,0]
	v_pk_fma_f32 v[164:165], v[148:149], v[164:165], v[164:165]
	v_pk_fma_f32 v[166:167], v[150:151], v[166:167], v[166:167]
	v_div_scale_f32 v168, s[2:3], 1.0, v156, 1.0
	v_div_scale_f32 v169, s[26:27], 1.0, v157, 1.0
	v_div_scale_f32 v170, s[28:29], 1.0, v158, 1.0
	v_div_scale_f32 v171, vcc, 1.0, v159, 1.0
	v_pk_mul_f32 v[128:129], v[168:169], v[164:165]
	v_pk_mul_f32 v[130:131], v[170:171], v[166:167]
	v_pk_fma_f32 v[148:149], v[160:161], v[128:129], v[168:169] neg_lo:[1,0,0] neg_hi:[1,0,0]
	v_pk_fma_f32 v[150:151], v[162:163], v[130:131], v[170:171] neg_lo:[1,0,0] neg_hi:[1,0,0]
	v_pk_fma_f32 v[128:129], v[148:149], v[164:165], v[128:129]
	v_pk_fma_f32 v[130:131], v[150:151], v[166:167], v[130:131]
	v_pk_fma_f32 v[160:161], v[160:161], v[128:129], v[168:169] neg_lo:[1,0,0] neg_hi:[1,0,0]
	v_pk_fma_f32 v[162:163], v[162:163], v[130:131], v[170:171] neg_lo:[1,0,0] neg_hi:[1,0,0]
	v_div_fmas_f32 v163, v163, v167, v131
	s_mov_b64 vcc, s[28:29]
	v_div_fmas_f32 v162, v162, v166, v130
	s_mov_b64 vcc, s[26:27]
	v_div_fmas_f32 v161, v161, v165, v129
	s_mov_b64 vcc, s[2:3]
	v_div_fmas_f32 v160, v160, v164, v128
	v_div_fixup_f32 v156, v160, v156, 1.0
	v_div_fixup_f32 v157, v161, v157, 1.0
	v_div_fixup_f32 v158, v162, v158, 1.0
	v_div_fixup_f32 v159, v163, v159, 1.0
	v_pk_mul_f32 v[152:153], v[100:101], v[152:153]
	v_pk_mul_f32 v[154:155], v[102:103], v[154:155]
	v_pk_mul_f32 v[156:157], v[96:97], v[156:157]
	v_pk_mul_f32 v[158:159], v[98:99], v[158:159]
	v_cvt_pk_bf16_f32 v168, v152, v153
	v_cvt_pk_bf16_f32 v169, v154, v155
	v_cvt_pk_bf16_f32 v170, v156, v157
	v_cvt_pk_bf16_f32 v171, v158, v159
	global_store_dwordx4 v185, v[168:171], s[68:69] offset:256
	global_load_dwordx4 v[100:103], v179, s[64:65] offset:256
	s_waitcnt vmcnt(6)
	v_lshlrev_b32_e32 v152, 16, v124
	v_and_b32_e32 v153, 0xffff0000, v124
	v_lshlrev_b32_e32 v154, 16, v125
	v_and_b32_e32 v155, 0xffff0000, v125
	v_lshlrev_b32_e32 v156, 16, v126
	v_and_b32_e32 v157, 0xffff0000, v126
	v_lshlrev_b32_e32 v158, 16, v127
	v_and_b32_e32 v159, 0xffff0000, v127
	v_mul_f32_e32 v152, 0xbfb8aa3b, v152
	v_mul_f32_e32 v153, 0xbfb8aa3b, v153
	v_mul_f32_e32 v154, 0xbfb8aa3b, v154
	v_mul_f32_e32 v155, 0xbfb8aa3b, v155
	v_mul_f32_e32 v156, 0xbfb8aa3b, v156
	v_mul_f32_e32 v157, 0xbfb8aa3b, v157
	v_mul_f32_e32 v158, 0xbfb8aa3b, v158
	v_mul_f32_e32 v159, 0xbfb8aa3b, v159
	v_exp_f32_e32 v152, v152
	v_exp_f32_e32 v153, v153
	v_exp_f32_e32 v154, v154
	v_exp_f32_e32 v155, v155
	v_exp_f32_e32 v156, v156
	v_exp_f32_e32 v157, v157
	v_exp_f32_e32 v158, v158
	v_exp_f32_e32 v159, v159
	v_pk_add_f32 v[152:153], v[152:153], 1.0 op_sel_hi:[1,0]
	v_pk_add_f32 v[154:155], v[154:155], 1.0 op_sel_hi:[1,0]
	v_pk_add_f32 v[156:157], v[156:157], 1.0 op_sel_hi:[1,0]
	v_pk_add_f32 v[158:159], v[158:159], 1.0 op_sel_hi:[1,0]
	v_div_scale_f32 v160, s[38:39], v152, v152, 1.0
	v_div_scale_f32 v161, s[38:39], v153, v153, 1.0
	v_div_scale_f32 v162, s[38:39], v154, v154, 1.0
	v_div_scale_f32 v163, s[38:39], v155, v155, 1.0
	v_rcp_f32_e32 v164, v160
	v_rcp_f32_e32 v165, v161
	v_rcp_f32_e32 v166, v162
	v_rcp_f32_e32 v167, v163
	v_pk_fma_f32 v[148:149], v[160:161], v[164:165], 1.0 op_sel_hi:[1,1,0] neg_lo:[1,0,0] neg_hi:[1,0,0]
	v_pk_fma_f32 v[150:151], v[162:163], v[166:167], 1.0 op_sel_hi:[1,1,0] neg_lo:[1,0,0] neg_hi:[1,0,0]
	v_pk_fma_f32 v[164:165], v[148:149], v[164:165], v[164:165]
	v_pk_fma_f32 v[166:167], v[150:151], v[166:167], v[166:167]
	v_div_scale_f32 v168, s[2:3], 1.0, v152, 1.0
	v_div_scale_f32 v169, s[26:27], 1.0, v153, 1.0
	v_div_scale_f32 v170, s[28:29], 1.0, v154, 1.0
	v_div_scale_f32 v171, vcc, 1.0, v155, 1.0
	v_pk_mul_f32 v[128:129], v[168:169], v[164:165]
	v_pk_mul_f32 v[130:131], v[170:171], v[166:167]
	v_pk_fma_f32 v[148:149], v[160:161], v[128:129], v[168:169] neg_lo:[1,0,0] neg_hi:[1,0,0]
	v_pk_fma_f32 v[150:151], v[162:163], v[130:131], v[170:171] neg_lo:[1,0,0] neg_hi:[1,0,0]
	v_pk_fma_f32 v[128:129], v[148:149], v[164:165], v[128:129]
	v_pk_fma_f32 v[130:131], v[150:151], v[166:167], v[130:131]
	v_pk_fma_f32 v[160:161], v[160:161], v[128:129], v[168:169] neg_lo:[1,0,0] neg_hi:[1,0,0]
	v_pk_fma_f32 v[162:163], v[162:163], v[130:131], v[170:171] neg_lo:[1,0,0] neg_hi:[1,0,0]
	v_div_fmas_f32 v163, v163, v167, v131
	s_mov_b64 vcc, s[28:29]
	v_div_fmas_f32 v162, v162, v166, v130
	s_mov_b64 vcc, s[26:27]
	v_div_fmas_f32 v161, v161, v165, v129
	s_mov_b64 vcc, s[2:3]
	v_div_fmas_f32 v160, v160, v164, v128
	v_div_fixup_f32 v152, v160, v152, 1.0
	v_div_fixup_f32 v153, v161, v153, 1.0
	v_div_fixup_f32 v154, v162, v154, 1.0
	v_div_fixup_f32 v155, v163, v155, 1.0
	v_div_scale_f32 v160, s[38:39], v156, v156, 1.0
	v_div_scale_f32 v161, s[38:39], v157, v157, 1.0
	v_div_scale_f32 v162, s[38:39], v158, v158, 1.0
	v_div_scale_f32 v163, s[38:39], v159, v159, 1.0
	v_rcp_f32_e32 v164, v160
	v_rcp_f32_e32 v165, v161
	v_rcp_f32_e32 v166, v162
	v_rcp_f32_e32 v167, v163
	v_pk_fma_f32 v[148:149], v[160:161], v[164:165], 1.0 op_sel_hi:[1,1,0] neg_lo:[1,0,0] neg_hi:[1,0,0]
	v_pk_fma_f32 v[150:151], v[162:163], v[166:167], 1.0 op_sel_hi:[1,1,0] neg_lo:[1,0,0] neg_hi:[1,0,0]
	v_pk_fma_f32 v[164:165], v[148:149], v[164:165], v[164:165]
	v_pk_fma_f32 v[166:167], v[150:151], v[166:167], v[166:167]
	v_div_scale_f32 v168, s[2:3], 1.0, v156, 1.0
	v_div_scale_f32 v169, s[26:27], 1.0, v157, 1.0
	v_div_scale_f32 v170, s[28:29], 1.0, v158, 1.0
	v_div_scale_f32 v171, vcc, 1.0, v159, 1.0
	v_pk_mul_f32 v[128:129], v[168:169], v[164:165]
	v_pk_mul_f32 v[130:131], v[170:171], v[166:167]
	v_pk_fma_f32 v[148:149], v[160:161], v[128:129], v[168:169] neg_lo:[1,0,0] neg_hi:[1,0,0]
	v_pk_fma_f32 v[150:151], v[162:163], v[130:131], v[170:171] neg_lo:[1,0,0] neg_hi:[1,0,0]
	v_pk_fma_f32 v[128:129], v[148:149], v[164:165], v[128:129]
	v_pk_fma_f32 v[130:131], v[150:151], v[166:167], v[130:131]
	v_pk_fma_f32 v[160:161], v[160:161], v[128:129], v[168:169] neg_lo:[1,0,0] neg_hi:[1,0,0]
	v_pk_fma_f32 v[162:163], v[162:163], v[130:131], v[170:171] neg_lo:[1,0,0] neg_hi:[1,0,0]
	v_div_fmas_f32 v163, v163, v167, v131
	s_mov_b64 vcc, s[28:29]
	v_div_fmas_f32 v162, v162, v166, v130
	s_mov_b64 vcc, s[26:27]
	v_div_fmas_f32 v161, v161, v165, v129
	s_mov_b64 vcc, s[2:3]
	v_div_fmas_f32 v160, v160, v164, v128
	v_div_fixup_f32 v156, v160, v156, 1.0
	v_div_fixup_f32 v157, v161, v157, 1.0
	v_div_fixup_f32 v158, v162, v158, 1.0
	v_div_fixup_f32 v159, v163, v159, 1.0
	v_pk_mul_f32 v[152:153], v[92:93], v[152:153]
	v_pk_mul_f32 v[154:155], v[94:95], v[154:155]
	v_pk_mul_f32 v[156:157], v[88:89], v[156:157]
	v_pk_mul_f32 v[158:159], v[90:91], v[158:159]
	v_cvt_pk_bf16_f32 v168, v152, v153
	v_cvt_pk_bf16_f32 v169, v154, v155
	v_cvt_pk_bf16_f32 v170, v156, v157
	v_cvt_pk_bf16_f32 v171, v158, v159
	global_store_dwordx4 v186, v[168:171], s[68:69]
	global_load_dwordx4 v[92:95], v180, s[64:65]
	s_waitcnt vmcnt(6)
	v_lshlrev_b32_e32 v152, 16, v116
	v_and_b32_e32 v153, 0xffff0000, v116
	v_lshlrev_b32_e32 v154, 16, v117
	v_and_b32_e32 v155, 0xffff0000, v117
	v_lshlrev_b32_e32 v156, 16, v118
	v_and_b32_e32 v157, 0xffff0000, v118
	v_lshlrev_b32_e32 v158, 16, v119
	v_and_b32_e32 v159, 0xffff0000, v119
	v_mul_f32_e32 v152, 0xbfb8aa3b, v152
	v_mul_f32_e32 v153, 0xbfb8aa3b, v153
	v_mul_f32_e32 v154, 0xbfb8aa3b, v154
	v_mul_f32_e32 v155, 0xbfb8aa3b, v155
	v_mul_f32_e32 v156, 0xbfb8aa3b, v156
	v_mul_f32_e32 v157, 0xbfb8aa3b, v157
	v_mul_f32_e32 v158, 0xbfb8aa3b, v158
	v_mul_f32_e32 v159, 0xbfb8aa3b, v159
	v_exp_f32_e32 v152, v152
	v_exp_f32_e32 v153, v153
	v_exp_f32_e32 v154, v154
	v_exp_f32_e32 v155, v155
	v_exp_f32_e32 v156, v156
	v_exp_f32_e32 v157, v157
	v_exp_f32_e32 v158, v158
	v_exp_f32_e32 v159, v159
	v_pk_add_f32 v[152:153], v[152:153], 1.0 op_sel_hi:[1,0]
	v_pk_add_f32 v[154:155], v[154:155], 1.0 op_sel_hi:[1,0]
	v_pk_add_f32 v[156:157], v[156:157], 1.0 op_sel_hi:[1,0]
	v_pk_add_f32 v[158:159], v[158:159], 1.0 op_sel_hi:[1,0]
	v_div_scale_f32 v160, s[38:39], v152, v152, 1.0
	v_div_scale_f32 v161, s[38:39], v153, v153, 1.0
	v_div_scale_f32 v162, s[38:39], v154, v154, 1.0
	v_div_scale_f32 v163, s[38:39], v155, v155, 1.0
	v_rcp_f32_e32 v164, v160
	v_rcp_f32_e32 v165, v161
	v_rcp_f32_e32 v166, v162
	v_rcp_f32_e32 v167, v163
	v_pk_fma_f32 v[148:149], v[160:161], v[164:165], 1.0 op_sel_hi:[1,1,0] neg_lo:[1,0,0] neg_hi:[1,0,0]
	v_pk_fma_f32 v[150:151], v[162:163], v[166:167], 1.0 op_sel_hi:[1,1,0] neg_lo:[1,0,0] neg_hi:[1,0,0]
	v_pk_fma_f32 v[164:165], v[148:149], v[164:165], v[164:165]
	v_pk_fma_f32 v[166:167], v[150:151], v[166:167], v[166:167]
	v_div_scale_f32 v168, s[2:3], 1.0, v152, 1.0
	v_div_scale_f32 v169, s[26:27], 1.0, v153, 1.0
	v_div_scale_f32 v170, s[28:29], 1.0, v154, 1.0
	v_div_scale_f32 v171, vcc, 1.0, v155, 1.0
	v_pk_mul_f32 v[128:129], v[168:169], v[164:165]
	v_pk_mul_f32 v[130:131], v[170:171], v[166:167]
	v_pk_fma_f32 v[148:149], v[160:161], v[128:129], v[168:169] neg_lo:[1,0,0] neg_hi:[1,0,0]
	v_pk_fma_f32 v[150:151], v[162:163], v[130:131], v[170:171] neg_lo:[1,0,0] neg_hi:[1,0,0]
	v_pk_fma_f32 v[128:129], v[148:149], v[164:165], v[128:129]
	v_pk_fma_f32 v[130:131], v[150:151], v[166:167], v[130:131]
	v_pk_fma_f32 v[160:161], v[160:161], v[128:129], v[168:169] neg_lo:[1,0,0] neg_hi:[1,0,0]
	v_pk_fma_f32 v[162:163], v[162:163], v[130:131], v[170:171] neg_lo:[1,0,0] neg_hi:[1,0,0]
	v_div_fmas_f32 v163, v163, v167, v131
	s_mov_b64 vcc, s[28:29]
	v_div_fmas_f32 v162, v162, v166, v130
	s_mov_b64 vcc, s[26:27]
	v_div_fmas_f32 v161, v161, v165, v129
	s_mov_b64 vcc, s[2:3]
	v_div_fmas_f32 v160, v160, v164, v128
	v_div_fixup_f32 v152, v160, v152, 1.0
	v_div_fixup_f32 v153, v161, v153, 1.0
	v_div_fixup_f32 v154, v162, v154, 1.0
	v_div_fixup_f32 v155, v163, v155, 1.0
	v_div_scale_f32 v160, s[38:39], v156, v156, 1.0
	v_div_scale_f32 v161, s[38:39], v157, v157, 1.0
	v_div_scale_f32 v162, s[38:39], v158, v158, 1.0
	v_div_scale_f32 v163, s[38:39], v159, v159, 1.0
	v_rcp_f32_e32 v164, v160
	v_rcp_f32_e32 v165, v161
	v_rcp_f32_e32 v166, v162
	v_rcp_f32_e32 v167, v163
	v_pk_fma_f32 v[148:149], v[160:161], v[164:165], 1.0 op_sel_hi:[1,1,0] neg_lo:[1,0,0] neg_hi:[1,0,0]
	v_pk_fma_f32 v[150:151], v[162:163], v[166:167], 1.0 op_sel_hi:[1,1,0] neg_lo:[1,0,0] neg_hi:[1,0,0]
	v_pk_fma_f32 v[164:165], v[148:149], v[164:165], v[164:165]
	v_pk_fma_f32 v[166:167], v[150:151], v[166:167], v[166:167]
	v_div_scale_f32 v168, s[2:3], 1.0, v156, 1.0
	v_div_scale_f32 v169, s[26:27], 1.0, v157, 1.0
	v_div_scale_f32 v170, s[28:29], 1.0, v158, 1.0
	v_div_scale_f32 v171, vcc, 1.0, v159, 1.0
	v_pk_mul_f32 v[128:129], v[168:169], v[164:165]
	v_pk_mul_f32 v[130:131], v[170:171], v[166:167]
	v_pk_fma_f32 v[148:149], v[160:161], v[128:129], v[168:169] neg_lo:[1,0,0] neg_hi:[1,0,0]
	v_pk_fma_f32 v[150:151], v[162:163], v[130:131], v[170:171] neg_lo:[1,0,0] neg_hi:[1,0,0]
	v_pk_fma_f32 v[128:129], v[148:149], v[164:165], v[128:129]
	v_pk_fma_f32 v[130:131], v[150:151], v[166:167], v[130:131]
	v_pk_fma_f32 v[160:161], v[160:161], v[128:129], v[168:169] neg_lo:[1,0,0] neg_hi:[1,0,0]
	v_pk_fma_f32 v[162:163], v[162:163], v[130:131], v[170:171] neg_lo:[1,0,0] neg_hi:[1,0,0]
	v_div_fmas_f32 v163, v163, v167, v131
	s_mov_b64 vcc, s[28:29]
	v_div_fmas_f32 v162, v162, v166, v130
	s_mov_b64 vcc, s[26:27]
	v_div_fmas_f32 v161, v161, v165, v129
	s_mov_b64 vcc, s[2:3]
	v_div_fmas_f32 v160, v160, v164, v128
	v_div_fixup_f32 v156, v160, v156, 1.0
	v_div_fixup_f32 v157, v161, v157, 1.0
	v_div_fixup_f32 v158, v162, v158, 1.0
	v_div_fixup_f32 v159, v163, v159, 1.0
	v_pk_mul_f32 v[152:153], v[84:85], v[152:153]
	v_pk_mul_f32 v[154:155], v[86:87], v[154:155]
	v_pk_mul_f32 v[156:157], v[80:81], v[156:157]
	v_pk_mul_f32 v[158:159], v[82:83], v[158:159]
	v_cvt_pk_bf16_f32 v168, v152, v153
	v_cvt_pk_bf16_f32 v169, v154, v155
	v_cvt_pk_bf16_f32 v170, v156, v157
	v_cvt_pk_bf16_f32 v171, v158, v159
	global_store_dwordx4 v186, v[168:171], s[68:69] offset:256
	global_load_dwordx4 v[84:87], v180, s[64:65] offset:256
	s_waitcnt vmcnt(6)
	v_lshlrev_b32_e32 v152, 16, v108
	v_and_b32_e32 v153, 0xffff0000, v108
	v_lshlrev_b32_e32 v154, 16, v109
	v_and_b32_e32 v155, 0xffff0000, v109
	v_lshlrev_b32_e32 v156, 16, v110
	v_and_b32_e32 v157, 0xffff0000, v110
	v_lshlrev_b32_e32 v158, 16, v111
	v_and_b32_e32 v159, 0xffff0000, v111
	v_mul_f32_e32 v152, 0xbfb8aa3b, v152
	v_mul_f32_e32 v153, 0xbfb8aa3b, v153
	v_mul_f32_e32 v154, 0xbfb8aa3b, v154
	v_mul_f32_e32 v155, 0xbfb8aa3b, v155
	v_mul_f32_e32 v156, 0xbfb8aa3b, v156
	v_mul_f32_e32 v157, 0xbfb8aa3b, v157
	v_mul_f32_e32 v158, 0xbfb8aa3b, v158
	v_mul_f32_e32 v159, 0xbfb8aa3b, v159
	v_exp_f32_e32 v152, v152
	v_exp_f32_e32 v153, v153
	v_exp_f32_e32 v154, v154
	v_exp_f32_e32 v155, v155
	v_exp_f32_e32 v156, v156
	v_exp_f32_e32 v157, v157
	v_exp_f32_e32 v158, v158
	v_exp_f32_e32 v159, v159
	v_pk_add_f32 v[152:153], v[152:153], 1.0 op_sel_hi:[1,0]
	v_pk_add_f32 v[154:155], v[154:155], 1.0 op_sel_hi:[1,0]
	v_pk_add_f32 v[156:157], v[156:157], 1.0 op_sel_hi:[1,0]
	v_pk_add_f32 v[158:159], v[158:159], 1.0 op_sel_hi:[1,0]
	v_div_scale_f32 v160, s[38:39], v152, v152, 1.0
	v_div_scale_f32 v161, s[38:39], v153, v153, 1.0
	v_div_scale_f32 v162, s[38:39], v154, v154, 1.0
	v_div_scale_f32 v163, s[38:39], v155, v155, 1.0
	v_rcp_f32_e32 v164, v160
	v_rcp_f32_e32 v165, v161
	v_rcp_f32_e32 v166, v162
	v_rcp_f32_e32 v167, v163
	v_pk_fma_f32 v[148:149], v[160:161], v[164:165], 1.0 op_sel_hi:[1,1,0] neg_lo:[1,0,0] neg_hi:[1,0,0]
	v_pk_fma_f32 v[150:151], v[162:163], v[166:167], 1.0 op_sel_hi:[1,1,0] neg_lo:[1,0,0] neg_hi:[1,0,0]
	v_pk_fma_f32 v[164:165], v[148:149], v[164:165], v[164:165]
	v_pk_fma_f32 v[166:167], v[150:151], v[166:167], v[166:167]
	v_div_scale_f32 v168, s[2:3], 1.0, v152, 1.0
	v_div_scale_f32 v169, s[26:27], 1.0, v153, 1.0
	v_div_scale_f32 v170, s[28:29], 1.0, v154, 1.0
	v_div_scale_f32 v171, vcc, 1.0, v155, 1.0
	v_pk_mul_f32 v[128:129], v[168:169], v[164:165]
	v_pk_mul_f32 v[130:131], v[170:171], v[166:167]
	v_pk_fma_f32 v[148:149], v[160:161], v[128:129], v[168:169] neg_lo:[1,0,0] neg_hi:[1,0,0]
	v_pk_fma_f32 v[150:151], v[162:163], v[130:131], v[170:171] neg_lo:[1,0,0] neg_hi:[1,0,0]
	v_pk_fma_f32 v[128:129], v[148:149], v[164:165], v[128:129]
	v_pk_fma_f32 v[130:131], v[150:151], v[166:167], v[130:131]
	v_pk_fma_f32 v[160:161], v[160:161], v[128:129], v[168:169] neg_lo:[1,0,0] neg_hi:[1,0,0]
	v_pk_fma_f32 v[162:163], v[162:163], v[130:131], v[170:171] neg_lo:[1,0,0] neg_hi:[1,0,0]
	v_div_fmas_f32 v163, v163, v167, v131
	s_mov_b64 vcc, s[28:29]
	v_div_fmas_f32 v162, v162, v166, v130
	s_mov_b64 vcc, s[26:27]
	v_div_fmas_f32 v161, v161, v165, v129
	s_mov_b64 vcc, s[2:3]
	v_div_fmas_f32 v160, v160, v164, v128
	v_div_fixup_f32 v152, v160, v152, 1.0
	v_div_fixup_f32 v153, v161, v153, 1.0
	v_div_fixup_f32 v154, v162, v154, 1.0
	v_div_fixup_f32 v155, v163, v155, 1.0
	v_div_scale_f32 v160, s[38:39], v156, v156, 1.0
	v_div_scale_f32 v161, s[38:39], v157, v157, 1.0
	v_div_scale_f32 v162, s[38:39], v158, v158, 1.0
	v_div_scale_f32 v163, s[38:39], v159, v159, 1.0
	v_rcp_f32_e32 v164, v160
	v_rcp_f32_e32 v165, v161
	v_rcp_f32_e32 v166, v162
	v_rcp_f32_e32 v167, v163
	v_pk_fma_f32 v[148:149], v[160:161], v[164:165], 1.0 op_sel_hi:[1,1,0] neg_lo:[1,0,0] neg_hi:[1,0,0]
	v_pk_fma_f32 v[150:151], v[162:163], v[166:167], 1.0 op_sel_hi:[1,1,0] neg_lo:[1,0,0] neg_hi:[1,0,0]
	v_pk_fma_f32 v[164:165], v[148:149], v[164:165], v[164:165]
	v_pk_fma_f32 v[166:167], v[150:151], v[166:167], v[166:167]
	v_div_scale_f32 v168, s[2:3], 1.0, v156, 1.0
	v_div_scale_f32 v169, s[26:27], 1.0, v157, 1.0
	v_div_scale_f32 v170, s[28:29], 1.0, v158, 1.0
	v_div_scale_f32 v171, vcc, 1.0, v159, 1.0
	v_pk_mul_f32 v[128:129], v[168:169], v[164:165]
	v_pk_mul_f32 v[130:131], v[170:171], v[166:167]
	v_pk_fma_f32 v[148:149], v[160:161], v[128:129], v[168:169] neg_lo:[1,0,0] neg_hi:[1,0,0]
	v_pk_fma_f32 v[150:151], v[162:163], v[130:131], v[170:171] neg_lo:[1,0,0] neg_hi:[1,0,0]
	v_pk_fma_f32 v[128:129], v[148:149], v[164:165], v[128:129]
	v_pk_fma_f32 v[130:131], v[150:151], v[166:167], v[130:131]
	v_pk_fma_f32 v[160:161], v[160:161], v[128:129], v[168:169] neg_lo:[1,0,0] neg_hi:[1,0,0]
	v_pk_fma_f32 v[162:163], v[162:163], v[130:131], v[170:171] neg_lo:[1,0,0] neg_hi:[1,0,0]
	v_div_fmas_f32 v163, v163, v167, v131
	s_mov_b64 vcc, s[28:29]
	v_div_fmas_f32 v162, v162, v166, v130
	s_mov_b64 vcc, s[26:27]
	v_div_fmas_f32 v161, v161, v165, v129
	s_mov_b64 vcc, s[2:3]
	v_div_fmas_f32 v160, v160, v164, v128
	v_div_fixup_f32 v156, v160, v156, 1.0
	v_div_fixup_f32 v157, v161, v157, 1.0
	v_div_fixup_f32 v158, v162, v158, 1.0
	v_div_fixup_f32 v159, v163, v159, 1.0
	v_pk_mul_f32 v[152:153], v[76:77], v[152:153]
	v_pk_mul_f32 v[154:155], v[78:79], v[154:155]
	v_pk_mul_f32 v[156:157], v[72:73], v[156:157]
	v_pk_mul_f32 v[158:159], v[74:75], v[158:159]
	v_cvt_pk_bf16_f32 v168, v152, v153
	v_cvt_pk_bf16_f32 v169, v154, v155
	v_cvt_pk_bf16_f32 v170, v156, v157
	v_cvt_pk_bf16_f32 v171, v158, v159
	global_store_dwordx4 v187, v[168:171], s[68:69]
	global_load_dwordx4 v[76:79], v181, s[64:65]
	s_waitcnt vmcnt(6)
	v_lshlrev_b32_e32 v152, 16, v100
	v_and_b32_e32 v153, 0xffff0000, v100
	v_lshlrev_b32_e32 v154, 16, v101
	v_and_b32_e32 v155, 0xffff0000, v101
	v_lshlrev_b32_e32 v156, 16, v102
	v_and_b32_e32 v157, 0xffff0000, v102
	v_lshlrev_b32_e32 v158, 16, v103
	v_and_b32_e32 v159, 0xffff0000, v103
	v_mul_f32_e32 v152, 0xbfb8aa3b, v152
	v_mul_f32_e32 v153, 0xbfb8aa3b, v153
	v_mul_f32_e32 v154, 0xbfb8aa3b, v154
	v_mul_f32_e32 v155, 0xbfb8aa3b, v155
	v_mul_f32_e32 v156, 0xbfb8aa3b, v156
	v_mul_f32_e32 v157, 0xbfb8aa3b, v157
	v_mul_f32_e32 v158, 0xbfb8aa3b, v158
	v_mul_f32_e32 v159, 0xbfb8aa3b, v159
	v_exp_f32_e32 v152, v152
	v_exp_f32_e32 v153, v153
	v_exp_f32_e32 v154, v154
	v_exp_f32_e32 v155, v155
	v_exp_f32_e32 v156, v156
	v_exp_f32_e32 v157, v157
	v_exp_f32_e32 v158, v158
	v_exp_f32_e32 v159, v159
	v_pk_add_f32 v[152:153], v[152:153], 1.0 op_sel_hi:[1,0]
	v_pk_add_f32 v[154:155], v[154:155], 1.0 op_sel_hi:[1,0]
	v_pk_add_f32 v[156:157], v[156:157], 1.0 op_sel_hi:[1,0]
	v_pk_add_f32 v[158:159], v[158:159], 1.0 op_sel_hi:[1,0]
	v_div_scale_f32 v160, s[38:39], v152, v152, 1.0
	v_div_scale_f32 v161, s[38:39], v153, v153, 1.0
	v_div_scale_f32 v162, s[38:39], v154, v154, 1.0
	v_div_scale_f32 v163, s[38:39], v155, v155, 1.0
	v_rcp_f32_e32 v164, v160
	v_rcp_f32_e32 v165, v161
	v_rcp_f32_e32 v166, v162
	v_rcp_f32_e32 v167, v163
	v_pk_fma_f32 v[148:149], v[160:161], v[164:165], 1.0 op_sel_hi:[1,1,0] neg_lo:[1,0,0] neg_hi:[1,0,0]
	v_pk_fma_f32 v[150:151], v[162:163], v[166:167], 1.0 op_sel_hi:[1,1,0] neg_lo:[1,0,0] neg_hi:[1,0,0]
	v_pk_fma_f32 v[164:165], v[148:149], v[164:165], v[164:165]
	v_pk_fma_f32 v[166:167], v[150:151], v[166:167], v[166:167]
	v_div_scale_f32 v168, s[2:3], 1.0, v152, 1.0
	v_div_scale_f32 v169, s[26:27], 1.0, v153, 1.0
	v_div_scale_f32 v170, s[28:29], 1.0, v154, 1.0
	v_div_scale_f32 v171, vcc, 1.0, v155, 1.0
	v_pk_mul_f32 v[128:129], v[168:169], v[164:165]
	v_pk_mul_f32 v[130:131], v[170:171], v[166:167]
	v_pk_fma_f32 v[148:149], v[160:161], v[128:129], v[168:169] neg_lo:[1,0,0] neg_hi:[1,0,0]
	v_pk_fma_f32 v[150:151], v[162:163], v[130:131], v[170:171] neg_lo:[1,0,0] neg_hi:[1,0,0]
	v_pk_fma_f32 v[128:129], v[148:149], v[164:165], v[128:129]
	v_pk_fma_f32 v[130:131], v[150:151], v[166:167], v[130:131]
	v_pk_fma_f32 v[160:161], v[160:161], v[128:129], v[168:169] neg_lo:[1,0,0] neg_hi:[1,0,0]
	v_pk_fma_f32 v[162:163], v[162:163], v[130:131], v[170:171] neg_lo:[1,0,0] neg_hi:[1,0,0]
	v_div_fmas_f32 v163, v163, v167, v131
	s_mov_b64 vcc, s[28:29]
	v_div_fmas_f32 v162, v162, v166, v130
	s_mov_b64 vcc, s[26:27]
	v_div_fmas_f32 v161, v161, v165, v129
	s_mov_b64 vcc, s[2:3]
	v_div_fmas_f32 v160, v160, v164, v128
	v_div_fixup_f32 v152, v160, v152, 1.0
	v_div_fixup_f32 v153, v161, v153, 1.0
	v_div_fixup_f32 v154, v162, v154, 1.0
	v_div_fixup_f32 v155, v163, v155, 1.0
	v_div_scale_f32 v160, s[38:39], v156, v156, 1.0
	v_div_scale_f32 v161, s[38:39], v157, v157, 1.0
	v_div_scale_f32 v162, s[38:39], v158, v158, 1.0
	v_div_scale_f32 v163, s[38:39], v159, v159, 1.0
	v_rcp_f32_e32 v164, v160
	v_rcp_f32_e32 v165, v161
	v_rcp_f32_e32 v166, v162
	v_rcp_f32_e32 v167, v163
	v_pk_fma_f32 v[148:149], v[160:161], v[164:165], 1.0 op_sel_hi:[1,1,0] neg_lo:[1,0,0] neg_hi:[1,0,0]
	v_pk_fma_f32 v[150:151], v[162:163], v[166:167], 1.0 op_sel_hi:[1,1,0] neg_lo:[1,0,0] neg_hi:[1,0,0]
	v_pk_fma_f32 v[164:165], v[148:149], v[164:165], v[164:165]
	v_pk_fma_f32 v[166:167], v[150:151], v[166:167], v[166:167]
	v_div_scale_f32 v168, s[2:3], 1.0, v156, 1.0
	v_div_scale_f32 v169, s[26:27], 1.0, v157, 1.0
	v_div_scale_f32 v170, s[28:29], 1.0, v158, 1.0
	v_div_scale_f32 v171, vcc, 1.0, v159, 1.0
	v_pk_mul_f32 v[128:129], v[168:169], v[164:165]
	v_pk_mul_f32 v[130:131], v[170:171], v[166:167]
	v_pk_fma_f32 v[148:149], v[160:161], v[128:129], v[168:169] neg_lo:[1,0,0] neg_hi:[1,0,0]
	v_pk_fma_f32 v[150:151], v[162:163], v[130:131], v[170:171] neg_lo:[1,0,0] neg_hi:[1,0,0]
	v_pk_fma_f32 v[128:129], v[148:149], v[164:165], v[128:129]
	v_pk_fma_f32 v[130:131], v[150:151], v[166:167], v[130:131]
	v_pk_fma_f32 v[160:161], v[160:161], v[128:129], v[168:169] neg_lo:[1,0,0] neg_hi:[1,0,0]
	v_pk_fma_f32 v[162:163], v[162:163], v[130:131], v[170:171] neg_lo:[1,0,0] neg_hi:[1,0,0]
	v_div_fmas_f32 v163, v163, v167, v131
	s_mov_b64 vcc, s[28:29]
	v_div_fmas_f32 v162, v162, v166, v130
	s_mov_b64 vcc, s[26:27]
	v_div_fmas_f32 v161, v161, v165, v129
	s_mov_b64 vcc, s[2:3]
	v_div_fmas_f32 v160, v160, v164, v128
	v_div_fixup_f32 v156, v160, v156, 1.0
	v_div_fixup_f32 v157, v161, v157, 1.0
	v_div_fixup_f32 v158, v162, v158, 1.0
	v_div_fixup_f32 v159, v163, v159, 1.0
	v_pk_mul_f32 v[152:153], v[68:69], v[152:153]
	v_pk_mul_f32 v[154:155], v[70:71], v[154:155]
	v_pk_mul_f32 v[156:157], v[64:65], v[156:157]
	v_pk_mul_f32 v[158:159], v[66:67], v[158:159]
	v_cvt_pk_bf16_f32 v168, v152, v153
	v_cvt_pk_bf16_f32 v169, v154, v155
	v_cvt_pk_bf16_f32 v170, v156, v157
	v_cvt_pk_bf16_f32 v171, v158, v159
	global_store_dwordx4 v187, v[168:171], s[68:69] offset:256
	global_load_dwordx4 v[68:71], v181, s[64:65] offset:256
	s_waitcnt vmcnt(6)
	v_lshlrev_b32_e32 v152, 16, v92
	v_and_b32_e32 v153, 0xffff0000, v92
	v_lshlrev_b32_e32 v154, 16, v93
	v_and_b32_e32 v155, 0xffff0000, v93
	v_lshlrev_b32_e32 v156, 16, v94
	v_and_b32_e32 v157, 0xffff0000, v94
	v_lshlrev_b32_e32 v158, 16, v95
	v_and_b32_e32 v159, 0xffff0000, v95
	v_mul_f32_e32 v152, 0xbfb8aa3b, v152
	v_mul_f32_e32 v153, 0xbfb8aa3b, v153
	v_mul_f32_e32 v154, 0xbfb8aa3b, v154
	v_mul_f32_e32 v155, 0xbfb8aa3b, v155
	v_mul_f32_e32 v156, 0xbfb8aa3b, v156
	v_mul_f32_e32 v157, 0xbfb8aa3b, v157
	v_mul_f32_e32 v158, 0xbfb8aa3b, v158
	v_mul_f32_e32 v159, 0xbfb8aa3b, v159
	v_exp_f32_e32 v152, v152
	v_exp_f32_e32 v153, v153
	v_exp_f32_e32 v154, v154
	v_exp_f32_e32 v155, v155
	v_exp_f32_e32 v156, v156
	v_exp_f32_e32 v157, v157
	v_exp_f32_e32 v158, v158
	v_exp_f32_e32 v159, v159
	v_pk_add_f32 v[152:153], v[152:153], 1.0 op_sel_hi:[1,0]
	v_pk_add_f32 v[154:155], v[154:155], 1.0 op_sel_hi:[1,0]
	v_pk_add_f32 v[156:157], v[156:157], 1.0 op_sel_hi:[1,0]
	v_pk_add_f32 v[158:159], v[158:159], 1.0 op_sel_hi:[1,0]
	v_div_scale_f32 v160, s[38:39], v152, v152, 1.0
	v_div_scale_f32 v161, s[38:39], v153, v153, 1.0
	v_div_scale_f32 v162, s[38:39], v154, v154, 1.0
	v_div_scale_f32 v163, s[38:39], v155, v155, 1.0
	v_rcp_f32_e32 v164, v160
	v_rcp_f32_e32 v165, v161
	v_rcp_f32_e32 v166, v162
	v_rcp_f32_e32 v167, v163
	v_pk_fma_f32 v[148:149], v[160:161], v[164:165], 1.0 op_sel_hi:[1,1,0] neg_lo:[1,0,0] neg_hi:[1,0,0]
	v_pk_fma_f32 v[150:151], v[162:163], v[166:167], 1.0 op_sel_hi:[1,1,0] neg_lo:[1,0,0] neg_hi:[1,0,0]
	v_pk_fma_f32 v[164:165], v[148:149], v[164:165], v[164:165]
	v_pk_fma_f32 v[166:167], v[150:151], v[166:167], v[166:167]
	v_div_scale_f32 v168, s[2:3], 1.0, v152, 1.0
	v_div_scale_f32 v169, s[26:27], 1.0, v153, 1.0
	v_div_scale_f32 v170, s[28:29], 1.0, v154, 1.0
	v_div_scale_f32 v171, vcc, 1.0, v155, 1.0
	v_pk_mul_f32 v[128:129], v[168:169], v[164:165]
	v_pk_mul_f32 v[130:131], v[170:171], v[166:167]
	v_pk_fma_f32 v[148:149], v[160:161], v[128:129], v[168:169] neg_lo:[1,0,0] neg_hi:[1,0,0]
	v_pk_fma_f32 v[150:151], v[162:163], v[130:131], v[170:171] neg_lo:[1,0,0] neg_hi:[1,0,0]
	v_pk_fma_f32 v[128:129], v[148:149], v[164:165], v[128:129]
	v_pk_fma_f32 v[130:131], v[150:151], v[166:167], v[130:131]
	v_pk_fma_f32 v[160:161], v[160:161], v[128:129], v[168:169] neg_lo:[1,0,0] neg_hi:[1,0,0]
	v_pk_fma_f32 v[162:163], v[162:163], v[130:131], v[170:171] neg_lo:[1,0,0] neg_hi:[1,0,0]
	v_div_fmas_f32 v163, v163, v167, v131
	s_mov_b64 vcc, s[28:29]
	v_div_fmas_f32 v162, v162, v166, v130
	s_mov_b64 vcc, s[26:27]
	v_div_fmas_f32 v161, v161, v165, v129
	s_mov_b64 vcc, s[2:3]
	v_div_fmas_f32 v160, v160, v164, v128
	v_div_fixup_f32 v152, v160, v152, 1.0
	v_div_fixup_f32 v153, v161, v153, 1.0
	v_div_fixup_f32 v154, v162, v154, 1.0
	v_div_fixup_f32 v155, v163, v155, 1.0
	v_div_scale_f32 v160, s[38:39], v156, v156, 1.0
	v_div_scale_f32 v161, s[38:39], v157, v157, 1.0
	v_div_scale_f32 v162, s[38:39], v158, v158, 1.0
	v_div_scale_f32 v163, s[38:39], v159, v159, 1.0
	v_rcp_f32_e32 v164, v160
	v_rcp_f32_e32 v165, v161
	v_rcp_f32_e32 v166, v162
	v_rcp_f32_e32 v167, v163
	v_pk_fma_f32 v[148:149], v[160:161], v[164:165], 1.0 op_sel_hi:[1,1,0] neg_lo:[1,0,0] neg_hi:[1,0,0]
	v_pk_fma_f32 v[150:151], v[162:163], v[166:167], 1.0 op_sel_hi:[1,1,0] neg_lo:[1,0,0] neg_hi:[1,0,0]
	v_pk_fma_f32 v[164:165], v[148:149], v[164:165], v[164:165]
	v_pk_fma_f32 v[166:167], v[150:151], v[166:167], v[166:167]
	v_div_scale_f32 v168, s[2:3], 1.0, v156, 1.0
	v_div_scale_f32 v169, s[26:27], 1.0, v157, 1.0
	v_div_scale_f32 v170, s[28:29], 1.0, v158, 1.0
	v_div_scale_f32 v171, vcc, 1.0, v159, 1.0
	v_pk_mul_f32 v[128:129], v[168:169], v[164:165]
	v_pk_mul_f32 v[130:131], v[170:171], v[166:167]
	v_pk_fma_f32 v[148:149], v[160:161], v[128:129], v[168:169] neg_lo:[1,0,0] neg_hi:[1,0,0]
	v_pk_fma_f32 v[150:151], v[162:163], v[130:131], v[170:171] neg_lo:[1,0,0] neg_hi:[1,0,0]
	v_pk_fma_f32 v[128:129], v[148:149], v[164:165], v[128:129]
	v_pk_fma_f32 v[130:131], v[150:151], v[166:167], v[130:131]
	v_pk_fma_f32 v[160:161], v[160:161], v[128:129], v[168:169] neg_lo:[1,0,0] neg_hi:[1,0,0]
	v_pk_fma_f32 v[162:163], v[162:163], v[130:131], v[170:171] neg_lo:[1,0,0] neg_hi:[1,0,0]
	v_div_fmas_f32 v163, v163, v167, v131
	s_mov_b64 vcc, s[28:29]
	v_div_fmas_f32 v162, v162, v166, v130
	s_mov_b64 vcc, s[26:27]
	v_div_fmas_f32 v161, v161, v165, v129
	s_mov_b64 vcc, s[2:3]
	v_div_fmas_f32 v160, v160, v164, v128
	v_div_fixup_f32 v156, v160, v156, 1.0
	v_div_fixup_f32 v157, v161, v157, 1.0
	v_div_fixup_f32 v158, v162, v158, 1.0
	v_div_fixup_f32 v159, v163, v159, 1.0
	v_pk_mul_f32 v[152:153], v[60:61], v[152:153]
	v_pk_mul_f32 v[154:155], v[62:63], v[154:155]
	v_pk_mul_f32 v[156:157], v[56:57], v[156:157]
	v_pk_mul_f32 v[158:159], v[58:59], v[158:159]
	v_cvt_pk_bf16_f32 v168, v152, v153
	v_cvt_pk_bf16_f32 v169, v154, v155
	v_cvt_pk_bf16_f32 v170, v156, v157
	v_cvt_pk_bf16_f32 v171, v158, v159
	global_store_dwordx4 v188, v[168:171], s[68:69]
	global_load_dwordx4 v[60:63], v182, s[64:65]
	s_waitcnt vmcnt(6)
	v_lshlrev_b32_e32 v152, 16, v84
	v_and_b32_e32 v153, 0xffff0000, v84
	v_lshlrev_b32_e32 v154, 16, v85
	v_and_b32_e32 v155, 0xffff0000, v85
	v_lshlrev_b32_e32 v156, 16, v86
	v_and_b32_e32 v157, 0xffff0000, v86
	v_lshlrev_b32_e32 v158, 16, v87
	v_and_b32_e32 v159, 0xffff0000, v87
	v_mul_f32_e32 v152, 0xbfb8aa3b, v152
	v_mul_f32_e32 v153, 0xbfb8aa3b, v153
	v_mul_f32_e32 v154, 0xbfb8aa3b, v154
	v_mul_f32_e32 v155, 0xbfb8aa3b, v155
	v_mul_f32_e32 v156, 0xbfb8aa3b, v156
	v_mul_f32_e32 v157, 0xbfb8aa3b, v157
	v_mul_f32_e32 v158, 0xbfb8aa3b, v158
	v_mul_f32_e32 v159, 0xbfb8aa3b, v159
	v_exp_f32_e32 v152, v152
	v_exp_f32_e32 v153, v153
	v_exp_f32_e32 v154, v154
	v_exp_f32_e32 v155, v155
	v_exp_f32_e32 v156, v156
	v_exp_f32_e32 v157, v157
	v_exp_f32_e32 v158, v158
	v_exp_f32_e32 v159, v159
	v_pk_add_f32 v[152:153], v[152:153], 1.0 op_sel_hi:[1,0]
	v_pk_add_f32 v[154:155], v[154:155], 1.0 op_sel_hi:[1,0]
	v_pk_add_f32 v[156:157], v[156:157], 1.0 op_sel_hi:[1,0]
	v_pk_add_f32 v[158:159], v[158:159], 1.0 op_sel_hi:[1,0]
	v_div_scale_f32 v160, s[38:39], v152, v152, 1.0
	v_div_scale_f32 v161, s[38:39], v153, v153, 1.0
	v_div_scale_f32 v162, s[38:39], v154, v154, 1.0
	v_div_scale_f32 v163, s[38:39], v155, v155, 1.0
	v_rcp_f32_e32 v164, v160
	v_rcp_f32_e32 v165, v161
	v_rcp_f32_e32 v166, v162
	v_rcp_f32_e32 v167, v163
	v_pk_fma_f32 v[148:149], v[160:161], v[164:165], 1.0 op_sel_hi:[1,1,0] neg_lo:[1,0,0] neg_hi:[1,0,0]
	v_pk_fma_f32 v[150:151], v[162:163], v[166:167], 1.0 op_sel_hi:[1,1,0] neg_lo:[1,0,0] neg_hi:[1,0,0]
	v_pk_fma_f32 v[164:165], v[148:149], v[164:165], v[164:165]
	v_pk_fma_f32 v[166:167], v[150:151], v[166:167], v[166:167]
	v_div_scale_f32 v168, s[2:3], 1.0, v152, 1.0
	v_div_scale_f32 v169, s[26:27], 1.0, v153, 1.0
	v_div_scale_f32 v170, s[28:29], 1.0, v154, 1.0
	v_div_scale_f32 v171, vcc, 1.0, v155, 1.0
	v_pk_mul_f32 v[128:129], v[168:169], v[164:165]
	v_pk_mul_f32 v[130:131], v[170:171], v[166:167]
	v_pk_fma_f32 v[148:149], v[160:161], v[128:129], v[168:169] neg_lo:[1,0,0] neg_hi:[1,0,0]
	v_pk_fma_f32 v[150:151], v[162:163], v[130:131], v[170:171] neg_lo:[1,0,0] neg_hi:[1,0,0]
	v_pk_fma_f32 v[128:129], v[148:149], v[164:165], v[128:129]
	v_pk_fma_f32 v[130:131], v[150:151], v[166:167], v[130:131]
	v_pk_fma_f32 v[160:161], v[160:161], v[128:129], v[168:169] neg_lo:[1,0,0] neg_hi:[1,0,0]
	v_pk_fma_f32 v[162:163], v[162:163], v[130:131], v[170:171] neg_lo:[1,0,0] neg_hi:[1,0,0]
	v_div_fmas_f32 v163, v163, v167, v131
	s_mov_b64 vcc, s[28:29]
	v_div_fmas_f32 v162, v162, v166, v130
	s_mov_b64 vcc, s[26:27]
	v_div_fmas_f32 v161, v161, v165, v129
	s_mov_b64 vcc, s[2:3]
	v_div_fmas_f32 v160, v160, v164, v128
	v_div_fixup_f32 v152, v160, v152, 1.0
	v_div_fixup_f32 v153, v161, v153, 1.0
	v_div_fixup_f32 v154, v162, v154, 1.0
	v_div_fixup_f32 v155, v163, v155, 1.0
	v_div_scale_f32 v160, s[38:39], v156, v156, 1.0
	v_div_scale_f32 v161, s[38:39], v157, v157, 1.0
	v_div_scale_f32 v162, s[38:39], v158, v158, 1.0
	v_div_scale_f32 v163, s[38:39], v159, v159, 1.0
	v_rcp_f32_e32 v164, v160
	v_rcp_f32_e32 v165, v161
	v_rcp_f32_e32 v166, v162
	v_rcp_f32_e32 v167, v163
	v_pk_fma_f32 v[148:149], v[160:161], v[164:165], 1.0 op_sel_hi:[1,1,0] neg_lo:[1,0,0] neg_hi:[1,0,0]
	v_pk_fma_f32 v[150:151], v[162:163], v[166:167], 1.0 op_sel_hi:[1,1,0] neg_lo:[1,0,0] neg_hi:[1,0,0]
	v_pk_fma_f32 v[164:165], v[148:149], v[164:165], v[164:165]
	v_pk_fma_f32 v[166:167], v[150:151], v[166:167], v[166:167]
	v_div_scale_f32 v168, s[2:3], 1.0, v156, 1.0
	v_div_scale_f32 v169, s[26:27], 1.0, v157, 1.0
	v_div_scale_f32 v170, s[28:29], 1.0, v158, 1.0
	v_div_scale_f32 v171, vcc, 1.0, v159, 1.0
	v_pk_mul_f32 v[128:129], v[168:169], v[164:165]
	v_pk_mul_f32 v[130:131], v[170:171], v[166:167]
	v_pk_fma_f32 v[148:149], v[160:161], v[128:129], v[168:169] neg_lo:[1,0,0] neg_hi:[1,0,0]
	v_pk_fma_f32 v[150:151], v[162:163], v[130:131], v[170:171] neg_lo:[1,0,0] neg_hi:[1,0,0]
	v_pk_fma_f32 v[128:129], v[148:149], v[164:165], v[128:129]
	v_pk_fma_f32 v[130:131], v[150:151], v[166:167], v[130:131]
	v_pk_fma_f32 v[160:161], v[160:161], v[128:129], v[168:169] neg_lo:[1,0,0] neg_hi:[1,0,0]
	v_pk_fma_f32 v[162:163], v[162:163], v[130:131], v[170:171] neg_lo:[1,0,0] neg_hi:[1,0,0]
	v_div_fmas_f32 v163, v163, v167, v131
	s_mov_b64 vcc, s[28:29]
	v_div_fmas_f32 v162, v162, v166, v130
	s_mov_b64 vcc, s[26:27]
	v_div_fmas_f32 v161, v161, v165, v129
	s_mov_b64 vcc, s[2:3]
	v_div_fmas_f32 v160, v160, v164, v128
	v_div_fixup_f32 v156, v160, v156, 1.0
	v_div_fixup_f32 v157, v161, v157, 1.0
	v_div_fixup_f32 v158, v162, v158, 1.0
	v_div_fixup_f32 v159, v163, v159, 1.0
	v_pk_mul_f32 v[152:153], v[52:53], v[152:153]
	v_pk_mul_f32 v[154:155], v[54:55], v[154:155]
	v_pk_mul_f32 v[156:157], v[48:49], v[156:157]
	v_pk_mul_f32 v[158:159], v[50:51], v[158:159]
	v_cvt_pk_bf16_f32 v168, v152, v153
	v_cvt_pk_bf16_f32 v169, v154, v155
	v_cvt_pk_bf16_f32 v170, v156, v157
	v_cvt_pk_bf16_f32 v171, v158, v159
	global_store_dwordx4 v188, v[168:171], s[68:69] offset:256
	global_load_dwordx4 v[52:55], v182, s[64:65] offset:256
	s_waitcnt vmcnt(6)
	v_lshlrev_b32_e32 v152, 16, v76
	v_and_b32_e32 v153, 0xffff0000, v76
	v_lshlrev_b32_e32 v154, 16, v77
	v_and_b32_e32 v155, 0xffff0000, v77
	v_lshlrev_b32_e32 v156, 16, v78
	v_and_b32_e32 v157, 0xffff0000, v78
	v_lshlrev_b32_e32 v158, 16, v79
	v_and_b32_e32 v159, 0xffff0000, v79
	v_mul_f32_e32 v152, 0xbfb8aa3b, v152
	v_mul_f32_e32 v153, 0xbfb8aa3b, v153
	v_mul_f32_e32 v154, 0xbfb8aa3b, v154
	v_mul_f32_e32 v155, 0xbfb8aa3b, v155
	v_mul_f32_e32 v156, 0xbfb8aa3b, v156
	v_mul_f32_e32 v157, 0xbfb8aa3b, v157
	v_mul_f32_e32 v158, 0xbfb8aa3b, v158
	v_mul_f32_e32 v159, 0xbfb8aa3b, v159
	v_exp_f32_e32 v152, v152
	v_exp_f32_e32 v153, v153
	v_exp_f32_e32 v154, v154
	v_exp_f32_e32 v155, v155
	v_exp_f32_e32 v156, v156
	v_exp_f32_e32 v157, v157
	v_exp_f32_e32 v158, v158
	v_exp_f32_e32 v159, v159
	v_pk_add_f32 v[152:153], v[152:153], 1.0 op_sel_hi:[1,0]
	v_pk_add_f32 v[154:155], v[154:155], 1.0 op_sel_hi:[1,0]
	v_pk_add_f32 v[156:157], v[156:157], 1.0 op_sel_hi:[1,0]
	v_pk_add_f32 v[158:159], v[158:159], 1.0 op_sel_hi:[1,0]
	v_div_scale_f32 v160, s[38:39], v152, v152, 1.0
	v_div_scale_f32 v161, s[38:39], v153, v153, 1.0
	v_div_scale_f32 v162, s[38:39], v154, v154, 1.0
	v_div_scale_f32 v163, s[38:39], v155, v155, 1.0
	v_rcp_f32_e32 v164, v160
	v_rcp_f32_e32 v165, v161
	v_rcp_f32_e32 v166, v162
	v_rcp_f32_e32 v167, v163
	v_pk_fma_f32 v[148:149], v[160:161], v[164:165], 1.0 op_sel_hi:[1,1,0] neg_lo:[1,0,0] neg_hi:[1,0,0]
	v_pk_fma_f32 v[150:151], v[162:163], v[166:167], 1.0 op_sel_hi:[1,1,0] neg_lo:[1,0,0] neg_hi:[1,0,0]
	v_pk_fma_f32 v[164:165], v[148:149], v[164:165], v[164:165]
	v_pk_fma_f32 v[166:167], v[150:151], v[166:167], v[166:167]
	v_div_scale_f32 v168, s[2:3], 1.0, v152, 1.0
	v_div_scale_f32 v169, s[26:27], 1.0, v153, 1.0
	v_div_scale_f32 v170, s[28:29], 1.0, v154, 1.0
	v_div_scale_f32 v171, vcc, 1.0, v155, 1.0
	v_pk_mul_f32 v[128:129], v[168:169], v[164:165]
	v_pk_mul_f32 v[130:131], v[170:171], v[166:167]
	v_pk_fma_f32 v[148:149], v[160:161], v[128:129], v[168:169] neg_lo:[1,0,0] neg_hi:[1,0,0]
	v_pk_fma_f32 v[150:151], v[162:163], v[130:131], v[170:171] neg_lo:[1,0,0] neg_hi:[1,0,0]
	v_pk_fma_f32 v[128:129], v[148:149], v[164:165], v[128:129]
	v_pk_fma_f32 v[130:131], v[150:151], v[166:167], v[130:131]
	v_pk_fma_f32 v[160:161], v[160:161], v[128:129], v[168:169] neg_lo:[1,0,0] neg_hi:[1,0,0]
	v_pk_fma_f32 v[162:163], v[162:163], v[130:131], v[170:171] neg_lo:[1,0,0] neg_hi:[1,0,0]
	v_div_fmas_f32 v163, v163, v167, v131
	s_mov_b64 vcc, s[28:29]
	v_div_fmas_f32 v162, v162, v166, v130
	s_mov_b64 vcc, s[26:27]
	v_div_fmas_f32 v161, v161, v165, v129
	s_mov_b64 vcc, s[2:3]
	v_div_fmas_f32 v160, v160, v164, v128
	v_div_fixup_f32 v152, v160, v152, 1.0
	v_div_fixup_f32 v153, v161, v153, 1.0
	v_div_fixup_f32 v154, v162, v154, 1.0
	v_div_fixup_f32 v155, v163, v155, 1.0
	v_div_scale_f32 v160, s[38:39], v156, v156, 1.0
	v_div_scale_f32 v161, s[38:39], v157, v157, 1.0
	v_div_scale_f32 v162, s[38:39], v158, v158, 1.0
	v_div_scale_f32 v163, s[38:39], v159, v159, 1.0
	v_rcp_f32_e32 v164, v160
	v_rcp_f32_e32 v165, v161
	v_rcp_f32_e32 v166, v162
	v_rcp_f32_e32 v167, v163
	v_pk_fma_f32 v[148:149], v[160:161], v[164:165], 1.0 op_sel_hi:[1,1,0] neg_lo:[1,0,0] neg_hi:[1,0,0]
	v_pk_fma_f32 v[150:151], v[162:163], v[166:167], 1.0 op_sel_hi:[1,1,0] neg_lo:[1,0,0] neg_hi:[1,0,0]
	v_pk_fma_f32 v[164:165], v[148:149], v[164:165], v[164:165]
	v_pk_fma_f32 v[166:167], v[150:151], v[166:167], v[166:167]
	v_div_scale_f32 v168, s[2:3], 1.0, v156, 1.0
	v_div_scale_f32 v169, s[26:27], 1.0, v157, 1.0
	v_div_scale_f32 v170, s[28:29], 1.0, v158, 1.0
	v_div_scale_f32 v171, vcc, 1.0, v159, 1.0
	v_pk_mul_f32 v[128:129], v[168:169], v[164:165]
	v_pk_mul_f32 v[130:131], v[170:171], v[166:167]
	v_pk_fma_f32 v[148:149], v[160:161], v[128:129], v[168:169] neg_lo:[1,0,0] neg_hi:[1,0,0]
	v_pk_fma_f32 v[150:151], v[162:163], v[130:131], v[170:171] neg_lo:[1,0,0] neg_hi:[1,0,0]
	v_pk_fma_f32 v[128:129], v[148:149], v[164:165], v[128:129]
	v_pk_fma_f32 v[130:131], v[150:151], v[166:167], v[130:131]
	v_pk_fma_f32 v[160:161], v[160:161], v[128:129], v[168:169] neg_lo:[1,0,0] neg_hi:[1,0,0]
	v_pk_fma_f32 v[162:163], v[162:163], v[130:131], v[170:171] neg_lo:[1,0,0] neg_hi:[1,0,0]
	v_div_fmas_f32 v163, v163, v167, v131
	s_mov_b64 vcc, s[28:29]
	v_div_fmas_f32 v162, v162, v166, v130
	s_mov_b64 vcc, s[26:27]
	v_div_fmas_f32 v161, v161, v165, v129
	s_mov_b64 vcc, s[2:3]
	v_div_fmas_f32 v160, v160, v164, v128
	v_div_fixup_f32 v156, v160, v156, 1.0
	v_div_fixup_f32 v157, v161, v157, 1.0
	v_div_fixup_f32 v158, v162, v158, 1.0
	v_div_fixup_f32 v159, v163, v159, 1.0
	v_pk_mul_f32 v[152:153], v[44:45], v[152:153]
	v_pk_mul_f32 v[154:155], v[46:47], v[154:155]
	v_pk_mul_f32 v[156:157], v[40:41], v[156:157]
	v_pk_mul_f32 v[158:159], v[42:43], v[158:159]
	v_cvt_pk_bf16_f32 v168, v152, v153
	v_cvt_pk_bf16_f32 v169, v154, v155
	v_cvt_pk_bf16_f32 v170, v156, v157
	v_cvt_pk_bf16_f32 v171, v158, v159
	global_store_dwordx4 v189, v[168:171], s[68:69]
	global_load_dwordx4 v[44:47], v183, s[64:65]
	s_waitcnt vmcnt(6)
; __device__ __forceinline__ float sigmoidf_(float x) { return 1.f / (1.f + __expf(-x)); }
	v_lshlrev_b32_e32 v152, 16, v68
	v_and_b32_e32 v153, 0xffff0000, v68
	v_lshlrev_b32_e32 v154, 16, v69
	v_and_b32_e32 v155, 0xffff0000, v69
	v_lshlrev_b32_e32 v156, 16, v70
	v_and_b32_e32 v157, 0xffff0000, v70
	v_lshlrev_b32_e32 v158, 16, v71
	v_and_b32_e32 v159, 0xffff0000, v71
	v_mul_f32_e32 v152, 0xbfb8aa3b, v152
	v_mul_f32_e32 v153, 0xbfb8aa3b, v153
	v_mul_f32_e32 v154, 0xbfb8aa3b, v154
	v_mul_f32_e32 v155, 0xbfb8aa3b, v155
	v_mul_f32_e32 v156, 0xbfb8aa3b, v156
	v_mul_f32_e32 v157, 0xbfb8aa3b, v157
	v_mul_f32_e32 v158, 0xbfb8aa3b, v158
	v_mul_f32_e32 v159, 0xbfb8aa3b, v159
	v_exp_f32_e32 v152, v152
	v_exp_f32_e32 v153, v153
	v_exp_f32_e32 v154, v154
	v_exp_f32_e32 v155, v155
	v_exp_f32_e32 v156, v156
	v_exp_f32_e32 v157, v157
	v_exp_f32_e32 v158, v158
	v_exp_f32_e32 v159, v159
	v_pk_add_f32 v[152:153], v[152:153], 1.0 op_sel_hi:[1,0]
	v_pk_add_f32 v[154:155], v[154:155], 1.0 op_sel_hi:[1,0]
	v_pk_add_f32 v[156:157], v[156:157], 1.0 op_sel_hi:[1,0]
	v_pk_add_f32 v[158:159], v[158:159], 1.0 op_sel_hi:[1,0]
	v_div_scale_f32 v160, s[38:39], v152, v152, 1.0
	v_div_scale_f32 v161, s[38:39], v153, v153, 1.0
	v_div_scale_f32 v162, s[38:39], v154, v154, 1.0
	v_div_scale_f32 v163, s[38:39], v155, v155, 1.0
	v_rcp_f32_e32 v164, v160
	v_rcp_f32_e32 v165, v161
	v_rcp_f32_e32 v166, v162
	v_rcp_f32_e32 v167, v163
	v_pk_fma_f32 v[148:149], v[160:161], v[164:165], 1.0 op_sel_hi:[1,1,0] neg_lo:[1,0,0] neg_hi:[1,0,0]
	v_pk_fma_f32 v[150:151], v[162:163], v[166:167], 1.0 op_sel_hi:[1,1,0] neg_lo:[1,0,0] neg_hi:[1,0,0]
	v_pk_fma_f32 v[164:165], v[148:149], v[164:165], v[164:165]
	v_pk_fma_f32 v[166:167], v[150:151], v[166:167], v[166:167]
	v_div_scale_f32 v168, s[2:3], 1.0, v152, 1.0
	v_div_scale_f32 v169, s[26:27], 1.0, v153, 1.0
	v_div_scale_f32 v170, s[28:29], 1.0, v154, 1.0
	v_div_scale_f32 v171, vcc, 1.0, v155, 1.0
	v_pk_mul_f32 v[128:129], v[168:169], v[164:165]
	v_pk_mul_f32 v[130:131], v[170:171], v[166:167]
	v_pk_fma_f32 v[148:149], v[160:161], v[128:129], v[168:169] neg_lo:[1,0,0] neg_hi:[1,0,0]
	v_pk_fma_f32 v[150:151], v[162:163], v[130:131], v[170:171] neg_lo:[1,0,0] neg_hi:[1,0,0]
	v_pk_fma_f32 v[128:129], v[148:149], v[164:165], v[128:129]
	v_pk_fma_f32 v[130:131], v[150:151], v[166:167], v[130:131]
	v_pk_fma_f32 v[160:161], v[160:161], v[128:129], v[168:169] neg_lo:[1,0,0] neg_hi:[1,0,0]
	v_pk_fma_f32 v[162:163], v[162:163], v[130:131], v[170:171] neg_lo:[1,0,0] neg_hi:[1,0,0]
	v_div_fmas_f32 v163, v163, v167, v131
	s_mov_b64 vcc, s[28:29]
	v_div_fmas_f32 v162, v162, v166, v130
	s_mov_b64 vcc, s[26:27]
	v_div_fmas_f32 v161, v161, v165, v129
	s_mov_b64 vcc, s[2:3]
	v_div_fmas_f32 v160, v160, v164, v128
	v_div_fixup_f32 v152, v160, v152, 1.0
	v_div_fixup_f32 v153, v161, v153, 1.0
	v_div_fixup_f32 v154, v162, v154, 1.0
	v_div_fixup_f32 v155, v163, v155, 1.0
	v_div_scale_f32 v160, s[38:39], v156, v156, 1.0
	v_div_scale_f32 v161, s[38:39], v157, v157, 1.0
	v_div_scale_f32 v162, s[38:39], v158, v158, 1.0
	v_div_scale_f32 v163, s[38:39], v159, v159, 1.0
	v_rcp_f32_e32 v164, v160
	v_rcp_f32_e32 v165, v161
	v_rcp_f32_e32 v166, v162
	v_rcp_f32_e32 v167, v163
	v_pk_fma_f32 v[148:149], v[160:161], v[164:165], 1.0 op_sel_hi:[1,1,0] neg_lo:[1,0,0] neg_hi:[1,0,0]
	v_pk_fma_f32 v[150:151], v[162:163], v[166:167], 1.0 op_sel_hi:[1,1,0] neg_lo:[1,0,0] neg_hi:[1,0,0]
	v_pk_fma_f32 v[164:165], v[148:149], v[164:165], v[164:165]
	v_pk_fma_f32 v[166:167], v[150:151], v[166:167], v[166:167]
	v_div_scale_f32 v168, s[2:3], 1.0, v156, 1.0
	v_div_scale_f32 v169, s[26:27], 1.0, v157, 1.0
	v_div_scale_f32 v170, s[28:29], 1.0, v158, 1.0
	v_div_scale_f32 v171, vcc, 1.0, v159, 1.0
	v_pk_mul_f32 v[128:129], v[168:169], v[164:165]
	v_pk_mul_f32 v[130:131], v[170:171], v[166:167]
	v_pk_fma_f32 v[148:149], v[160:161], v[128:129], v[168:169] neg_lo:[1,0,0] neg_hi:[1,0,0]
	v_pk_fma_f32 v[150:151], v[162:163], v[130:131], v[170:171] neg_lo:[1,0,0] neg_hi:[1,0,0]
	v_pk_fma_f32 v[128:129], v[148:149], v[164:165], v[128:129]
	v_pk_fma_f32 v[130:131], v[150:151], v[166:167], v[130:131]
	v_pk_fma_f32 v[160:161], v[160:161], v[128:129], v[168:169] neg_lo:[1,0,0] neg_hi:[1,0,0]
	v_pk_fma_f32 v[162:163], v[162:163], v[130:131], v[170:171] neg_lo:[1,0,0] neg_hi:[1,0,0]
	v_div_fmas_f32 v163, v163, v167, v131
	s_mov_b64 vcc, s[28:29]
	v_div_fmas_f32 v162, v162, v166, v130
	s_mov_b64 vcc, s[26:27]
	v_div_fmas_f32 v161, v161, v165, v129
	s_mov_b64 vcc, s[2:3]
	v_div_fmas_f32 v160, v160, v164, v128
	v_div_fixup_f32 v156, v160, v156, 1.0
	v_div_fixup_f32 v157, v161, v157, 1.0
	v_div_fixup_f32 v158, v162, v158, 1.0
	v_div_fixup_f32 v159, v163, v159, 1.0
	v_pk_mul_f32 v[152:153], v[36:37], v[152:153]
	v_pk_mul_f32 v[154:155], v[38:39], v[154:155]
	v_pk_mul_f32 v[156:157], v[32:33], v[156:157]
	v_pk_mul_f32 v[158:159], v[34:35], v[158:159]
	v_cvt_pk_bf16_f32 v168, v152, v153
	v_cvt_pk_bf16_f32 v169, v154, v155
	v_cvt_pk_bf16_f32 v170, v156, v157
	v_cvt_pk_bf16_f32 v171, v158, v159
	global_store_dwordx4 v189, v[168:171], s[68:69] offset:256
	global_load_dwordx4 v[36:39], v183, s[64:65] offset:256
	s_waitcnt vmcnt(6)
; __device__ __forceinline__ float sigmoidf_(float x) { return 1.f / (1.f + __expf(-x)); }
	v_lshlrev_b32_e32 v152, 16, v60
	v_and_b32_e32 v153, 0xffff0000, v60
	v_lshlrev_b32_e32 v154, 16, v61
	v_and_b32_e32 v155, 0xffff0000, v61
	v_lshlrev_b32_e32 v156, 16, v62
	v_and_b32_e32 v157, 0xffff0000, v62
	v_lshlrev_b32_e32 v158, 16, v63
	v_and_b32_e32 v159, 0xffff0000, v63
	v_mul_f32_e32 v152, 0xbfb8aa3b, v152
	v_mul_f32_e32 v153, 0xbfb8aa3b, v153
	v_mul_f32_e32 v154, 0xbfb8aa3b, v154
	v_mul_f32_e32 v155, 0xbfb8aa3b, v155
	v_mul_f32_e32 v156, 0xbfb8aa3b, v156
	v_mul_f32_e32 v157, 0xbfb8aa3b, v157
	v_mul_f32_e32 v158, 0xbfb8aa3b, v158
	v_mul_f32_e32 v159, 0xbfb8aa3b, v159
	v_exp_f32_e32 v152, v152
	v_exp_f32_e32 v153, v153
	v_exp_f32_e32 v154, v154
	v_exp_f32_e32 v155, v155
	v_exp_f32_e32 v156, v156
	v_exp_f32_e32 v157, v157
	v_exp_f32_e32 v158, v158
	v_exp_f32_e32 v159, v159
	v_pk_add_f32 v[152:153], v[152:153], 1.0 op_sel_hi:[1,0]
	v_pk_add_f32 v[154:155], v[154:155], 1.0 op_sel_hi:[1,0]
	v_pk_add_f32 v[156:157], v[156:157], 1.0 op_sel_hi:[1,0]
	v_pk_add_f32 v[158:159], v[158:159], 1.0 op_sel_hi:[1,0]
	v_div_scale_f32 v160, s[38:39], v152, v152, 1.0
	v_div_scale_f32 v161, s[38:39], v153, v153, 1.0
	v_div_scale_f32 v162, s[38:39], v154, v154, 1.0
	v_div_scale_f32 v163, s[38:39], v155, v155, 1.0
	v_rcp_f32_e32 v164, v160
	v_rcp_f32_e32 v165, v161
	v_rcp_f32_e32 v166, v162
	v_rcp_f32_e32 v167, v163
	v_pk_fma_f32 v[148:149], v[160:161], v[164:165], 1.0 op_sel_hi:[1,1,0] neg_lo:[1,0,0] neg_hi:[1,0,0]
	v_pk_fma_f32 v[150:151], v[162:163], v[166:167], 1.0 op_sel_hi:[1,1,0] neg_lo:[1,0,0] neg_hi:[1,0,0]
	v_pk_fma_f32 v[164:165], v[148:149], v[164:165], v[164:165]
	v_pk_fma_f32 v[166:167], v[150:151], v[166:167], v[166:167]
	v_div_scale_f32 v168, s[2:3], 1.0, v152, 1.0
	v_div_scale_f32 v169, s[26:27], 1.0, v153, 1.0
	v_div_scale_f32 v170, s[28:29], 1.0, v154, 1.0
	v_div_scale_f32 v171, vcc, 1.0, v155, 1.0
	v_pk_mul_f32 v[128:129], v[168:169], v[164:165]
	v_pk_mul_f32 v[130:131], v[170:171], v[166:167]
	v_pk_fma_f32 v[148:149], v[160:161], v[128:129], v[168:169] neg_lo:[1,0,0] neg_hi:[1,0,0]
	v_pk_fma_f32 v[150:151], v[162:163], v[130:131], v[170:171] neg_lo:[1,0,0] neg_hi:[1,0,0]
	v_pk_fma_f32 v[128:129], v[148:149], v[164:165], v[128:129]
	v_pk_fma_f32 v[130:131], v[150:151], v[166:167], v[130:131]
	v_pk_fma_f32 v[160:161], v[160:161], v[128:129], v[168:169] neg_lo:[1,0,0] neg_hi:[1,0,0]
	v_pk_fma_f32 v[162:163], v[162:163], v[130:131], v[170:171] neg_lo:[1,0,0] neg_hi:[1,0,0]
	v_div_fmas_f32 v163, v163, v167, v131
	s_mov_b64 vcc, s[28:29]
	v_div_fmas_f32 v162, v162, v166, v130
	s_mov_b64 vcc, s[26:27]
	v_div_fmas_f32 v161, v161, v165, v129
	s_mov_b64 vcc, s[2:3]
	v_div_fmas_f32 v160, v160, v164, v128
	v_div_fixup_f32 v152, v160, v152, 1.0
	v_div_fixup_f32 v153, v161, v153, 1.0
	v_div_fixup_f32 v154, v162, v154, 1.0
	v_div_fixup_f32 v155, v163, v155, 1.0
	v_div_scale_f32 v160, s[38:39], v156, v156, 1.0
	v_div_scale_f32 v161, s[38:39], v157, v157, 1.0
	v_div_scale_f32 v162, s[38:39], v158, v158, 1.0
	v_div_scale_f32 v163, s[38:39], v159, v159, 1.0
	v_rcp_f32_e32 v164, v160
	v_rcp_f32_e32 v165, v161
	v_rcp_f32_e32 v166, v162
	v_rcp_f32_e32 v167, v163
	v_pk_fma_f32 v[148:149], v[160:161], v[164:165], 1.0 op_sel_hi:[1,1,0] neg_lo:[1,0,0] neg_hi:[1,0,0]
	v_pk_fma_f32 v[150:151], v[162:163], v[166:167], 1.0 op_sel_hi:[1,1,0] neg_lo:[1,0,0] neg_hi:[1,0,0]
	v_pk_fma_f32 v[164:165], v[148:149], v[164:165], v[164:165]
	v_pk_fma_f32 v[166:167], v[150:151], v[166:167], v[166:167]
	v_div_scale_f32 v168, s[2:3], 1.0, v156, 1.0
	v_div_scale_f32 v169, s[26:27], 1.0, v157, 1.0
	v_div_scale_f32 v170, s[28:29], 1.0, v158, 1.0
	v_div_scale_f32 v171, vcc, 1.0, v159, 1.0
	v_pk_mul_f32 v[128:129], v[168:169], v[164:165]
	v_pk_mul_f32 v[130:131], v[170:171], v[166:167]
	v_pk_fma_f32 v[148:149], v[160:161], v[128:129], v[168:169] neg_lo:[1,0,0] neg_hi:[1,0,0]
	v_pk_fma_f32 v[150:151], v[162:163], v[130:131], v[170:171] neg_lo:[1,0,0] neg_hi:[1,0,0]
	v_pk_fma_f32 v[128:129], v[148:149], v[164:165], v[128:129]
	v_pk_fma_f32 v[130:131], v[150:151], v[166:167], v[130:131]
	v_pk_fma_f32 v[160:161], v[160:161], v[128:129], v[168:169] neg_lo:[1,0,0] neg_hi:[1,0,0]
	v_pk_fma_f32 v[162:163], v[162:163], v[130:131], v[170:171] neg_lo:[1,0,0] neg_hi:[1,0,0]
	v_div_fmas_f32 v163, v163, v167, v131
	s_mov_b64 vcc, s[28:29]
	v_div_fmas_f32 v162, v162, v166, v130
	s_mov_b64 vcc, s[26:27]
	v_div_fmas_f32 v161, v161, v165, v129
	s_mov_b64 vcc, s[2:3]
	v_div_fmas_f32 v160, v160, v164, v128
	v_div_fixup_f32 v156, v160, v156, 1.0
	v_div_fixup_f32 v157, v161, v157, 1.0
	v_div_fixup_f32 v158, v162, v158, 1.0
	v_div_fixup_f32 v159, v163, v159, 1.0
	v_pk_mul_f32 v[152:153], v[28:29], v[152:153]
	v_pk_mul_f32 v[154:155], v[30:31], v[154:155]
	v_pk_mul_f32 v[156:157], v[24:25], v[156:157]
	v_pk_mul_f32 v[158:159], v[26:27], v[158:159]
	v_cvt_pk_bf16_f32 v168, v152, v153
	v_cvt_pk_bf16_f32 v169, v154, v155
	v_cvt_pk_bf16_f32 v170, v156, v157
	v_cvt_pk_bf16_f32 v171, v158, v159
	global_store_dwordx4 v190, v[168:171], s[68:69]
	s_waitcnt vmcnt(5)
; __device__ __forceinline__ float sigmoidf_(float x) { return 1.f / (1.f + __expf(-x)); }
	v_lshlrev_b32_e32 v152, 16, v52
	v_and_b32_e32 v153, 0xffff0000, v52
	v_lshlrev_b32_e32 v154, 16, v53
	v_and_b32_e32 v155, 0xffff0000, v53
	v_lshlrev_b32_e32 v156, 16, v54
	v_and_b32_e32 v157, 0xffff0000, v54
	v_lshlrev_b32_e32 v158, 16, v55
	v_and_b32_e32 v159, 0xffff0000, v55
	v_mul_f32_e32 v152, 0xbfb8aa3b, v152
	v_mul_f32_e32 v153, 0xbfb8aa3b, v153
	v_mul_f32_e32 v154, 0xbfb8aa3b, v154
	v_mul_f32_e32 v155, 0xbfb8aa3b, v155
	v_mul_f32_e32 v156, 0xbfb8aa3b, v156
	v_mul_f32_e32 v157, 0xbfb8aa3b, v157
	v_mul_f32_e32 v158, 0xbfb8aa3b, v158
	v_mul_f32_e32 v159, 0xbfb8aa3b, v159
	v_exp_f32_e32 v152, v152
	v_exp_f32_e32 v153, v153
	v_exp_f32_e32 v154, v154
	v_exp_f32_e32 v155, v155
	v_exp_f32_e32 v156, v156
	v_exp_f32_e32 v157, v157
	v_exp_f32_e32 v158, v158
	v_exp_f32_e32 v159, v159
	v_pk_add_f32 v[152:153], v[152:153], 1.0 op_sel_hi:[1,0]
	v_pk_add_f32 v[154:155], v[154:155], 1.0 op_sel_hi:[1,0]
	v_pk_add_f32 v[156:157], v[156:157], 1.0 op_sel_hi:[1,0]
	v_pk_add_f32 v[158:159], v[158:159], 1.0 op_sel_hi:[1,0]
	v_div_scale_f32 v160, s[38:39], v152, v152, 1.0
	v_div_scale_f32 v161, s[38:39], v153, v153, 1.0
	v_div_scale_f32 v162, s[38:39], v154, v154, 1.0
	v_div_scale_f32 v163, s[38:39], v155, v155, 1.0
	v_rcp_f32_e32 v164, v160
	v_rcp_f32_e32 v165, v161
	v_rcp_f32_e32 v166, v162
	v_rcp_f32_e32 v167, v163
	v_pk_fma_f32 v[148:149], v[160:161], v[164:165], 1.0 op_sel_hi:[1,1,0] neg_lo:[1,0,0] neg_hi:[1,0,0]
	v_pk_fma_f32 v[150:151], v[162:163], v[166:167], 1.0 op_sel_hi:[1,1,0] neg_lo:[1,0,0] neg_hi:[1,0,0]
	v_pk_fma_f32 v[164:165], v[148:149], v[164:165], v[164:165]
	v_pk_fma_f32 v[166:167], v[150:151], v[166:167], v[166:167]
	v_div_scale_f32 v168, s[2:3], 1.0, v152, 1.0
	v_div_scale_f32 v169, s[26:27], 1.0, v153, 1.0
	v_div_scale_f32 v170, s[28:29], 1.0, v154, 1.0
	v_div_scale_f32 v171, vcc, 1.0, v155, 1.0
	v_pk_mul_f32 v[128:129], v[168:169], v[164:165]
	v_pk_mul_f32 v[130:131], v[170:171], v[166:167]
	v_pk_fma_f32 v[148:149], v[160:161], v[128:129], v[168:169] neg_lo:[1,0,0] neg_hi:[1,0,0]
	v_pk_fma_f32 v[150:151], v[162:163], v[130:131], v[170:171] neg_lo:[1,0,0] neg_hi:[1,0,0]
	v_pk_fma_f32 v[128:129], v[148:149], v[164:165], v[128:129]
	v_pk_fma_f32 v[130:131], v[150:151], v[166:167], v[130:131]
	v_pk_fma_f32 v[160:161], v[160:161], v[128:129], v[168:169] neg_lo:[1,0,0] neg_hi:[1,0,0]
	v_pk_fma_f32 v[162:163], v[162:163], v[130:131], v[170:171] neg_lo:[1,0,0] neg_hi:[1,0,0]
	v_div_fmas_f32 v163, v163, v167, v131
	s_mov_b64 vcc, s[28:29]
	v_div_fmas_f32 v162, v162, v166, v130
	s_mov_b64 vcc, s[26:27]
	v_div_fmas_f32 v161, v161, v165, v129
	s_mov_b64 vcc, s[2:3]
	v_div_fmas_f32 v160, v160, v164, v128
	v_div_fixup_f32 v152, v160, v152, 1.0
	v_div_fixup_f32 v153, v161, v153, 1.0
	v_div_fixup_f32 v154, v162, v154, 1.0
	v_div_fixup_f32 v155, v163, v155, 1.0
	v_div_scale_f32 v160, s[38:39], v156, v156, 1.0
	v_div_scale_f32 v161, s[38:39], v157, v157, 1.0
	v_div_scale_f32 v162, s[38:39], v158, v158, 1.0
	v_div_scale_f32 v163, s[38:39], v159, v159, 1.0
	v_rcp_f32_e32 v164, v160
	v_rcp_f32_e32 v165, v161
	v_rcp_f32_e32 v166, v162
	v_rcp_f32_e32 v167, v163
	v_pk_fma_f32 v[148:149], v[160:161], v[164:165], 1.0 op_sel_hi:[1,1,0] neg_lo:[1,0,0] neg_hi:[1,0,0]
	v_pk_fma_f32 v[150:151], v[162:163], v[166:167], 1.0 op_sel_hi:[1,1,0] neg_lo:[1,0,0] neg_hi:[1,0,0]
	v_pk_fma_f32 v[164:165], v[148:149], v[164:165], v[164:165]
	v_pk_fma_f32 v[166:167], v[150:151], v[166:167], v[166:167]
	v_div_scale_f32 v168, s[2:3], 1.0, v156, 1.0
	v_div_scale_f32 v169, s[26:27], 1.0, v157, 1.0
	v_div_scale_f32 v170, s[28:29], 1.0, v158, 1.0
	v_div_scale_f32 v171, vcc, 1.0, v159, 1.0
	v_pk_mul_f32 v[128:129], v[168:169], v[164:165]
	v_pk_mul_f32 v[130:131], v[170:171], v[166:167]
	v_pk_fma_f32 v[148:149], v[160:161], v[128:129], v[168:169] neg_lo:[1,0,0] neg_hi:[1,0,0]
	v_pk_fma_f32 v[150:151], v[162:163], v[130:131], v[170:171] neg_lo:[1,0,0] neg_hi:[1,0,0]
	v_pk_fma_f32 v[128:129], v[148:149], v[164:165], v[128:129]
	v_pk_fma_f32 v[130:131], v[150:151], v[166:167], v[130:131]
	v_pk_fma_f32 v[160:161], v[160:161], v[128:129], v[168:169] neg_lo:[1,0,0] neg_hi:[1,0,0]
	v_pk_fma_f32 v[162:163], v[162:163], v[130:131], v[170:171] neg_lo:[1,0,0] neg_hi:[1,0,0]
	v_div_fmas_f32 v163, v163, v167, v131
	s_mov_b64 vcc, s[28:29]
	v_div_fmas_f32 v162, v162, v166, v130
	s_mov_b64 vcc, s[26:27]
	v_div_fmas_f32 v161, v161, v165, v129
	s_mov_b64 vcc, s[2:3]
	v_div_fmas_f32 v160, v160, v164, v128
	v_div_fixup_f32 v156, v160, v156, 1.0
	v_div_fixup_f32 v157, v161, v157, 1.0
	v_div_fixup_f32 v158, v162, v158, 1.0
	v_div_fixup_f32 v159, v163, v159, 1.0
	v_pk_mul_f32 v[152:153], v[20:21], v[152:153]
	v_pk_mul_f32 v[154:155], v[22:23], v[154:155]
	v_pk_mul_f32 v[156:157], v[16:17], v[156:157]
	v_pk_mul_f32 v[158:159], v[18:19], v[158:159]
	v_cvt_pk_bf16_f32 v168, v152, v153
	v_cvt_pk_bf16_f32 v169, v154, v155
	v_cvt_pk_bf16_f32 v170, v156, v157
	v_cvt_pk_bf16_f32 v171, v158, v159
	global_store_dwordx4 v190, v[168:171], s[68:69] offset:256
	s_waitcnt vmcnt(4)
; __device__ __forceinline__ float sigmoidf_(float x) { return 1.f / (1.f + __expf(-x)); }
	v_lshlrev_b32_e32 v152, 16, v44
	v_and_b32_e32 v153, 0xffff0000, v44
	v_lshlrev_b32_e32 v154, 16, v45
	v_and_b32_e32 v155, 0xffff0000, v45
	v_lshlrev_b32_e32 v156, 16, v46
	v_and_b32_e32 v157, 0xffff0000, v46
	v_lshlrev_b32_e32 v158, 16, v47
	v_and_b32_e32 v159, 0xffff0000, v47
	v_mul_f32_e32 v152, 0xbfb8aa3b, v152
	v_mul_f32_e32 v153, 0xbfb8aa3b, v153
	v_mul_f32_e32 v154, 0xbfb8aa3b, v154
	v_mul_f32_e32 v155, 0xbfb8aa3b, v155
	v_mul_f32_e32 v156, 0xbfb8aa3b, v156
	v_mul_f32_e32 v157, 0xbfb8aa3b, v157
	v_mul_f32_e32 v158, 0xbfb8aa3b, v158
	v_mul_f32_e32 v159, 0xbfb8aa3b, v159
	v_exp_f32_e32 v152, v152
	v_exp_f32_e32 v153, v153
	v_exp_f32_e32 v154, v154
	v_exp_f32_e32 v155, v155
	v_exp_f32_e32 v156, v156
	v_exp_f32_e32 v157, v157
	v_exp_f32_e32 v158, v158
	v_exp_f32_e32 v159, v159
	v_pk_add_f32 v[152:153], v[152:153], 1.0 op_sel_hi:[1,0]
	v_pk_add_f32 v[154:155], v[154:155], 1.0 op_sel_hi:[1,0]
	v_pk_add_f32 v[156:157], v[156:157], 1.0 op_sel_hi:[1,0]
	v_pk_add_f32 v[158:159], v[158:159], 1.0 op_sel_hi:[1,0]
	v_div_scale_f32 v160, s[38:39], v152, v152, 1.0
	v_div_scale_f32 v161, s[38:39], v153, v153, 1.0
	v_div_scale_f32 v162, s[38:39], v154, v154, 1.0
	v_div_scale_f32 v163, s[38:39], v155, v155, 1.0
	v_rcp_f32_e32 v164, v160
	v_rcp_f32_e32 v165, v161
	v_rcp_f32_e32 v166, v162
	v_rcp_f32_e32 v167, v163
	v_pk_fma_f32 v[148:149], v[160:161], v[164:165], 1.0 op_sel_hi:[1,1,0] neg_lo:[1,0,0] neg_hi:[1,0,0]
	v_pk_fma_f32 v[150:151], v[162:163], v[166:167], 1.0 op_sel_hi:[1,1,0] neg_lo:[1,0,0] neg_hi:[1,0,0]
	v_pk_fma_f32 v[164:165], v[148:149], v[164:165], v[164:165]
	v_pk_fma_f32 v[166:167], v[150:151], v[166:167], v[166:167]
	v_div_scale_f32 v168, s[2:3], 1.0, v152, 1.0
	v_div_scale_f32 v169, s[26:27], 1.0, v153, 1.0
	v_div_scale_f32 v170, s[28:29], 1.0, v154, 1.0
	v_div_scale_f32 v171, vcc, 1.0, v155, 1.0
	v_pk_mul_f32 v[128:129], v[168:169], v[164:165]
	v_pk_mul_f32 v[130:131], v[170:171], v[166:167]
	v_pk_fma_f32 v[148:149], v[160:161], v[128:129], v[168:169] neg_lo:[1,0,0] neg_hi:[1,0,0]
	v_pk_fma_f32 v[150:151], v[162:163], v[130:131], v[170:171] neg_lo:[1,0,0] neg_hi:[1,0,0]
	v_pk_fma_f32 v[128:129], v[148:149], v[164:165], v[128:129]
	v_pk_fma_f32 v[130:131], v[150:151], v[166:167], v[130:131]
	v_pk_fma_f32 v[160:161], v[160:161], v[128:129], v[168:169] neg_lo:[1,0,0] neg_hi:[1,0,0]
	v_pk_fma_f32 v[162:163], v[162:163], v[130:131], v[170:171] neg_lo:[1,0,0] neg_hi:[1,0,0]
	v_div_fmas_f32 v163, v163, v167, v131
	s_mov_b64 vcc, s[28:29]
	v_div_fmas_f32 v162, v162, v166, v130
	s_mov_b64 vcc, s[26:27]
	v_div_fmas_f32 v161, v161, v165, v129
	s_mov_b64 vcc, s[2:3]
	v_div_fmas_f32 v160, v160, v164, v128
	v_div_fixup_f32 v152, v160, v152, 1.0
	v_div_fixup_f32 v153, v161, v153, 1.0
	v_div_fixup_f32 v154, v162, v154, 1.0
	v_div_fixup_f32 v155, v163, v155, 1.0
	v_div_scale_f32 v160, s[38:39], v156, v156, 1.0
	v_div_scale_f32 v161, s[38:39], v157, v157, 1.0
	v_div_scale_f32 v162, s[38:39], v158, v158, 1.0
	v_div_scale_f32 v163, s[38:39], v159, v159, 1.0
	v_rcp_f32_e32 v164, v160
	v_rcp_f32_e32 v165, v161
	v_rcp_f32_e32 v166, v162
	v_rcp_f32_e32 v167, v163
	v_pk_fma_f32 v[148:149], v[160:161], v[164:165], 1.0 op_sel_hi:[1,1,0] neg_lo:[1,0,0] neg_hi:[1,0,0]
	v_pk_fma_f32 v[150:151], v[162:163], v[166:167], 1.0 op_sel_hi:[1,1,0] neg_lo:[1,0,0] neg_hi:[1,0,0]
	v_pk_fma_f32 v[164:165], v[148:149], v[164:165], v[164:165]
	v_pk_fma_f32 v[166:167], v[150:151], v[166:167], v[166:167]
	v_div_scale_f32 v168, s[2:3], 1.0, v156, 1.0
	v_div_scale_f32 v169, s[26:27], 1.0, v157, 1.0
	v_div_scale_f32 v170, s[28:29], 1.0, v158, 1.0
	v_div_scale_f32 v171, vcc, 1.0, v159, 1.0
	v_pk_mul_f32 v[128:129], v[168:169], v[164:165]
	v_pk_mul_f32 v[130:131], v[170:171], v[166:167]
	v_pk_fma_f32 v[148:149], v[160:161], v[128:129], v[168:169] neg_lo:[1,0,0] neg_hi:[1,0,0]
	v_pk_fma_f32 v[150:151], v[162:163], v[130:131], v[170:171] neg_lo:[1,0,0] neg_hi:[1,0,0]
	v_pk_fma_f32 v[128:129], v[148:149], v[164:165], v[128:129]
	v_pk_fma_f32 v[130:131], v[150:151], v[166:167], v[130:131]
	v_pk_fma_f32 v[160:161], v[160:161], v[128:129], v[168:169] neg_lo:[1,0,0] neg_hi:[1,0,0]
	v_pk_fma_f32 v[162:163], v[162:163], v[130:131], v[170:171] neg_lo:[1,0,0] neg_hi:[1,0,0]
	v_div_fmas_f32 v163, v163, v167, v131
	s_mov_b64 vcc, s[28:29]
	v_div_fmas_f32 v162, v162, v166, v130
	s_mov_b64 vcc, s[26:27]
	v_div_fmas_f32 v161, v161, v165, v129
	s_mov_b64 vcc, s[2:3]
	v_div_fmas_f32 v160, v160, v164, v128
	v_div_fixup_f32 v156, v160, v156, 1.0
	v_div_fixup_f32 v157, v161, v157, 1.0
	v_div_fixup_f32 v158, v162, v158, 1.0
	v_div_fixup_f32 v159, v163, v159, 1.0
	v_pk_mul_f32 v[152:153], v[12:13], v[152:153]
	v_pk_mul_f32 v[154:155], v[14:15], v[154:155]
	v_pk_mul_f32 v[156:157], v[8:9], v[156:157]
	v_pk_mul_f32 v[158:159], v[10:11], v[158:159]
	v_cvt_pk_bf16_f32 v168, v152, v153
	v_cvt_pk_bf16_f32 v169, v154, v155
	v_cvt_pk_bf16_f32 v170, v156, v157
	v_cvt_pk_bf16_f32 v171, v158, v159
	global_store_dwordx4 v191, v[168:171], s[68:69]
	s_waitcnt vmcnt(3)
; __device__ __forceinline__ float sigmoidf_(float x) { return 1.f / (1.f + __expf(-x)); }
; template <class Epi>
; __device__ __forceinline__ void gemm_phase(LAS unsigned char* lds, const Gemm g, const Epi& E) {
;     ...
;           { E.st2(cur.w, cur.pm * BM + ai * HALF + wr * 64 + m * 16 + fr, cur.pn * BM + bj * HALF + wc * 32 + 8 * fq, acc[ai][bj][m][0], acc[ai][bj][m][1]); if (bj == 1 && (m & 1)) asm volatile("" ::: "memory"); }
	v_lshlrev_b32_e32 v152, 16, v36
	v_and_b32_e32 v153, 0xffff0000, v36
	v_lshlrev_b32_e32 v154, 16, v37
	v_and_b32_e32 v155, 0xffff0000, v37
	v_lshlrev_b32_e32 v156, 16, v38
	v_and_b32_e32 v157, 0xffff0000, v38
	v_lshlrev_b32_e32 v158, 16, v39
	v_and_b32_e32 v159, 0xffff0000, v39
	v_mul_f32_e32 v152, 0xbfb8aa3b, v152
	v_mul_f32_e32 v153, 0xbfb8aa3b, v153
	v_mul_f32_e32 v154, 0xbfb8aa3b, v154
	v_mul_f32_e32 v155, 0xbfb8aa3b, v155
	v_mul_f32_e32 v156, 0xbfb8aa3b, v156
	v_mul_f32_e32 v157, 0xbfb8aa3b, v157
	v_mul_f32_e32 v158, 0xbfb8aa3b, v158
	v_mul_f32_e32 v159, 0xbfb8aa3b, v159
	v_exp_f32_e32 v152, v152
	v_exp_f32_e32 v153, v153
	v_exp_f32_e32 v154, v154
	v_exp_f32_e32 v155, v155
	v_exp_f32_e32 v156, v156
	v_exp_f32_e32 v157, v157
	v_exp_f32_e32 v158, v158
	v_exp_f32_e32 v159, v159
	v_pk_add_f32 v[152:153], v[152:153], 1.0 op_sel_hi:[1,0]
	v_pk_add_f32 v[154:155], v[154:155], 1.0 op_sel_hi:[1,0]
	v_pk_add_f32 v[156:157], v[156:157], 1.0 op_sel_hi:[1,0]
	v_pk_add_f32 v[158:159], v[158:159], 1.0 op_sel_hi:[1,0]
	v_div_scale_f32 v160, s[38:39], v152, v152, 1.0
	v_div_scale_f32 v161, s[38:39], v153, v153, 1.0
	v_div_scale_f32 v162, s[38:39], v154, v154, 1.0
	v_div_scale_f32 v163, s[38:39], v155, v155, 1.0
	v_rcp_f32_e32 v164, v160
	v_rcp_f32_e32 v165, v161
	v_rcp_f32_e32 v166, v162
	v_rcp_f32_e32 v167, v163
	v_pk_fma_f32 v[148:149], v[160:161], v[164:165], 1.0 op_sel_hi:[1,1,0] neg_lo:[1,0,0] neg_hi:[1,0,0]
	v_pk_fma_f32 v[150:151], v[162:163], v[166:167], 1.0 op_sel_hi:[1,1,0] neg_lo:[1,0,0] neg_hi:[1,0,0]
	v_pk_fma_f32 v[164:165], v[148:149], v[164:165], v[164:165]
	v_pk_fma_f32 v[166:167], v[150:151], v[166:167], v[166:167]
	v_div_scale_f32 v168, s[2:3], 1.0, v152, 1.0
	v_div_scale_f32 v169, s[26:27], 1.0, v153, 1.0
	v_div_scale_f32 v170, s[28:29], 1.0, v154, 1.0
	v_div_scale_f32 v171, vcc, 1.0, v155, 1.0
	v_pk_mul_f32 v[128:129], v[168:169], v[164:165]
	v_pk_mul_f32 v[130:131], v[170:171], v[166:167]
	v_pk_fma_f32 v[148:149], v[160:161], v[128:129], v[168:169] neg_lo:[1,0,0] neg_hi:[1,0,0]
	v_pk_fma_f32 v[150:151], v[162:163], v[130:131], v[170:171] neg_lo:[1,0,0] neg_hi:[1,0,0]
	v_pk_fma_f32 v[128:129], v[148:149], v[164:165], v[128:129]
	v_pk_fma_f32 v[130:131], v[150:151], v[166:167], v[130:131]
	v_pk_fma_f32 v[160:161], v[160:161], v[128:129], v[168:169] neg_lo:[1,0,0] neg_hi:[1,0,0]
	v_pk_fma_f32 v[162:163], v[162:163], v[130:131], v[170:171] neg_lo:[1,0,0] neg_hi:[1,0,0]
	v_div_fmas_f32 v163, v163, v167, v131
	s_mov_b64 vcc, s[28:29]
	v_div_fmas_f32 v162, v162, v166, v130
	s_mov_b64 vcc, s[26:27]
	v_div_fmas_f32 v161, v161, v165, v129
	s_mov_b64 vcc, s[2:3]
	v_div_fmas_f32 v160, v160, v164, v128
	v_div_fixup_f32 v152, v160, v152, 1.0
	v_div_fixup_f32 v153, v161, v153, 1.0
	v_div_fixup_f32 v154, v162, v154, 1.0
	v_div_fixup_f32 v155, v163, v155, 1.0
	v_div_scale_f32 v160, s[38:39], v156, v156, 1.0
	v_div_scale_f32 v161, s[38:39], v157, v157, 1.0
	v_div_scale_f32 v162, s[38:39], v158, v158, 1.0
	v_div_scale_f32 v163, s[38:39], v159, v159, 1.0
	v_rcp_f32_e32 v164, v160
	v_rcp_f32_e32 v165, v161
	v_rcp_f32_e32 v166, v162
	v_rcp_f32_e32 v167, v163
	v_pk_fma_f32 v[148:149], v[160:161], v[164:165], 1.0 op_sel_hi:[1,1,0] neg_lo:[1,0,0] neg_hi:[1,0,0]
	v_pk_fma_f32 v[150:151], v[162:163], v[166:167], 1.0 op_sel_hi:[1,1,0] neg_lo:[1,0,0] neg_hi:[1,0,0]
	v_pk_fma_f32 v[164:165], v[148:149], v[164:165], v[164:165]
	v_pk_fma_f32 v[166:167], v[150:151], v[166:167], v[166:167]
	v_div_scale_f32 v168, s[2:3], 1.0, v156, 1.0
	v_div_scale_f32 v169, s[26:27], 1.0, v157, 1.0
	v_div_scale_f32 v170, s[28:29], 1.0, v158, 1.0
	v_div_scale_f32 v171, vcc, 1.0, v159, 1.0
	v_pk_mul_f32 v[128:129], v[168:169], v[164:165]
	v_pk_mul_f32 v[130:131], v[170:171], v[166:167]
	v_pk_fma_f32 v[148:149], v[160:161], v[128:129], v[168:169] neg_lo:[1,0,0] neg_hi:[1,0,0]
	v_pk_fma_f32 v[150:151], v[162:163], v[130:131], v[170:171] neg_lo:[1,0,0] neg_hi:[1,0,0]
	v_pk_fma_f32 v[128:129], v[148:149], v[164:165], v[128:129]
	v_pk_fma_f32 v[130:131], v[150:151], v[166:167], v[130:131]
	v_pk_fma_f32 v[160:161], v[160:161], v[128:129], v[168:169] neg_lo:[1,0,0] neg_hi:[1,0,0]
	v_pk_fma_f32 v[162:163], v[162:163], v[130:131], v[170:171] neg_lo:[1,0,0] neg_hi:[1,0,0]
	v_div_fmas_f32 v163, v163, v167, v131
	s_mov_b64 vcc, s[28:29]
	v_div_fmas_f32 v162, v162, v166, v130
	s_mov_b64 vcc, s[26:27]
	v_div_fmas_f32 v161, v161, v165, v129
	s_mov_b64 vcc, s[2:3]
	v_div_fmas_f32 v160, v160, v164, v128
	v_div_fixup_f32 v156, v160, v156, 1.0
	v_div_fixup_f32 v157, v161, v157, 1.0
	v_div_fixup_f32 v158, v162, v158, 1.0
	v_div_fixup_f32 v159, v163, v159, 1.0
	v_pk_mul_f32 v[152:153], v[4:5], v[152:153]
	v_pk_mul_f32 v[154:155], v[6:7], v[154:155]
	v_pk_mul_f32 v[156:157], v[0:1], v[156:157]
	v_pk_mul_f32 v[158:159], v[2:3], v[158:159]
	v_cvt_pk_bf16_f32 v168, v152, v153
	v_cvt_pk_bf16_f32 v169, v154, v155
	v_cvt_pk_bf16_f32 v170, v156, v157
	v_cvt_pk_bf16_f32 v171, v158, v159
	global_store_dwordx4 v191, v[168:171], s[68:69] offset:256
	s_mov_b32 s32, 1
	s_branch .LBB0_567
; __device__ __forceinline__ float sigmoidf_(float x) { return 1.f / (1.f + __expf(-x)); }
.Lepi4:
	v_mul_u32_u24_e32 v176, 0x1800, v150
	v_lshl_add_u32 v176, v148, 1, v176
	v_add_u32_e32 v176, 0x1000, v176
	v_lshlrev_b32_e32 v184, 11, v150
	v_lshl_add_u32 v184, v148, 1, v184
	v_add_u32_e32 v177, 0x18000, v176
	v_add_u32_e32 v185, 0x8000, v184
	v_add_u32_e32 v178, 0x30000, v176
	v_add_u32_e32 v186, 0x10000, v184
	v_add_u32_e32 v179, 0x48000, v176
	v_add_u32_e32 v187, 0x18000, v184
	v_add_u32_e32 v180, 0xc0000, v176
	v_add_u32_e32 v188, 0x40000, v184
	v_add_u32_e32 v181, 0xd8000, v176
	v_add_u32_e32 v189, 0x48000, v184
	v_add_u32_e32 v182, 0xf0000, v176
	v_add_u32_e32 v190, 0x50000, v184
	v_add_u32_e32 v183, 0x108000, v176
	v_add_u32_e32 v191, 0x58000, v184
	global_load_dwordx4 v[192:195], v176, s[64:65]
	global_load_dwordx4 v[196:199], v184, s[68:69]
	global_load_dwordx4 v[200:203], v176, s[64:65] offset:256
	global_load_dwordx4 v[204:207], v184, s[68:69] offset:256
	global_load_dwordx4 v[208:211], v177, s[64:65]
	global_load_dwordx4 v[212:215], v185, s[68:69]
	global_load_dwordx4 v[216:219], v177, s[64:65] offset:256
	global_load_dwordx4 v[220:223], v185, s[68:69] offset:256
	s_waitcnt vmcnt(6)
	v_lshlrev_b32_e32 v152, 16, v192
	v_and_b32_e32 v153, 0xffff0000, v192
	v_lshlrev_b32_e32 v154, 16, v193
	v_and_b32_e32 v155, 0xffff0000, v193
	v_lshlrev_b32_e32 v156, 16, v194
	v_and_b32_e32 v157, 0xffff0000, v194
	v_lshlrev_b32_e32 v158, 16, v195
	v_and_b32_e32 v159, 0xffff0000, v195
	v_mul_f32_e32 v152, 0xbfb8aa3b, v152
	v_mul_f32_e32 v153, 0xbfb8aa3b, v153
	v_mul_f32_e32 v154, 0xbfb8aa3b, v154
	v_mul_f32_e32 v155, 0xbfb8aa3b, v155
	v_mul_f32_e32 v156, 0xbfb8aa3b, v156
	v_mul_f32_e32 v157, 0xbfb8aa3b, v157
	v_mul_f32_e32 v158, 0xbfb8aa3b, v158
	v_mul_f32_e32 v159, 0xbfb8aa3b, v159
	v_exp_f32_e32 v152, v152
	v_exp_f32_e32 v153, v153
	v_exp_f32_e32 v154, v154
	v_exp_f32_e32 v155, v155
	v_exp_f32_e32 v156, v156
	v_exp_f32_e32 v157, v157
	v_exp_f32_e32 v158, v158
	v_exp_f32_e32 v159, v159
	v_pk_add_f32 v[152:153], v[152:153], 1.0 op_sel_hi:[1,0]
	v_pk_add_f32 v[154:155], v[154:155], 1.0 op_sel_hi:[1,0]
	v_pk_add_f32 v[156:157], v[156:157], 1.0 op_sel_hi:[1,0]
	v_pk_add_f32 v[158:159], v[158:159], 1.0 op_sel_hi:[1,0]
	v_div_scale_f32 v160, s[38:39], v152, v152, 1.0
	v_div_scale_f32 v161, s[38:39], v153, v153, 1.0
	v_div_scale_f32 v162, s[38:39], v154, v154, 1.0
	v_div_scale_f32 v163, s[38:39], v155, v155, 1.0
	v_rcp_f32_e32 v164, v160
	v_rcp_f32_e32 v165, v161
	v_rcp_f32_e32 v166, v162
	v_rcp_f32_e32 v167, v163
	v_pk_fma_f32 v[148:149], v[160:161], v[164:165], 1.0 op_sel_hi:[1,1,0] neg_lo:[1,0,0] neg_hi:[1,0,0]
	v_pk_fma_f32 v[150:151], v[162:163], v[166:167], 1.0 op_sel_hi:[1,1,0] neg_lo:[1,0,0] neg_hi:[1,0,0]
	v_pk_fma_f32 v[164:165], v[148:149], v[164:165], v[164:165]
	v_pk_fma_f32 v[166:167], v[150:151], v[166:167], v[166:167]
	v_div_scale_f32 v168, s[2:3], 1.0, v152, 1.0
	v_div_scale_f32 v169, s[26:27], 1.0, v153, 1.0
	v_div_scale_f32 v170, s[28:29], 1.0, v154, 1.0
	v_div_scale_f32 v171, vcc, 1.0, v155, 1.0
	v_pk_mul_f32 v[128:129], v[168:169], v[164:165]
	v_pk_mul_f32 v[130:131], v[170:171], v[166:167]
	v_pk_fma_f32 v[148:149], v[160:161], v[128:129], v[168:169] neg_lo:[1,0,0] neg_hi:[1,0,0]
	v_pk_fma_f32 v[150:151], v[162:163], v[130:131], v[170:171] neg_lo:[1,0,0] neg_hi:[1,0,0]
	v_pk_fma_f32 v[128:129], v[148:149], v[164:165], v[128:129]
	v_pk_fma_f32 v[130:131], v[150:151], v[166:167], v[130:131]
	v_pk_fma_f32 v[160:161], v[160:161], v[128:129], v[168:169] neg_lo:[1,0,0] neg_hi:[1,0,0]
	v_pk_fma_f32 v[162:163], v[162:163], v[130:131], v[170:171] neg_lo:[1,0,0] neg_hi:[1,0,0]
	v_div_fmas_f32 v163, v163, v167, v131
	s_mov_b64 vcc, s[28:29]
	v_div_fmas_f32 v162, v162, v166, v130
	s_mov_b64 vcc, s[26:27]
	v_div_fmas_f32 v161, v161, v165, v129
	s_mov_b64 vcc, s[2:3]
	v_div_fmas_f32 v160, v160, v164, v128
	v_div_fixup_f32 v152, v160, v152, 1.0
	v_div_fixup_f32 v153, v161, v153, 1.0
	v_div_fixup_f32 v154, v162, v154, 1.0
	v_div_fixup_f32 v155, v163, v155, 1.0
	v_div_scale_f32 v160, s[38:39], v156, v156, 1.0
	v_div_scale_f32 v161, s[38:39], v157, v157, 1.0
	v_div_scale_f32 v162, s[38:39], v158, v158, 1.0
	v_div_scale_f32 v163, s[38:39], v159, v159, 1.0
	v_rcp_f32_e32 v164, v160
	v_rcp_f32_e32 v165, v161
	v_rcp_f32_e32 v166, v162
	v_rcp_f32_e32 v167, v163
	v_pk_fma_f32 v[148:149], v[160:161], v[164:165], 1.0 op_sel_hi:[1,1,0] neg_lo:[1,0,0] neg_hi:[1,0,0]
	v_pk_fma_f32 v[150:151], v[162:163], v[166:167], 1.0 op_sel_hi:[1,1,0] neg_lo:[1,0,0] neg_hi:[1,0,0]
	v_pk_fma_f32 v[164:165], v[148:149], v[164:165], v[164:165]
	v_pk_fma_f32 v[166:167], v[150:151], v[166:167], v[166:167]
	v_div_scale_f32 v168, s[2:3], 1.0, v156, 1.0
	v_div_scale_f32 v169, s[26:27], 1.0, v157, 1.0
	v_div_scale_f32 v170, s[28:29], 1.0, v158, 1.0
	v_div_scale_f32 v171, vcc, 1.0, v159, 1.0
	v_pk_mul_f32 v[128:129], v[168:169], v[164:165]
	v_pk_mul_f32 v[130:131], v[170:171], v[166:167]
	v_pk_fma_f32 v[148:149], v[160:161], v[128:129], v[168:169] neg_lo:[1,0,0] neg_hi:[1,0,0]
	v_pk_fma_f32 v[150:151], v[162:163], v[130:131], v[170:171] neg_lo:[1,0,0] neg_hi:[1,0,0]
	v_pk_fma_f32 v[128:129], v[148:149], v[164:165], v[128:129]
	v_pk_fma_f32 v[130:131], v[150:151], v[166:167], v[130:131]
	v_pk_fma_f32 v[160:161], v[160:161], v[128:129], v[168:169] neg_lo:[1,0,0] neg_hi:[1,0,0]
	v_pk_fma_f32 v[162:163], v[162:163], v[130:131], v[170:171] neg_lo:[1,0,0] neg_hi:[1,0,0]
	v_div_fmas_f32 v163, v163, v167, v131
	s_mov_b64 vcc, s[28:29]
	v_div_fmas_f32 v162, v162, v166, v130
	s_mov_b64 vcc, s[26:27]
	v_div_fmas_f32 v161, v161, v165, v129
	s_mov_b64 vcc, s[2:3]
	v_div_fmas_f32 v160, v160, v164, v128
	v_div_fixup_f32 v156, v160, v156, 1.0
	v_div_fixup_f32 v157, v161, v157, 1.0
	v_div_fixup_f32 v158, v162, v158, 1.0
	v_div_fixup_f32 v159, v163, v159, 1.0
	v_lshlrev_b32_e32 v166, 16, v196
	v_and_b32_e32 v167, 0xffff0000, v196
	v_pk_fma_f32 v[152:153], v[124:125], v[152:153], v[166:167]
	v_lshlrev_b32_e32 v166, 16, v197
	v_and_b32_e32 v167, 0xffff0000, v197
	v_pk_fma_f32 v[154:155], v[126:127], v[154:155], v[166:167]
	v_lshlrev_b32_e32 v166, 16, v198
	v_and_b32_e32 v167, 0xffff0000, v198
	v_pk_fma_f32 v[156:157], v[120:121], v[156:157], v[166:167]
	v_lshlrev_b32_e32 v166, 16, v199
	v_and_b32_e32 v167, 0xffff0000, v199
	v_pk_fma_f32 v[158:159], v[122:123], v[158:159], v[166:167]
	v_cvt_pk_bf16_f32 v168, v152, v153
	v_cvt_pk_bf16_f32 v169, v154, v155
	v_cvt_pk_bf16_f32 v170, v156, v157
	v_cvt_pk_bf16_f32 v171, v158, v159
	global_store_dwordx4 v184, v[168:171], s[66:67]
	global_load_dwordx4 v[124:127], v178, s[64:65]
	global_load_dwordx4 v[120:123], v186, s[68:69]
	s_waitcnt vmcnt(7)
; __device__ __forceinline__ float sigmoidf_(float x) { return 1.f / (1.f + __expf(-x)); }
	v_lshlrev_b32_e32 v152, 16, v200
	v_and_b32_e32 v153, 0xffff0000, v200
	v_lshlrev_b32_e32 v154, 16, v201
	v_and_b32_e32 v155, 0xffff0000, v201
	v_lshlrev_b32_e32 v156, 16, v202
	v_and_b32_e32 v157, 0xffff0000, v202
	v_lshlrev_b32_e32 v158, 16, v203
	v_and_b32_e32 v159, 0xffff0000, v203
	v_mul_f32_e32 v152, 0xbfb8aa3b, v152
	v_mul_f32_e32 v153, 0xbfb8aa3b, v153
	v_mul_f32_e32 v154, 0xbfb8aa3b, v154
	v_mul_f32_e32 v155, 0xbfb8aa3b, v155
	v_mul_f32_e32 v156, 0xbfb8aa3b, v156
	v_mul_f32_e32 v157, 0xbfb8aa3b, v157
	v_mul_f32_e32 v158, 0xbfb8aa3b, v158
	v_mul_f32_e32 v159, 0xbfb8aa3b, v159
	v_exp_f32_e32 v152, v152
	v_exp_f32_e32 v153, v153
	v_exp_f32_e32 v154, v154
	v_exp_f32_e32 v155, v155
	v_exp_f32_e32 v156, v156
	v_exp_f32_e32 v157, v157
	v_exp_f32_e32 v158, v158
	v_exp_f32_e32 v159, v159
	v_pk_add_f32 v[152:153], v[152:153], 1.0 op_sel_hi:[1,0]
	v_pk_add_f32 v[154:155], v[154:155], 1.0 op_sel_hi:[1,0]
	v_pk_add_f32 v[156:157], v[156:157], 1.0 op_sel_hi:[1,0]
	v_pk_add_f32 v[158:159], v[158:159], 1.0 op_sel_hi:[1,0]
	v_div_scale_f32 v160, s[38:39], v152, v152, 1.0
	v_div_scale_f32 v161, s[38:39], v153, v153, 1.0
	v_div_scale_f32 v162, s[38:39], v154, v154, 1.0
	v_div_scale_f32 v163, s[38:39], v155, v155, 1.0
	v_rcp_f32_e32 v164, v160
	v_rcp_f32_e32 v165, v161
	v_rcp_f32_e32 v166, v162
	v_rcp_f32_e32 v167, v163
	v_pk_fma_f32 v[148:149], v[160:161], v[164:165], 1.0 op_sel_hi:[1,1,0] neg_lo:[1,0,0] neg_hi:[1,0,0]
	v_pk_fma_f32 v[150:151], v[162:163], v[166:167], 1.0 op_sel_hi:[1,1,0] neg_lo:[1,0,0] neg_hi:[1,0,0]
	v_pk_fma_f32 v[164:165], v[148:149], v[164:165], v[164:165]
	v_pk_fma_f32 v[166:167], v[150:151], v[166:167], v[166:167]
	v_div_scale_f32 v168, s[2:3], 1.0, v152, 1.0
	v_div_scale_f32 v169, s[26:27], 1.0, v153, 1.0
	v_div_scale_f32 v170, s[28:29], 1.0, v154, 1.0
	v_div_scale_f32 v171, vcc, 1.0, v155, 1.0
	v_pk_mul_f32 v[128:129], v[168:169], v[164:165]
	v_pk_mul_f32 v[130:131], v[170:171], v[166:167]
	v_pk_fma_f32 v[148:149], v[160:161], v[128:129], v[168:169] neg_lo:[1,0,0] neg_hi:[1,0,0]
	v_pk_fma_f32 v[150:151], v[162:163], v[130:131], v[170:171] neg_lo:[1,0,0] neg_hi:[1,0,0]
	v_pk_fma_f32 v[128:129], v[148:149], v[164:165], v[128:129]
	v_pk_fma_f32 v[130:131], v[150:151], v[166:167], v[130:131]
	v_pk_fma_f32 v[160:161], v[160:161], v[128:129], v[168:169] neg_lo:[1,0,0] neg_hi:[1,0,0]
	v_pk_fma_f32 v[162:163], v[162:163], v[130:131], v[170:171] neg_lo:[1,0,0] neg_hi:[1,0,0]
	v_div_fmas_f32 v163, v163, v167, v131
	s_mov_b64 vcc, s[28:29]
	v_div_fmas_f32 v162, v162, v166, v130
	s_mov_b64 vcc, s[26:27]
	v_div_fmas_f32 v161, v161, v165, v129
	s_mov_b64 vcc, s[2:3]
	v_div_fmas_f32 v160, v160, v164, v128
	v_div_fixup_f32 v152, v160, v152, 1.0
	v_div_fixup_f32 v153, v161, v153, 1.0
	v_div_fixup_f32 v154, v162, v154, 1.0
	v_div_fixup_f32 v155, v163, v155, 1.0
	v_div_scale_f32 v160, s[38:39], v156, v156, 1.0
	v_div_scale_f32 v161, s[38:39], v157, v157, 1.0
	v_div_scale_f32 v162, s[38:39], v158, v158, 1.0
	v_div_scale_f32 v163, s[38:39], v159, v159, 1.0
	v_rcp_f32_e32 v164, v160
	v_rcp_f32_e32 v165, v161
	v_rcp_f32_e32 v166, v162
	v_rcp_f32_e32 v167, v163
	v_pk_fma_f32 v[148:149], v[160:161], v[164:165], 1.0 op_sel_hi:[1,1,0] neg_lo:[1,0,0] neg_hi:[1,0,0]
	v_pk_fma_f32 v[150:151], v[162:163], v[166:167], 1.0 op_sel_hi:[1,1,0] neg_lo:[1,0,0] neg_hi:[1,0,0]
	v_pk_fma_f32 v[164:165], v[148:149], v[164:165], v[164:165]
	v_pk_fma_f32 v[166:167], v[150:151], v[166:167], v[166:167]
	v_div_scale_f32 v168, s[2:3], 1.0, v156, 1.0
	v_div_scale_f32 v169, s[26:27], 1.0, v157, 1.0
	v_div_scale_f32 v170, s[28:29], 1.0, v158, 1.0
	v_div_scale_f32 v171, vcc, 1.0, v159, 1.0
	v_pk_mul_f32 v[128:129], v[168:169], v[164:165]
	v_pk_mul_f32 v[130:131], v[170:171], v[166:167]
	v_pk_fma_f32 v[148:149], v[160:161], v[128:129], v[168:169] neg_lo:[1,0,0] neg_hi:[1,0,0]
	v_pk_fma_f32 v[150:151], v[162:163], v[130:131], v[170:171] neg_lo:[1,0,0] neg_hi:[1,0,0]
	v_pk_fma_f32 v[128:129], v[148:149], v[164:165], v[128:129]
	v_pk_fma_f32 v[130:131], v[150:151], v[166:167], v[130:131]
	v_pk_fma_f32 v[160:161], v[160:161], v[128:129], v[168:169] neg_lo:[1,0,0] neg_hi:[1,0,0]
	v_pk_fma_f32 v[162:163], v[162:163], v[130:131], v[170:171] neg_lo:[1,0,0] neg_hi:[1,0,0]
	v_div_fmas_f32 v163, v163, v167, v131
	s_mov_b64 vcc, s[28:29]
	v_div_fmas_f32 v162, v162, v166, v130
	s_mov_b64 vcc, s[26:27]
	v_div_fmas_f32 v161, v161, v165, v129
	s_mov_b64 vcc, s[2:3]
	v_div_fmas_f32 v160, v160, v164, v128
	v_div_fixup_f32 v156, v160, v156, 1.0
	v_div_fixup_f32 v157, v161, v157, 1.0
	v_div_fixup_f32 v158, v162, v158, 1.0
	v_div_fixup_f32 v159, v163, v159, 1.0
	v_lshlrev_b32_e32 v166, 16, v204
	v_and_b32_e32 v167, 0xffff0000, v204
	v_pk_fma_f32 v[152:153], v[116:117], v[152:153], v[166:167]
	v_lshlrev_b32_e32 v166, 16, v205
	v_and_b32_e32 v167, 0xffff0000, v205
	v_pk_fma_f32 v[154:155], v[118:119], v[154:155], v[166:167]
	v_lshlrev_b32_e32 v166, 16, v206
	v_and_b32_e32 v167, 0xffff0000, v206
	v_pk_fma_f32 v[156:157], v[112:113], v[156:157], v[166:167]
	v_lshlrev_b32_e32 v166, 16, v207
	v_and_b32_e32 v167, 0xffff0000, v207
	v_pk_fma_f32 v[158:159], v[114:115], v[158:159], v[166:167]
	v_cvt_pk_bf16_f32 v168, v152, v153
	v_cvt_pk_bf16_f32 v169, v154, v155
	v_cvt_pk_bf16_f32 v170, v156, v157
	v_cvt_pk_bf16_f32 v171, v158, v159
	global_store_dwordx4 v184, v[168:171], s[66:67] offset:256
	global_load_dwordx4 v[116:119], v178, s[64:65] offset:256
	global_load_dwordx4 v[112:115], v186, s[68:69] offset:256
	s_waitcnt vmcnt(8)
; __device__ __forceinline__ float sigmoidf_(float x) { return 1.f / (1.f + __expf(-x)); }
	v_lshlrev_b32_e32 v152, 16, v208
	v_and_b32_e32 v153, 0xffff0000, v208
	v_lshlrev_b32_e32 v154, 16, v209
	v_and_b32_e32 v155, 0xffff0000, v209
	v_lshlrev_b32_e32 v156, 16, v210
	v_and_b32_e32 v157, 0xffff0000, v210
	v_lshlrev_b32_e32 v158, 16, v211
	v_and_b32_e32 v159, 0xffff0000, v211
	v_mul_f32_e32 v152, 0xbfb8aa3b, v152
	v_mul_f32_e32 v153, 0xbfb8aa3b, v153
	v_mul_f32_e32 v154, 0xbfb8aa3b, v154
	v_mul_f32_e32 v155, 0xbfb8aa3b, v155
	v_mul_f32_e32 v156, 0xbfb8aa3b, v156
	v_mul_f32_e32 v157, 0xbfb8aa3b, v157
	v_mul_f32_e32 v158, 0xbfb8aa3b, v158
	v_mul_f32_e32 v159, 0xbfb8aa3b, v159
	v_exp_f32_e32 v152, v152
	v_exp_f32_e32 v153, v153
	v_exp_f32_e32 v154, v154
	v_exp_f32_e32 v155, v155
	v_exp_f32_e32 v156, v156
	v_exp_f32_e32 v157, v157
	v_exp_f32_e32 v158, v158
	v_exp_f32_e32 v159, v159
	v_pk_add_f32 v[152:153], v[152:153], 1.0 op_sel_hi:[1,0]
	v_pk_add_f32 v[154:155], v[154:155], 1.0 op_sel_hi:[1,0]
	v_pk_add_f32 v[156:157], v[156:157], 1.0 op_sel_hi:[1,0]
	v_pk_add_f32 v[158:159], v[158:159], 1.0 op_sel_hi:[1,0]
	v_div_scale_f32 v160, s[38:39], v152, v152, 1.0
	v_div_scale_f32 v161, s[38:39], v153, v153, 1.0
	v_div_scale_f32 v162, s[38:39], v154, v154, 1.0
	v_div_scale_f32 v163, s[38:39], v155, v155, 1.0
	v_rcp_f32_e32 v164, v160
	v_rcp_f32_e32 v165, v161
	v_rcp_f32_e32 v166, v162
	v_rcp_f32_e32 v167, v163
	v_pk_fma_f32 v[148:149], v[160:161], v[164:165], 1.0 op_sel_hi:[1,1,0] neg_lo:[1,0,0] neg_hi:[1,0,0]
	v_pk_fma_f32 v[150:151], v[162:163], v[166:167], 1.0 op_sel_hi:[1,1,0] neg_lo:[1,0,0] neg_hi:[1,0,0]
	v_pk_fma_f32 v[164:165], v[148:149], v[164:165], v[164:165]
	v_pk_fma_f32 v[166:167], v[150:151], v[166:167], v[166:167]
	v_div_scale_f32 v168, s[2:3], 1.0, v152, 1.0
	v_div_scale_f32 v169, s[26:27], 1.0, v153, 1.0
	v_div_scale_f32 v170, s[28:29], 1.0, v154, 1.0
	v_div_scale_f32 v171, vcc, 1.0, v155, 1.0
	v_pk_mul_f32 v[128:129], v[168:169], v[164:165]
	v_pk_mul_f32 v[130:131], v[170:171], v[166:167]
	v_pk_fma_f32 v[148:149], v[160:161], v[128:129], v[168:169] neg_lo:[1,0,0] neg_hi:[1,0,0]
	v_pk_fma_f32 v[150:151], v[162:163], v[130:131], v[170:171] neg_lo:[1,0,0] neg_hi:[1,0,0]
	v_pk_fma_f32 v[128:129], v[148:149], v[164:165], v[128:129]
	v_pk_fma_f32 v[130:131], v[150:151], v[166:167], v[130:131]
	v_pk_fma_f32 v[160:161], v[160:161], v[128:129], v[168:169] neg_lo:[1,0,0] neg_hi:[1,0,0]
	v_pk_fma_f32 v[162:163], v[162:163], v[130:131], v[170:171] neg_lo:[1,0,0] neg_hi:[1,0,0]
	v_div_fmas_f32 v163, v163, v167, v131
	s_mov_b64 vcc, s[28:29]
	v_div_fmas_f32 v162, v162, v166, v130
	s_mov_b64 vcc, s[26:27]
	v_div_fmas_f32 v161, v161, v165, v129
	s_mov_b64 vcc, s[2:3]
	v_div_fmas_f32 v160, v160, v164, v128
	v_div_fixup_f32 v152, v160, v152, 1.0
	v_div_fixup_f32 v153, v161, v153, 1.0
	v_div_fixup_f32 v154, v162, v154, 1.0
	v_div_fixup_f32 v155, v163, v155, 1.0
	v_div_scale_f32 v160, s[38:39], v156, v156, 1.0
	v_div_scale_f32 v161, s[38:39], v157, v157, 1.0
	v_div_scale_f32 v162, s[38:39], v158, v158, 1.0
	v_div_scale_f32 v163, s[38:39], v159, v159, 1.0
	v_rcp_f32_e32 v164, v160
	v_rcp_f32_e32 v165, v161
	v_rcp_f32_e32 v166, v162
	v_rcp_f32_e32 v167, v163
	v_pk_fma_f32 v[148:149], v[160:161], v[164:165], 1.0 op_sel_hi:[1,1,0] neg_lo:[1,0,0] neg_hi:[1,0,0]
	v_pk_fma_f32 v[150:151], v[162:163], v[166:167], 1.0 op_sel_hi:[1,1,0] neg_lo:[1,0,0] neg_hi:[1,0,0]
	v_pk_fma_f32 v[164:165], v[148:149], v[164:165], v[164:165]
	v_pk_fma_f32 v[166:167], v[150:151], v[166:167], v[166:167]
	v_div_scale_f32 v168, s[2:3], 1.0, v156, 1.0
	v_div_scale_f32 v169, s[26:27], 1.0, v157, 1.0
	v_div_scale_f32 v170, s[28:29], 1.0, v158, 1.0
	v_div_scale_f32 v171, vcc, 1.0, v159, 1.0
	v_pk_mul_f32 v[128:129], v[168:169], v[164:165]
	v_pk_mul_f32 v[130:131], v[170:171], v[166:167]
	v_pk_fma_f32 v[148:149], v[160:161], v[128:129], v[168:169] neg_lo:[1,0,0] neg_hi:[1,0,0]
	v_pk_fma_f32 v[150:151], v[162:163], v[130:131], v[170:171] neg_lo:[1,0,0] neg_hi:[1,0,0]
	v_pk_fma_f32 v[128:129], v[148:149], v[164:165], v[128:129]
	v_pk_fma_f32 v[130:131], v[150:151], v[166:167], v[130:131]
	v_pk_fma_f32 v[160:161], v[160:161], v[128:129], v[168:169] neg_lo:[1,0,0] neg_hi:[1,0,0]
	v_pk_fma_f32 v[162:163], v[162:163], v[130:131], v[170:171] neg_lo:[1,0,0] neg_hi:[1,0,0]
	v_div_fmas_f32 v163, v163, v167, v131
	s_mov_b64 vcc, s[28:29]
	v_div_fmas_f32 v162, v162, v166, v130
	s_mov_b64 vcc, s[26:27]
	v_div_fmas_f32 v161, v161, v165, v129
	s_mov_b64 vcc, s[2:3]
	v_div_fmas_f32 v160, v160, v164, v128
	v_div_fixup_f32 v156, v160, v156, 1.0
	v_div_fixup_f32 v157, v161, v157, 1.0
	v_div_fixup_f32 v158, v162, v158, 1.0
	v_div_fixup_f32 v159, v163, v159, 1.0
	v_lshlrev_b32_e32 v166, 16, v212
	v_and_b32_e32 v167, 0xffff0000, v212
	v_pk_fma_f32 v[152:153], v[108:109], v[152:153], v[166:167]
	v_lshlrev_b32_e32 v166, 16, v213
	v_and_b32_e32 v167, 0xffff0000, v213
	v_pk_fma_f32 v[154:155], v[110:111], v[154:155], v[166:167]
	v_lshlrev_b32_e32 v166, 16, v214
	v_and_b32_e32 v167, 0xffff0000, v214
	v_pk_fma_f32 v[156:157], v[104:105], v[156:157], v[166:167]
	v_lshlrev_b32_e32 v166, 16, v215
	v_and_b32_e32 v167, 0xffff0000, v215
	v_pk_fma_f32 v[158:159], v[106:107], v[158:159], v[166:167]
	v_cvt_pk_bf16_f32 v168, v152, v153
	v_cvt_pk_bf16_f32 v169, v154, v155
	v_cvt_pk_bf16_f32 v170, v156, v157
	v_cvt_pk_bf16_f32 v171, v158, v159
	global_store_dwordx4 v185, v[168:171], s[66:67]
	global_load_dwordx4 v[108:111], v179, s[64:65]
	global_load_dwordx4 v[104:107], v187, s[68:69]
	s_waitcnt vmcnt(9)
; __device__ __forceinline__ float sigmoidf_(float x) { return 1.f / (1.f + __expf(-x)); }
	v_lshlrev_b32_e32 v152, 16, v216
	v_and_b32_e32 v153, 0xffff0000, v216
	v_lshlrev_b32_e32 v154, 16, v217
	v_and_b32_e32 v155, 0xffff0000, v217
	v_lshlrev_b32_e32 v156, 16, v218
	v_and_b32_e32 v157, 0xffff0000, v218
	v_lshlrev_b32_e32 v158, 16, v219
	v_and_b32_e32 v159, 0xffff0000, v219
	v_mul_f32_e32 v152, 0xbfb8aa3b, v152
	v_mul_f32_e32 v153, 0xbfb8aa3b, v153
	v_mul_f32_e32 v154, 0xbfb8aa3b, v154
	v_mul_f32_e32 v155, 0xbfb8aa3b, v155
	v_mul_f32_e32 v156, 0xbfb8aa3b, v156
	v_mul_f32_e32 v157, 0xbfb8aa3b, v157
	v_mul_f32_e32 v158, 0xbfb8aa3b, v158
	v_mul_f32_e32 v159, 0xbfb8aa3b, v159
	v_exp_f32_e32 v152, v152
	v_exp_f32_e32 v153, v153
	v_exp_f32_e32 v154, v154
	v_exp_f32_e32 v155, v155
	v_exp_f32_e32 v156, v156
	v_exp_f32_e32 v157, v157
	v_exp_f32_e32 v158, v158
	v_exp_f32_e32 v159, v159
	v_pk_add_f32 v[152:153], v[152:153], 1.0 op_sel_hi:[1,0]
	v_pk_add_f32 v[154:155], v[154:155], 1.0 op_sel_hi:[1,0]
	v_pk_add_f32 v[156:157], v[156:157], 1.0 op_sel_hi:[1,0]
	v_pk_add_f32 v[158:159], v[158:159], 1.0 op_sel_hi:[1,0]
	v_div_scale_f32 v160, s[38:39], v152, v152, 1.0
	v_div_scale_f32 v161, s[38:39], v153, v153, 1.0
	v_div_scale_f32 v162, s[38:39], v154, v154, 1.0
	v_div_scale_f32 v163, s[38:39], v155, v155, 1.0
	v_rcp_f32_e32 v164, v160
	v_rcp_f32_e32 v165, v161
	v_rcp_f32_e32 v166, v162
	v_rcp_f32_e32 v167, v163
	v_pk_fma_f32 v[148:149], v[160:161], v[164:165], 1.0 op_sel_hi:[1,1,0] neg_lo:[1,0,0] neg_hi:[1,0,0]
	v_pk_fma_f32 v[150:151], v[162:163], v[166:167], 1.0 op_sel_hi:[1,1,0] neg_lo:[1,0,0] neg_hi:[1,0,0]
	v_pk_fma_f32 v[164:165], v[148:149], v[164:165], v[164:165]
	v_pk_fma_f32 v[166:167], v[150:151], v[166:167], v[166:167]
	v_div_scale_f32 v168, s[2:3], 1.0, v152, 1.0
	v_div_scale_f32 v169, s[26:27], 1.0, v153, 1.0
	v_div_scale_f32 v170, s[28:29], 1.0, v154, 1.0
	v_div_scale_f32 v171, vcc, 1.0, v155, 1.0
	v_pk_mul_f32 v[128:129], v[168:169], v[164:165]
	v_pk_mul_f32 v[130:131], v[170:171], v[166:167]
	v_pk_fma_f32 v[148:149], v[160:161], v[128:129], v[168:169] neg_lo:[1,0,0] neg_hi:[1,0,0]
	v_pk_fma_f32 v[150:151], v[162:163], v[130:131], v[170:171] neg_lo:[1,0,0] neg_hi:[1,0,0]
	v_pk_fma_f32 v[128:129], v[148:149], v[164:165], v[128:129]
	v_pk_fma_f32 v[130:131], v[150:151], v[166:167], v[130:131]
	v_pk_fma_f32 v[160:161], v[160:161], v[128:129], v[168:169] neg_lo:[1,0,0] neg_hi:[1,0,0]
	v_pk_fma_f32 v[162:163], v[162:163], v[130:131], v[170:171] neg_lo:[1,0,0] neg_hi:[1,0,0]
	v_div_fmas_f32 v163, v163, v167, v131
	s_mov_b64 vcc, s[28:29]
	v_div_fmas_f32 v162, v162, v166, v130
	s_mov_b64 vcc, s[26:27]
	v_div_fmas_f32 v161, v161, v165, v129
	s_mov_b64 vcc, s[2:3]
	v_div_fmas_f32 v160, v160, v164, v128
	v_div_fixup_f32 v152, v160, v152, 1.0
	v_div_fixup_f32 v153, v161, v153, 1.0
	v_div_fixup_f32 v154, v162, v154, 1.0
	v_div_fixup_f32 v155, v163, v155, 1.0
	v_div_scale_f32 v160, s[38:39], v156, v156, 1.0
	v_div_scale_f32 v161, s[38:39], v157, v157, 1.0
	v_div_scale_f32 v162, s[38:39], v158, v158, 1.0
	v_div_scale_f32 v163, s[38:39], v159, v159, 1.0
	v_rcp_f32_e32 v164, v160
	v_rcp_f32_e32 v165, v161
	v_rcp_f32_e32 v166, v162
	v_rcp_f32_e32 v167, v163
	v_pk_fma_f32 v[148:149], v[160:161], v[164:165], 1.0 op_sel_hi:[1,1,0] neg_lo:[1,0,0] neg_hi:[1,0,0]
	v_pk_fma_f32 v[150:151], v[162:163], v[166:167], 1.0 op_sel_hi:[1,1,0] neg_lo:[1,0,0] neg_hi:[1,0,0]
	v_pk_fma_f32 v[164:165], v[148:149], v[164:165], v[164:165]
	v_pk_fma_f32 v[166:167], v[150:151], v[166:167], v[166:167]
	v_div_scale_f32 v168, s[2:3], 1.0, v156, 1.0
	v_div_scale_f32 v169, s[26:27], 1.0, v157, 1.0
	v_div_scale_f32 v170, s[28:29], 1.0, v158, 1.0
	v_div_scale_f32 v171, vcc, 1.0, v159, 1.0
	v_pk_mul_f32 v[128:129], v[168:169], v[164:165]
	v_pk_mul_f32 v[130:131], v[170:171], v[166:167]
	v_pk_fma_f32 v[148:149], v[160:161], v[128:129], v[168:169] neg_lo:[1,0,0] neg_hi:[1,0,0]
	v_pk_fma_f32 v[150:151], v[162:163], v[130:131], v[170:171] neg_lo:[1,0,0] neg_hi:[1,0,0]
	v_pk_fma_f32 v[128:129], v[148:149], v[164:165], v[128:129]
	v_pk_fma_f32 v[130:131], v[150:151], v[166:167], v[130:131]
	v_pk_fma_f32 v[160:161], v[160:161], v[128:129], v[168:169] neg_lo:[1,0,0] neg_hi:[1,0,0]
	v_pk_fma_f32 v[162:163], v[162:163], v[130:131], v[170:171] neg_lo:[1,0,0] neg_hi:[1,0,0]
	v_div_fmas_f32 v163, v163, v167, v131
	s_mov_b64 vcc, s[28:29]
	v_div_fmas_f32 v162, v162, v166, v130
	s_mov_b64 vcc, s[26:27]
	v_div_fmas_f32 v161, v161, v165, v129
	s_mov_b64 vcc, s[2:3]
	v_div_fmas_f32 v160, v160, v164, v128
	v_div_fixup_f32 v156, v160, v156, 1.0
	v_div_fixup_f32 v157, v161, v157, 1.0
	v_div_fixup_f32 v158, v162, v158, 1.0
	v_div_fixup_f32 v159, v163, v159, 1.0
	v_lshlrev_b32_e32 v166, 16, v220
	v_and_b32_e32 v167, 0xffff0000, v220
	v_pk_fma_f32 v[152:153], v[100:101], v[152:153], v[166:167]
	v_lshlrev_b32_e32 v166, 16, v221
	v_and_b32_e32 v167, 0xffff0000, v221
	v_pk_fma_f32 v[154:155], v[102:103], v[154:155], v[166:167]
	v_lshlrev_b32_e32 v166, 16, v222
	v_and_b32_e32 v167, 0xffff0000, v222
	v_pk_fma_f32 v[156:157], v[96:97], v[156:157], v[166:167]
	v_lshlrev_b32_e32 v166, 16, v223
	v_and_b32_e32 v167, 0xffff0000, v223
	v_pk_fma_f32 v[158:159], v[98:99], v[158:159], v[166:167]
	v_cvt_pk_bf16_f32 v168, v152, v153
	v_cvt_pk_bf16_f32 v169, v154, v155
	v_cvt_pk_bf16_f32 v170, v156, v157
	v_cvt_pk_bf16_f32 v171, v158, v159
	global_store_dwordx4 v185, v[168:171], s[66:67] offset:256
	global_load_dwordx4 v[100:103], v179, s[64:65] offset:256
	global_load_dwordx4 v[96:99], v187, s[68:69] offset:256
	s_waitcnt vmcnt(9)
; __device__ __forceinline__ float sigmoidf_(float x) { return 1.f / (1.f + __expf(-x)); }
	v_lshlrev_b32_e32 v152, 16, v124
	v_and_b32_e32 v153, 0xffff0000, v124
	v_lshlrev_b32_e32 v154, 16, v125
	v_and_b32_e32 v155, 0xffff0000, v125
	v_lshlrev_b32_e32 v156, 16, v126
	v_and_b32_e32 v157, 0xffff0000, v126
	v_lshlrev_b32_e32 v158, 16, v127
	v_and_b32_e32 v159, 0xffff0000, v127
	v_mul_f32_e32 v152, 0xbfb8aa3b, v152
	v_mul_f32_e32 v153, 0xbfb8aa3b, v153
	v_mul_f32_e32 v154, 0xbfb8aa3b, v154
	v_mul_f32_e32 v155, 0xbfb8aa3b, v155
	v_mul_f32_e32 v156, 0xbfb8aa3b, v156
	v_mul_f32_e32 v157, 0xbfb8aa3b, v157
	v_mul_f32_e32 v158, 0xbfb8aa3b, v158
	v_mul_f32_e32 v159, 0xbfb8aa3b, v159
	v_exp_f32_e32 v152, v152
	v_exp_f32_e32 v153, v153
	v_exp_f32_e32 v154, v154
	v_exp_f32_e32 v155, v155
	v_exp_f32_e32 v156, v156
	v_exp_f32_e32 v157, v157
	v_exp_f32_e32 v158, v158
	v_exp_f32_e32 v159, v159
	v_pk_add_f32 v[152:153], v[152:153], 1.0 op_sel_hi:[1,0]
	v_pk_add_f32 v[154:155], v[154:155], 1.0 op_sel_hi:[1,0]
	v_pk_add_f32 v[156:157], v[156:157], 1.0 op_sel_hi:[1,0]
	v_pk_add_f32 v[158:159], v[158:159], 1.0 op_sel_hi:[1,0]
	v_div_scale_f32 v160, s[38:39], v152, v152, 1.0
	v_div_scale_f32 v161, s[38:39], v153, v153, 1.0
	v_div_scale_f32 v162, s[38:39], v154, v154, 1.0
	v_div_scale_f32 v163, s[38:39], v155, v155, 1.0
	v_rcp_f32_e32 v164, v160
	v_rcp_f32_e32 v165, v161
	v_rcp_f32_e32 v166, v162
	v_rcp_f32_e32 v167, v163
	v_pk_fma_f32 v[148:149], v[160:161], v[164:165], 1.0 op_sel_hi:[1,1,0] neg_lo:[1,0,0] neg_hi:[1,0,0]
	v_pk_fma_f32 v[150:151], v[162:163], v[166:167], 1.0 op_sel_hi:[1,1,0] neg_lo:[1,0,0] neg_hi:[1,0,0]
	v_pk_fma_f32 v[164:165], v[148:149], v[164:165], v[164:165]
	v_pk_fma_f32 v[166:167], v[150:151], v[166:167], v[166:167]
	v_div_scale_f32 v168, s[2:3], 1.0, v152, 1.0
	v_div_scale_f32 v169, s[26:27], 1.0, v153, 1.0
	v_div_scale_f32 v170, s[28:29], 1.0, v154, 1.0
	v_div_scale_f32 v171, vcc, 1.0, v155, 1.0
	v_pk_mul_f32 v[128:129], v[168:169], v[164:165]
	v_pk_mul_f32 v[130:131], v[170:171], v[166:167]
	v_pk_fma_f32 v[148:149], v[160:161], v[128:129], v[168:169] neg_lo:[1,0,0] neg_hi:[1,0,0]
	v_pk_fma_f32 v[150:151], v[162:163], v[130:131], v[170:171] neg_lo:[1,0,0] neg_hi:[1,0,0]
	v_pk_fma_f32 v[128:129], v[148:149], v[164:165], v[128:129]
	v_pk_fma_f32 v[130:131], v[150:151], v[166:167], v[130:131]
	v_pk_fma_f32 v[160:161], v[160:161], v[128:129], v[168:169] neg_lo:[1,0,0] neg_hi:[1,0,0]
	v_pk_fma_f32 v[162:163], v[162:163], v[130:131], v[170:171] neg_lo:[1,0,0] neg_hi:[1,0,0]
	v_div_fmas_f32 v163, v163, v167, v131
	s_mov_b64 vcc, s[28:29]
	v_div_fmas_f32 v162, v162, v166, v130
	s_mov_b64 vcc, s[26:27]
	v_div_fmas_f32 v161, v161, v165, v129
	s_mov_b64 vcc, s[2:3]
	v_div_fmas_f32 v160, v160, v164, v128
	v_div_fixup_f32 v152, v160, v152, 1.0
	v_div_fixup_f32 v153, v161, v153, 1.0
	v_div_fixup_f32 v154, v162, v154, 1.0
	v_div_fixup_f32 v155, v163, v155, 1.0
	v_div_scale_f32 v160, s[38:39], v156, v156, 1.0
	v_div_scale_f32 v161, s[38:39], v157, v157, 1.0
	v_div_scale_f32 v162, s[38:39], v158, v158, 1.0
	v_div_scale_f32 v163, s[38:39], v159, v159, 1.0
	v_rcp_f32_e32 v164, v160
	v_rcp_f32_e32 v165, v161
	v_rcp_f32_e32 v166, v162
	v_rcp_f32_e32 v167, v163
	v_pk_fma_f32 v[148:149], v[160:161], v[164:165], 1.0 op_sel_hi:[1,1,0] neg_lo:[1,0,0] neg_hi:[1,0,0]
	v_pk_fma_f32 v[150:151], v[162:163], v[166:167], 1.0 op_sel_hi:[1,1,0] neg_lo:[1,0,0] neg_hi:[1,0,0]
	v_pk_fma_f32 v[164:165], v[148:149], v[164:165], v[164:165]
	v_pk_fma_f32 v[166:167], v[150:151], v[166:167], v[166:167]
	v_div_scale_f32 v168, s[2:3], 1.0, v156, 1.0
	v_div_scale_f32 v169, s[26:27], 1.0, v157, 1.0
	v_div_scale_f32 v170, s[28:29], 1.0, v158, 1.0
	v_div_scale_f32 v171, vcc, 1.0, v159, 1.0
	v_pk_mul_f32 v[128:129], v[168:169], v[164:165]
	v_pk_mul_f32 v[130:131], v[170:171], v[166:167]
	v_pk_fma_f32 v[148:149], v[160:161], v[128:129], v[168:169] neg_lo:[1,0,0] neg_hi:[1,0,0]
	v_pk_fma_f32 v[150:151], v[162:163], v[130:131], v[170:171] neg_lo:[1,0,0] neg_hi:[1,0,0]
	v_pk_fma_f32 v[128:129], v[148:149], v[164:165], v[128:129]
	v_pk_fma_f32 v[130:131], v[150:151], v[166:167], v[130:131]
	v_pk_fma_f32 v[160:161], v[160:161], v[128:129], v[168:169] neg_lo:[1,0,0] neg_hi:[1,0,0]
	v_pk_fma_f32 v[162:163], v[162:163], v[130:131], v[170:171] neg_lo:[1,0,0] neg_hi:[1,0,0]
	v_div_fmas_f32 v163, v163, v167, v131
	s_mov_b64 vcc, s[28:29]
	v_div_fmas_f32 v162, v162, v166, v130
	s_mov_b64 vcc, s[26:27]
	v_div_fmas_f32 v161, v161, v165, v129
	s_mov_b64 vcc, s[2:3]
	v_div_fmas_f32 v160, v160, v164, v128
	v_div_fixup_f32 v156, v160, v156, 1.0
	v_div_fixup_f32 v157, v161, v157, 1.0
	v_div_fixup_f32 v158, v162, v158, 1.0
	v_div_fixup_f32 v159, v163, v159, 1.0
	v_lshlrev_b32_e32 v166, 16, v120
	v_and_b32_e32 v167, 0xffff0000, v120
	v_pk_fma_f32 v[152:153], v[92:93], v[152:153], v[166:167]
	v_lshlrev_b32_e32 v166, 16, v121
	v_and_b32_e32 v167, 0xffff0000, v121
	v_pk_fma_f32 v[154:155], v[94:95], v[154:155], v[166:167]
	v_lshlrev_b32_e32 v166, 16, v122
	v_and_b32_e32 v167, 0xffff0000, v122
	v_pk_fma_f32 v[156:157], v[88:89], v[156:157], v[166:167]
	v_lshlrev_b32_e32 v166, 16, v123
	v_and_b32_e32 v167, 0xffff0000, v123
	v_pk_fma_f32 v[158:159], v[90:91], v[158:159], v[166:167]
	v_cvt_pk_bf16_f32 v168, v152, v153
	v_cvt_pk_bf16_f32 v169, v154, v155
	v_cvt_pk_bf16_f32 v170, v156, v157
	v_cvt_pk_bf16_f32 v171, v158, v159
	global_store_dwordx4 v186, v[168:171], s[66:67]
	global_load_dwordx4 v[92:95], v180, s[64:65]
	global_load_dwordx4 v[88:91], v188, s[68:69]
	s_waitcnt vmcnt(9)
; __device__ __forceinline__ float sigmoidf_(float x) { return 1.f / (1.f + __expf(-x)); }
	v_lshlrev_b32_e32 v152, 16, v116
	v_and_b32_e32 v153, 0xffff0000, v116
	v_lshlrev_b32_e32 v154, 16, v117
	v_and_b32_e32 v155, 0xffff0000, v117
	v_lshlrev_b32_e32 v156, 16, v118
	v_and_b32_e32 v157, 0xffff0000, v118
	v_lshlrev_b32_e32 v158, 16, v119
	v_and_b32_e32 v159, 0xffff0000, v119
	v_mul_f32_e32 v152, 0xbfb8aa3b, v152
	v_mul_f32_e32 v153, 0xbfb8aa3b, v153
	v_mul_f32_e32 v154, 0xbfb8aa3b, v154
	v_mul_f32_e32 v155, 0xbfb8aa3b, v155
	v_mul_f32_e32 v156, 0xbfb8aa3b, v156
	v_mul_f32_e32 v157, 0xbfb8aa3b, v157
	v_mul_f32_e32 v158, 0xbfb8aa3b, v158
	v_mul_f32_e32 v159, 0xbfb8aa3b, v159
	v_exp_f32_e32 v152, v152
	v_exp_f32_e32 v153, v153
	v_exp_f32_e32 v154, v154
	v_exp_f32_e32 v155, v155
	v_exp_f32_e32 v156, v156
	v_exp_f32_e32 v157, v157
	v_exp_f32_e32 v158, v158
	v_exp_f32_e32 v159, v159
	v_pk_add_f32 v[152:153], v[152:153], 1.0 op_sel_hi:[1,0]
	v_pk_add_f32 v[154:155], v[154:155], 1.0 op_sel_hi:[1,0]
	v_pk_add_f32 v[156:157], v[156:157], 1.0 op_sel_hi:[1,0]
	v_pk_add_f32 v[158:159], v[158:159], 1.0 op_sel_hi:[1,0]
	v_div_scale_f32 v160, s[38:39], v152, v152, 1.0
	v_div_scale_f32 v161, s[38:39], v153, v153, 1.0
	v_div_scale_f32 v162, s[38:39], v154, v154, 1.0
	v_div_scale_f32 v163, s[38:39], v155, v155, 1.0
	v_rcp_f32_e32 v164, v160
	v_rcp_f32_e32 v165, v161
	v_rcp_f32_e32 v166, v162
	v_rcp_f32_e32 v167, v163
	v_pk_fma_f32 v[148:149], v[160:161], v[164:165], 1.0 op_sel_hi:[1,1,0] neg_lo:[1,0,0] neg_hi:[1,0,0]
	v_pk_fma_f32 v[150:151], v[162:163], v[166:167], 1.0 op_sel_hi:[1,1,0] neg_lo:[1,0,0] neg_hi:[1,0,0]
	v_pk_fma_f32 v[164:165], v[148:149], v[164:165], v[164:165]
	v_pk_fma_f32 v[166:167], v[150:151], v[166:167], v[166:167]
	v_div_scale_f32 v168, s[2:3], 1.0, v152, 1.0
	v_div_scale_f32 v169, s[26:27], 1.0, v153, 1.0
	v_div_scale_f32 v170, s[28:29], 1.0, v154, 1.0
	v_div_scale_f32 v171, vcc, 1.0, v155, 1.0
	v_pk_mul_f32 v[128:129], v[168:169], v[164:165]
	v_pk_mul_f32 v[130:131], v[170:171], v[166:167]
	v_pk_fma_f32 v[148:149], v[160:161], v[128:129], v[168:169] neg_lo:[1,0,0] neg_hi:[1,0,0]
	v_pk_fma_f32 v[150:151], v[162:163], v[130:131], v[170:171] neg_lo:[1,0,0] neg_hi:[1,0,0]
	v_pk_fma_f32 v[128:129], v[148:149], v[164:165], v[128:129]
	v_pk_fma_f32 v[130:131], v[150:151], v[166:167], v[130:131]
	v_pk_fma_f32 v[160:161], v[160:161], v[128:129], v[168:169] neg_lo:[1,0,0] neg_hi:[1,0,0]
	v_pk_fma_f32 v[162:163], v[162:163], v[130:131], v[170:171] neg_lo:[1,0,0] neg_hi:[1,0,0]
	v_div_fmas_f32 v163, v163, v167, v131
	s_mov_b64 vcc, s[28:29]
	v_div_fmas_f32 v162, v162, v166, v130
	s_mov_b64 vcc, s[26:27]
	v_div_fmas_f32 v161, v161, v165, v129
	s_mov_b64 vcc, s[2:3]
	v_div_fmas_f32 v160, v160, v164, v128
	v_div_fixup_f32 v152, v160, v152, 1.0
	v_div_fixup_f32 v153, v161, v153, 1.0
	v_div_fixup_f32 v154, v162, v154, 1.0
	v_div_fixup_f32 v155, v163, v155, 1.0
	v_div_scale_f32 v160, s[38:39], v156, v156, 1.0
	v_div_scale_f32 v161, s[38:39], v157, v157, 1.0
	v_div_scale_f32 v162, s[38:39], v158, v158, 1.0
	v_div_scale_f32 v163, s[38:39], v159, v159, 1.0
	v_rcp_f32_e32 v164, v160
	v_rcp_f32_e32 v165, v161
	v_rcp_f32_e32 v166, v162
	v_rcp_f32_e32 v167, v163
	v_pk_fma_f32 v[148:149], v[160:161], v[164:165], 1.0 op_sel_hi:[1,1,0] neg_lo:[1,0,0] neg_hi:[1,0,0]
	v_pk_fma_f32 v[150:151], v[162:163], v[166:167], 1.0 op_sel_hi:[1,1,0] neg_lo:[1,0,0] neg_hi:[1,0,0]
	v_pk_fma_f32 v[164:165], v[148:149], v[164:165], v[164:165]
	v_pk_fma_f32 v[166:167], v[150:151], v[166:167], v[166:167]
	v_div_scale_f32 v168, s[2:3], 1.0, v156, 1.0
	v_div_scale_f32 v169, s[26:27], 1.0, v157, 1.0
	v_div_scale_f32 v170, s[28:29], 1.0, v158, 1.0
	v_div_scale_f32 v171, vcc, 1.0, v159, 1.0
	v_pk_mul_f32 v[128:129], v[168:169], v[164:165]
	v_pk_mul_f32 v[130:131], v[170:171], v[166:167]
	v_pk_fma_f32 v[148:149], v[160:161], v[128:129], v[168:169] neg_lo:[1,0,0] neg_hi:[1,0,0]
	v_pk_fma_f32 v[150:151], v[162:163], v[130:131], v[170:171] neg_lo:[1,0,0] neg_hi:[1,0,0]
	v_pk_fma_f32 v[128:129], v[148:149], v[164:165], v[128:129]
	v_pk_fma_f32 v[130:131], v[150:151], v[166:167], v[130:131]
	v_pk_fma_f32 v[160:161], v[160:161], v[128:129], v[168:169] neg_lo:[1,0,0] neg_hi:[1,0,0]
	v_pk_fma_f32 v[162:163], v[162:163], v[130:131], v[170:171] neg_lo:[1,0,0] neg_hi:[1,0,0]
	v_div_fmas_f32 v163, v163, v167, v131
	s_mov_b64 vcc, s[28:29]
	v_div_fmas_f32 v162, v162, v166, v130
	s_mov_b64 vcc, s[26:27]
	v_div_fmas_f32 v161, v161, v165, v129
	s_mov_b64 vcc, s[2:3]
	v_div_fmas_f32 v160, v160, v164, v128
	v_div_fixup_f32 v156, v160, v156, 1.0
	v_div_fixup_f32 v157, v161, v157, 1.0
	v_div_fixup_f32 v158, v162, v158, 1.0
	v_div_fixup_f32 v159, v163, v159, 1.0
	v_lshlrev_b32_e32 v166, 16, v112
	v_and_b32_e32 v167, 0xffff0000, v112
	v_pk_fma_f32 v[152:153], v[84:85], v[152:153], v[166:167]
	v_lshlrev_b32_e32 v166, 16, v113
	v_and_b32_e32 v167, 0xffff0000, v113
	v_pk_fma_f32 v[154:155], v[86:87], v[154:155], v[166:167]
	v_lshlrev_b32_e32 v166, 16, v114
	v_and_b32_e32 v167, 0xffff0000, v114
	v_pk_fma_f32 v[156:157], v[80:81], v[156:157], v[166:167]
	v_lshlrev_b32_e32 v166, 16, v115
	v_and_b32_e32 v167, 0xffff0000, v115
	v_pk_fma_f32 v[158:159], v[82:83], v[158:159], v[166:167]
	v_cvt_pk_bf16_f32 v168, v152, v153
	v_cvt_pk_bf16_f32 v169, v154, v155
	v_cvt_pk_bf16_f32 v170, v156, v157
	v_cvt_pk_bf16_f32 v171, v158, v159
	global_store_dwordx4 v186, v[168:171], s[66:67] offset:256
	global_load_dwordx4 v[84:87], v180, s[64:65] offset:256
	global_load_dwordx4 v[80:83], v188, s[68:69] offset:256
	s_waitcnt vmcnt(9)
; __device__ __forceinline__ float sigmoidf_(float x) { return 1.f / (1.f + __expf(-x)); }
	v_lshlrev_b32_e32 v152, 16, v108
	v_and_b32_e32 v153, 0xffff0000, v108
	v_lshlrev_b32_e32 v154, 16, v109
	v_and_b32_e32 v155, 0xffff0000, v109
	v_lshlrev_b32_e32 v156, 16, v110
	v_and_b32_e32 v157, 0xffff0000, v110
	v_lshlrev_b32_e32 v158, 16, v111
	v_and_b32_e32 v159, 0xffff0000, v111
	v_mul_f32_e32 v152, 0xbfb8aa3b, v152
	v_mul_f32_e32 v153, 0xbfb8aa3b, v153
	v_mul_f32_e32 v154, 0xbfb8aa3b, v154
	v_mul_f32_e32 v155, 0xbfb8aa3b, v155
	v_mul_f32_e32 v156, 0xbfb8aa3b, v156
	v_mul_f32_e32 v157, 0xbfb8aa3b, v157
	v_mul_f32_e32 v158, 0xbfb8aa3b, v158
	v_mul_f32_e32 v159, 0xbfb8aa3b, v159
	v_exp_f32_e32 v152, v152
	v_exp_f32_e32 v153, v153
	v_exp_f32_e32 v154, v154
	v_exp_f32_e32 v155, v155
	v_exp_f32_e32 v156, v156
	v_exp_f32_e32 v157, v157
	v_exp_f32_e32 v158, v158
	v_exp_f32_e32 v159, v159
	v_pk_add_f32 v[152:153], v[152:153], 1.0 op_sel_hi:[1,0]
	v_pk_add_f32 v[154:155], v[154:155], 1.0 op_sel_hi:[1,0]
	v_pk_add_f32 v[156:157], v[156:157], 1.0 op_sel_hi:[1,0]
	v_pk_add_f32 v[158:159], v[158:159], 1.0 op_sel_hi:[1,0]
	v_div_scale_f32 v160, s[38:39], v152, v152, 1.0
	v_div_scale_f32 v161, s[38:39], v153, v153, 1.0
	v_div_scale_f32 v162, s[38:39], v154, v154, 1.0
	v_div_scale_f32 v163, s[38:39], v155, v155, 1.0
	v_rcp_f32_e32 v164, v160
	v_rcp_f32_e32 v165, v161
	v_rcp_f32_e32 v166, v162
	v_rcp_f32_e32 v167, v163
	v_pk_fma_f32 v[148:149], v[160:161], v[164:165], 1.0 op_sel_hi:[1,1,0] neg_lo:[1,0,0] neg_hi:[1,0,0]
	v_pk_fma_f32 v[150:151], v[162:163], v[166:167], 1.0 op_sel_hi:[1,1,0] neg_lo:[1,0,0] neg_hi:[1,0,0]
	v_pk_fma_f32 v[164:165], v[148:149], v[164:165], v[164:165]
	v_pk_fma_f32 v[166:167], v[150:151], v[166:167], v[166:167]
	v_div_scale_f32 v168, s[2:3], 1.0, v152, 1.0
	v_div_scale_f32 v169, s[26:27], 1.0, v153, 1.0
	v_div_scale_f32 v170, s[28:29], 1.0, v154, 1.0
	v_div_scale_f32 v171, vcc, 1.0, v155, 1.0
	v_pk_mul_f32 v[128:129], v[168:169], v[164:165]
	v_pk_mul_f32 v[130:131], v[170:171], v[166:167]
	v_pk_fma_f32 v[148:149], v[160:161], v[128:129], v[168:169] neg_lo:[1,0,0] neg_hi:[1,0,0]
	v_pk_fma_f32 v[150:151], v[162:163], v[130:131], v[170:171] neg_lo:[1,0,0] neg_hi:[1,0,0]
	v_pk_fma_f32 v[128:129], v[148:149], v[164:165], v[128:129]
	v_pk_fma_f32 v[130:131], v[150:151], v[166:167], v[130:131]
	v_pk_fma_f32 v[160:161], v[160:161], v[128:129], v[168:169] neg_lo:[1,0,0] neg_hi:[1,0,0]
	v_pk_fma_f32 v[162:163], v[162:163], v[130:131], v[170:171] neg_lo:[1,0,0] neg_hi:[1,0,0]
	v_div_fmas_f32 v163, v163, v167, v131
	s_mov_b64 vcc, s[28:29]
	v_div_fmas_f32 v162, v162, v166, v130
	s_mov_b64 vcc, s[26:27]
	v_div_fmas_f32 v161, v161, v165, v129
	s_mov_b64 vcc, s[2:3]
	v_div_fmas_f32 v160, v160, v164, v128
	v_div_fixup_f32 v152, v160, v152, 1.0
	v_div_fixup_f32 v153, v161, v153, 1.0
	v_div_fixup_f32 v154, v162, v154, 1.0
	v_div_fixup_f32 v155, v163, v155, 1.0
	v_div_scale_f32 v160, s[38:39], v156, v156, 1.0
	v_div_scale_f32 v161, s[38:39], v157, v157, 1.0
	v_div_scale_f32 v162, s[38:39], v158, v158, 1.0
	v_div_scale_f32 v163, s[38:39], v159, v159, 1.0
	v_rcp_f32_e32 v164, v160
	v_rcp_f32_e32 v165, v161
	v_rcp_f32_e32 v166, v162
	v_rcp_f32_e32 v167, v163
	v_pk_fma_f32 v[148:149], v[160:161], v[164:165], 1.0 op_sel_hi:[1,1,0] neg_lo:[1,0,0] neg_hi:[1,0,0]
	v_pk_fma_f32 v[150:151], v[162:163], v[166:167], 1.0 op_sel_hi:[1,1,0] neg_lo:[1,0,0] neg_hi:[1,0,0]
	v_pk_fma_f32 v[164:165], v[148:149], v[164:165], v[164:165]
	v_pk_fma_f32 v[166:167], v[150:151], v[166:167], v[166:167]
	v_div_scale_f32 v168, s[2:3], 1.0, v156, 1.0
	v_div_scale_f32 v169, s[26:27], 1.0, v157, 1.0
	v_div_scale_f32 v170, s[28:29], 1.0, v158, 1.0
	v_div_scale_f32 v171, vcc, 1.0, v159, 1.0
	v_pk_mul_f32 v[128:129], v[168:169], v[164:165]
	v_pk_mul_f32 v[130:131], v[170:171], v[166:167]
	v_pk_fma_f32 v[148:149], v[160:161], v[128:129], v[168:169] neg_lo:[1,0,0] neg_hi:[1,0,0]
	v_pk_fma_f32 v[150:151], v[162:163], v[130:131], v[170:171] neg_lo:[1,0,0] neg_hi:[1,0,0]
	v_pk_fma_f32 v[128:129], v[148:149], v[164:165], v[128:129]
	v_pk_fma_f32 v[130:131], v[150:151], v[166:167], v[130:131]
	v_pk_fma_f32 v[160:161], v[160:161], v[128:129], v[168:169] neg_lo:[1,0,0] neg_hi:[1,0,0]
	v_pk_fma_f32 v[162:163], v[162:163], v[130:131], v[170:171] neg_lo:[1,0,0] neg_hi:[1,0,0]
	v_div_fmas_f32 v163, v163, v167, v131
	s_mov_b64 vcc, s[28:29]
	v_div_fmas_f32 v162, v162, v166, v130
	s_mov_b64 vcc, s[26:27]
	v_div_fmas_f32 v161, v161, v165, v129
	s_mov_b64 vcc, s[2:3]
	v_div_fmas_f32 v160, v160, v164, v128
	v_div_fixup_f32 v156, v160, v156, 1.0
	v_div_fixup_f32 v157, v161, v157, 1.0
	v_div_fixup_f32 v158, v162, v158, 1.0
	v_div_fixup_f32 v159, v163, v159, 1.0
	v_lshlrev_b32_e32 v166, 16, v104
	v_and_b32_e32 v167, 0xffff0000, v104
	v_pk_fma_f32 v[152:153], v[76:77], v[152:153], v[166:167]
	v_lshlrev_b32_e32 v166, 16, v105
	v_and_b32_e32 v167, 0xffff0000, v105
	v_pk_fma_f32 v[154:155], v[78:79], v[154:155], v[166:167]
	v_lshlrev_b32_e32 v166, 16, v106
	v_and_b32_e32 v167, 0xffff0000, v106
	v_pk_fma_f32 v[156:157], v[72:73], v[156:157], v[166:167]
	v_lshlrev_b32_e32 v166, 16, v107
	v_and_b32_e32 v167, 0xffff0000, v107
	v_pk_fma_f32 v[158:159], v[74:75], v[158:159], v[166:167]
	v_cvt_pk_bf16_f32 v168, v152, v153
	v_cvt_pk_bf16_f32 v169, v154, v155
	v_cvt_pk_bf16_f32 v170, v156, v157
	v_cvt_pk_bf16_f32 v171, v158, v159
	global_store_dwordx4 v187, v[168:171], s[66:67]
	global_load_dwordx4 v[76:79], v181, s[64:65]
	global_load_dwordx4 v[72:75], v189, s[68:69]
	s_waitcnt vmcnt(9)
; __device__ __forceinline__ float sigmoidf_(float x) { return 1.f / (1.f + __expf(-x)); }
	v_lshlrev_b32_e32 v152, 16, v100
	v_and_b32_e32 v153, 0xffff0000, v100
	v_lshlrev_b32_e32 v154, 16, v101
	v_and_b32_e32 v155, 0xffff0000, v101
	v_lshlrev_b32_e32 v156, 16, v102
	v_and_b32_e32 v157, 0xffff0000, v102
	v_lshlrev_b32_e32 v158, 16, v103
	v_and_b32_e32 v159, 0xffff0000, v103
	v_mul_f32_e32 v152, 0xbfb8aa3b, v152
	v_mul_f32_e32 v153, 0xbfb8aa3b, v153
	v_mul_f32_e32 v154, 0xbfb8aa3b, v154
	v_mul_f32_e32 v155, 0xbfb8aa3b, v155
	v_mul_f32_e32 v156, 0xbfb8aa3b, v156
	v_mul_f32_e32 v157, 0xbfb8aa3b, v157
	v_mul_f32_e32 v158, 0xbfb8aa3b, v158
	v_mul_f32_e32 v159, 0xbfb8aa3b, v159
	v_exp_f32_e32 v152, v152
	v_exp_f32_e32 v153, v153
	v_exp_f32_e32 v154, v154
	v_exp_f32_e32 v155, v155
	v_exp_f32_e32 v156, v156
	v_exp_f32_e32 v157, v157
	v_exp_f32_e32 v158, v158
	v_exp_f32_e32 v159, v159
	v_pk_add_f32 v[152:153], v[152:153], 1.0 op_sel_hi:[1,0]
	v_pk_add_f32 v[154:155], v[154:155], 1.0 op_sel_hi:[1,0]
	v_pk_add_f32 v[156:157], v[156:157], 1.0 op_sel_hi:[1,0]
	v_pk_add_f32 v[158:159], v[158:159], 1.0 op_sel_hi:[1,0]
	v_div_scale_f32 v160, s[38:39], v152, v152, 1.0
	v_div_scale_f32 v161, s[38:39], v153, v153, 1.0
	v_div_scale_f32 v162, s[38:39], v154, v154, 1.0
	v_div_scale_f32 v163, s[38:39], v155, v155, 1.0
	v_rcp_f32_e32 v164, v160
	v_rcp_f32_e32 v165, v161
	v_rcp_f32_e32 v166, v162
	v_rcp_f32_e32 v167, v163
	v_pk_fma_f32 v[148:149], v[160:161], v[164:165], 1.0 op_sel_hi:[1,1,0] neg_lo:[1,0,0] neg_hi:[1,0,0]
	v_pk_fma_f32 v[150:151], v[162:163], v[166:167], 1.0 op_sel_hi:[1,1,0] neg_lo:[1,0,0] neg_hi:[1,0,0]
	v_pk_fma_f32 v[164:165], v[148:149], v[164:165], v[164:165]
	v_pk_fma_f32 v[166:167], v[150:151], v[166:167], v[166:167]
	v_div_scale_f32 v168, s[2:3], 1.0, v152, 1.0
	v_div_scale_f32 v169, s[26:27], 1.0, v153, 1.0
	v_div_scale_f32 v170, s[28:29], 1.0, v154, 1.0
	v_div_scale_f32 v171, vcc, 1.0, v155, 1.0
	v_pk_mul_f32 v[128:129], v[168:169], v[164:165]
	v_pk_mul_f32 v[130:131], v[170:171], v[166:167]
	v_pk_fma_f32 v[148:149], v[160:161], v[128:129], v[168:169] neg_lo:[1,0,0] neg_hi:[1,0,0]
	v_pk_fma_f32 v[150:151], v[162:163], v[130:131], v[170:171] neg_lo:[1,0,0] neg_hi:[1,0,0]
	v_pk_fma_f32 v[128:129], v[148:149], v[164:165], v[128:129]
	v_pk_fma_f32 v[130:131], v[150:151], v[166:167], v[130:131]
	v_pk_fma_f32 v[160:161], v[160:161], v[128:129], v[168:169] neg_lo:[1,0,0] neg_hi:[1,0,0]
	v_pk_fma_f32 v[162:163], v[162:163], v[130:131], v[170:171] neg_lo:[1,0,0] neg_hi:[1,0,0]
	v_div_fmas_f32 v163, v163, v167, v131
	s_mov_b64 vcc, s[28:29]
	v_div_fmas_f32 v162, v162, v166, v130
	s_mov_b64 vcc, s[26:27]
	v_div_fmas_f32 v161, v161, v165, v129
	s_mov_b64 vcc, s[2:3]
	v_div_fmas_f32 v160, v160, v164, v128
	v_div_fixup_f32 v152, v160, v152, 1.0
	v_div_fixup_f32 v153, v161, v153, 1.0
	v_div_fixup_f32 v154, v162, v154, 1.0
	v_div_fixup_f32 v155, v163, v155, 1.0
	v_div_scale_f32 v160, s[38:39], v156, v156, 1.0
	v_div_scale_f32 v161, s[38:39], v157, v157, 1.0
	v_div_scale_f32 v162, s[38:39], v158, v158, 1.0
	v_div_scale_f32 v163, s[38:39], v159, v159, 1.0
	v_rcp_f32_e32 v164, v160
	v_rcp_f32_e32 v165, v161
	v_rcp_f32_e32 v166, v162
	v_rcp_f32_e32 v167, v163
	v_pk_fma_f32 v[148:149], v[160:161], v[164:165], 1.0 op_sel_hi:[1,1,0] neg_lo:[1,0,0] neg_hi:[1,0,0]
	v_pk_fma_f32 v[150:151], v[162:163], v[166:167], 1.0 op_sel_hi:[1,1,0] neg_lo:[1,0,0] neg_hi:[1,0,0]
	v_pk_fma_f32 v[164:165], v[148:149], v[164:165], v[164:165]
	v_pk_fma_f32 v[166:167], v[150:151], v[166:167], v[166:167]
	v_div_scale_f32 v168, s[2:3], 1.0, v156, 1.0
	v_div_scale_f32 v169, s[26:27], 1.0, v157, 1.0
	v_div_scale_f32 v170, s[28:29], 1.0, v158, 1.0
	v_div_scale_f32 v171, vcc, 1.0, v159, 1.0
	v_pk_mul_f32 v[128:129], v[168:169], v[164:165]
	v_pk_mul_f32 v[130:131], v[170:171], v[166:167]
	v_pk_fma_f32 v[148:149], v[160:161], v[128:129], v[168:169] neg_lo:[1,0,0] neg_hi:[1,0,0]
	v_pk_fma_f32 v[150:151], v[162:163], v[130:131], v[170:171] neg_lo:[1,0,0] neg_hi:[1,0,0]
	v_pk_fma_f32 v[128:129], v[148:149], v[164:165], v[128:129]
	v_pk_fma_f32 v[130:131], v[150:151], v[166:167], v[130:131]
	v_pk_fma_f32 v[160:161], v[160:161], v[128:129], v[168:169] neg_lo:[1,0,0] neg_hi:[1,0,0]
	v_pk_fma_f32 v[162:163], v[162:163], v[130:131], v[170:171] neg_lo:[1,0,0] neg_hi:[1,0,0]
	v_div_fmas_f32 v163, v163, v167, v131
	s_mov_b64 vcc, s[28:29]
	v_div_fmas_f32 v162, v162, v166, v130
	s_mov_b64 vcc, s[26:27]
	v_div_fmas_f32 v161, v161, v165, v129
	s_mov_b64 vcc, s[2:3]
	v_div_fmas_f32 v160, v160, v164, v128
	v_div_fixup_f32 v156, v160, v156, 1.0
	v_div_fixup_f32 v157, v161, v157, 1.0
	v_div_fixup_f32 v158, v162, v158, 1.0
	v_div_fixup_f32 v159, v163, v159, 1.0
	v_lshlrev_b32_e32 v166, 16, v96
	v_and_b32_e32 v167, 0xffff0000, v96
	v_pk_fma_f32 v[152:153], v[68:69], v[152:153], v[166:167]
	v_lshlrev_b32_e32 v166, 16, v97
	v_and_b32_e32 v167, 0xffff0000, v97
	v_pk_fma_f32 v[154:155], v[70:71], v[154:155], v[166:167]
	v_lshlrev_b32_e32 v166, 16, v98
	v_and_b32_e32 v167, 0xffff0000, v98
	v_pk_fma_f32 v[156:157], v[64:65], v[156:157], v[166:167]
	v_lshlrev_b32_e32 v166, 16, v99
	v_and_b32_e32 v167, 0xffff0000, v99
	v_pk_fma_f32 v[158:159], v[66:67], v[158:159], v[166:167]
	v_cvt_pk_bf16_f32 v168, v152, v153
	v_cvt_pk_bf16_f32 v169, v154, v155
	v_cvt_pk_bf16_f32 v170, v156, v157
	v_cvt_pk_bf16_f32 v171, v158, v159
	global_store_dwordx4 v187, v[168:171], s[66:67] offset:256
	global_load_dwordx4 v[68:71], v181, s[64:65] offset:256
	global_load_dwordx4 v[64:67], v189, s[68:69] offset:256
	s_waitcnt vmcnt(9)
; __device__ __forceinline__ float sigmoidf_(float x) { return 1.f / (1.f + __expf(-x)); }
	v_lshlrev_b32_e32 v152, 16, v92
	v_and_b32_e32 v153, 0xffff0000, v92
	v_lshlrev_b32_e32 v154, 16, v93
	v_and_b32_e32 v155, 0xffff0000, v93
	v_lshlrev_b32_e32 v156, 16, v94
	v_and_b32_e32 v157, 0xffff0000, v94
	v_lshlrev_b32_e32 v158, 16, v95
	v_and_b32_e32 v159, 0xffff0000, v95
	v_mul_f32_e32 v152, 0xbfb8aa3b, v152
	v_mul_f32_e32 v153, 0xbfb8aa3b, v153
	v_mul_f32_e32 v154, 0xbfb8aa3b, v154
	v_mul_f32_e32 v155, 0xbfb8aa3b, v155
	v_mul_f32_e32 v156, 0xbfb8aa3b, v156
	v_mul_f32_e32 v157, 0xbfb8aa3b, v157
	v_mul_f32_e32 v158, 0xbfb8aa3b, v158
	v_mul_f32_e32 v159, 0xbfb8aa3b, v159
	v_exp_f32_e32 v152, v152
	v_exp_f32_e32 v153, v153
	v_exp_f32_e32 v154, v154
	v_exp_f32_e32 v155, v155
	v_exp_f32_e32 v156, v156
	v_exp_f32_e32 v157, v157
	v_exp_f32_e32 v158, v158
	v_exp_f32_e32 v159, v159
	v_pk_add_f32 v[152:153], v[152:153], 1.0 op_sel_hi:[1,0]
	v_pk_add_f32 v[154:155], v[154:155], 1.0 op_sel_hi:[1,0]
	v_pk_add_f32 v[156:157], v[156:157], 1.0 op_sel_hi:[1,0]
	v_pk_add_f32 v[158:159], v[158:159], 1.0 op_sel_hi:[1,0]
	v_div_scale_f32 v160, s[38:39], v152, v152, 1.0
	v_div_scale_f32 v161, s[38:39], v153, v153, 1.0
	v_div_scale_f32 v162, s[38:39], v154, v154, 1.0
	v_div_scale_f32 v163, s[38:39], v155, v155, 1.0
	v_rcp_f32_e32 v164, v160
	v_rcp_f32_e32 v165, v161
	v_rcp_f32_e32 v166, v162
	v_rcp_f32_e32 v167, v163
	v_pk_fma_f32 v[148:149], v[160:161], v[164:165], 1.0 op_sel_hi:[1,1,0] neg_lo:[1,0,0] neg_hi:[1,0,0]
	v_pk_fma_f32 v[150:151], v[162:163], v[166:167], 1.0 op_sel_hi:[1,1,0] neg_lo:[1,0,0] neg_hi:[1,0,0]
	v_pk_fma_f32 v[164:165], v[148:149], v[164:165], v[164:165]
	v_pk_fma_f32 v[166:167], v[150:151], v[166:167], v[166:167]
	v_div_scale_f32 v168, s[2:3], 1.0, v152, 1.0
	v_div_scale_f32 v169, s[26:27], 1.0, v153, 1.0
	v_div_scale_f32 v170, s[28:29], 1.0, v154, 1.0
	v_div_scale_f32 v171, vcc, 1.0, v155, 1.0
	v_pk_mul_f32 v[128:129], v[168:169], v[164:165]
	v_pk_mul_f32 v[130:131], v[170:171], v[166:167]
	v_pk_fma_f32 v[148:149], v[160:161], v[128:129], v[168:169] neg_lo:[1,0,0] neg_hi:[1,0,0]
	v_pk_fma_f32 v[150:151], v[162:163], v[130:131], v[170:171] neg_lo:[1,0,0] neg_hi:[1,0,0]
	v_pk_fma_f32 v[128:129], v[148:149], v[164:165], v[128:129]
	v_pk_fma_f32 v[130:131], v[150:151], v[166:167], v[130:131]
	v_pk_fma_f32 v[160:161], v[160:161], v[128:129], v[168:169] neg_lo:[1,0,0] neg_hi:[1,0,0]
	v_pk_fma_f32 v[162:163], v[162:163], v[130:131], v[170:171] neg_lo:[1,0,0] neg_hi:[1,0,0]
	v_div_fmas_f32 v163, v163, v167, v131
	s_mov_b64 vcc, s[28:29]
	v_div_fmas_f32 v162, v162, v166, v130
	s_mov_b64 vcc, s[26:27]
	v_div_fmas_f32 v161, v161, v165, v129
	s_mov_b64 vcc, s[2:3]
	v_div_fmas_f32 v160, v160, v164, v128
	v_div_fixup_f32 v152, v160, v152, 1.0
	v_div_fixup_f32 v153, v161, v153, 1.0
	v_div_fixup_f32 v154, v162, v154, 1.0
	v_div_fixup_f32 v155, v163, v155, 1.0
	v_div_scale_f32 v160, s[38:39], v156, v156, 1.0
	v_div_scale_f32 v161, s[38:39], v157, v157, 1.0
	v_div_scale_f32 v162, s[38:39], v158, v158, 1.0
	v_div_scale_f32 v163, s[38:39], v159, v159, 1.0
	v_rcp_f32_e32 v164, v160
	v_rcp_f32_e32 v165, v161
	v_rcp_f32_e32 v166, v162
	v_rcp_f32_e32 v167, v163
	v_pk_fma_f32 v[148:149], v[160:161], v[164:165], 1.0 op_sel_hi:[1,1,0] neg_lo:[1,0,0] neg_hi:[1,0,0]
	v_pk_fma_f32 v[150:151], v[162:163], v[166:167], 1.0 op_sel_hi:[1,1,0] neg_lo:[1,0,0] neg_hi:[1,0,0]
	v_pk_fma_f32 v[164:165], v[148:149], v[164:165], v[164:165]
	v_pk_fma_f32 v[166:167], v[150:151], v[166:167], v[166:167]
	v_div_scale_f32 v168, s[2:3], 1.0, v156, 1.0
	v_div_scale_f32 v169, s[26:27], 1.0, v157, 1.0
	v_div_scale_f32 v170, s[28:29], 1.0, v158, 1.0
	v_div_scale_f32 v171, vcc, 1.0, v159, 1.0
	v_pk_mul_f32 v[128:129], v[168:169], v[164:165]
	v_pk_mul_f32 v[130:131], v[170:171], v[166:167]
	v_pk_fma_f32 v[148:149], v[160:161], v[128:129], v[168:169] neg_lo:[1,0,0] neg_hi:[1,0,0]
	v_pk_fma_f32 v[150:151], v[162:163], v[130:131], v[170:171] neg_lo:[1,0,0] neg_hi:[1,0,0]
	v_pk_fma_f32 v[128:129], v[148:149], v[164:165], v[128:129]
	v_pk_fma_f32 v[130:131], v[150:151], v[166:167], v[130:131]
	v_pk_fma_f32 v[160:161], v[160:161], v[128:129], v[168:169] neg_lo:[1,0,0] neg_hi:[1,0,0]
	v_pk_fma_f32 v[162:163], v[162:163], v[130:131], v[170:171] neg_lo:[1,0,0] neg_hi:[1,0,0]
	v_div_fmas_f32 v163, v163, v167, v131
	s_mov_b64 vcc, s[28:29]
	v_div_fmas_f32 v162, v162, v166, v130
	s_mov_b64 vcc, s[26:27]
	v_div_fmas_f32 v161, v161, v165, v129
	s_mov_b64 vcc, s[2:3]
	v_div_fmas_f32 v160, v160, v164, v128
	v_div_fixup_f32 v156, v160, v156, 1.0
	v_div_fixup_f32 v157, v161, v157, 1.0
	v_div_fixup_f32 v158, v162, v158, 1.0
	v_div_fixup_f32 v159, v163, v159, 1.0
	v_lshlrev_b32_e32 v166, 16, v88
	v_and_b32_e32 v167, 0xffff0000, v88
	v_pk_fma_f32 v[152:153], v[60:61], v[152:153], v[166:167]
	v_lshlrev_b32_e32 v166, 16, v89
	v_and_b32_e32 v167, 0xffff0000, v89
	v_pk_fma_f32 v[154:155], v[62:63], v[154:155], v[166:167]
	v_lshlrev_b32_e32 v166, 16, v90
	v_and_b32_e32 v167, 0xffff0000, v90
	v_pk_fma_f32 v[156:157], v[56:57], v[156:157], v[166:167]
	v_lshlrev_b32_e32 v166, 16, v91
	v_and_b32_e32 v167, 0xffff0000, v91
	v_pk_fma_f32 v[158:159], v[58:59], v[158:159], v[166:167]
	v_cvt_pk_bf16_f32 v168, v152, v153
	v_cvt_pk_bf16_f32 v169, v154, v155
	v_cvt_pk_bf16_f32 v170, v156, v157
	v_cvt_pk_bf16_f32 v171, v158, v159
	global_store_dwordx4 v188, v[168:171], s[66:67]
	global_load_dwordx4 v[60:63], v182, s[64:65]
	global_load_dwordx4 v[56:59], v190, s[68:69]
	s_waitcnt vmcnt(9)
; __device__ __forceinline__ float sigmoidf_(float x) { return 1.f / (1.f + __expf(-x)); }
	v_lshlrev_b32_e32 v152, 16, v84
	v_and_b32_e32 v153, 0xffff0000, v84
	v_lshlrev_b32_e32 v154, 16, v85
	v_and_b32_e32 v155, 0xffff0000, v85
	v_lshlrev_b32_e32 v156, 16, v86
	v_and_b32_e32 v157, 0xffff0000, v86
	v_lshlrev_b32_e32 v158, 16, v87
	v_and_b32_e32 v159, 0xffff0000, v87
	v_mul_f32_e32 v152, 0xbfb8aa3b, v152
	v_mul_f32_e32 v153, 0xbfb8aa3b, v153
	v_mul_f32_e32 v154, 0xbfb8aa3b, v154
	v_mul_f32_e32 v155, 0xbfb8aa3b, v155
	v_mul_f32_e32 v156, 0xbfb8aa3b, v156
	v_mul_f32_e32 v157, 0xbfb8aa3b, v157
	v_mul_f32_e32 v158, 0xbfb8aa3b, v158
	v_mul_f32_e32 v159, 0xbfb8aa3b, v159
	v_exp_f32_e32 v152, v152
	v_exp_f32_e32 v153, v153
	v_exp_f32_e32 v154, v154
	v_exp_f32_e32 v155, v155
	v_exp_f32_e32 v156, v156
	v_exp_f32_e32 v157, v157
	v_exp_f32_e32 v158, v158
	v_exp_f32_e32 v159, v159
	v_pk_add_f32 v[152:153], v[152:153], 1.0 op_sel_hi:[1,0]
	v_pk_add_f32 v[154:155], v[154:155], 1.0 op_sel_hi:[1,0]
	v_pk_add_f32 v[156:157], v[156:157], 1.0 op_sel_hi:[1,0]
	v_pk_add_f32 v[158:159], v[158:159], 1.0 op_sel_hi:[1,0]
	v_div_scale_f32 v160, s[38:39], v152, v152, 1.0
	v_div_scale_f32 v161, s[38:39], v153, v153, 1.0
	v_div_scale_f32 v162, s[38:39], v154, v154, 1.0
	v_div_scale_f32 v163, s[38:39], v155, v155, 1.0
	v_rcp_f32_e32 v164, v160
	v_rcp_f32_e32 v165, v161
	v_rcp_f32_e32 v166, v162
	v_rcp_f32_e32 v167, v163
	v_pk_fma_f32 v[148:149], v[160:161], v[164:165], 1.0 op_sel_hi:[1,1,0] neg_lo:[1,0,0] neg_hi:[1,0,0]
	v_pk_fma_f32 v[150:151], v[162:163], v[166:167], 1.0 op_sel_hi:[1,1,0] neg_lo:[1,0,0] neg_hi:[1,0,0]
	v_pk_fma_f32 v[164:165], v[148:149], v[164:165], v[164:165]
	v_pk_fma_f32 v[166:167], v[150:151], v[166:167], v[166:167]
	v_div_scale_f32 v168, s[2:3], 1.0, v152, 1.0
	v_div_scale_f32 v169, s[26:27], 1.0, v153, 1.0
	v_div_scale_f32 v170, s[28:29], 1.0, v154, 1.0
	v_div_scale_f32 v171, vcc, 1.0, v155, 1.0
	v_pk_mul_f32 v[128:129], v[168:169], v[164:165]
	v_pk_mul_f32 v[130:131], v[170:171], v[166:167]
	v_pk_fma_f32 v[148:149], v[160:161], v[128:129], v[168:169] neg_lo:[1,0,0] neg_hi:[1,0,0]
	v_pk_fma_f32 v[150:151], v[162:163], v[130:131], v[170:171] neg_lo:[1,0,0] neg_hi:[1,0,0]
	v_pk_fma_f32 v[128:129], v[148:149], v[164:165], v[128:129]
	v_pk_fma_f32 v[130:131], v[150:151], v[166:167], v[130:131]
	v_pk_fma_f32 v[160:161], v[160:161], v[128:129], v[168:169] neg_lo:[1,0,0] neg_hi:[1,0,0]
	v_pk_fma_f32 v[162:163], v[162:163], v[130:131], v[170:171] neg_lo:[1,0,0] neg_hi:[1,0,0]
	v_div_fmas_f32 v163, v163, v167, v131
	s_mov_b64 vcc, s[28:29]
	v_div_fmas_f32 v162, v162, v166, v130
	s_mov_b64 vcc, s[26:27]
	v_div_fmas_f32 v161, v161, v165, v129
	s_mov_b64 vcc, s[2:3]
	v_div_fmas_f32 v160, v160, v164, v128
	v_div_fixup_f32 v152, v160, v152, 1.0
	v_div_fixup_f32 v153, v161, v153, 1.0
	v_div_fixup_f32 v154, v162, v154, 1.0
	v_div_fixup_f32 v155, v163, v155, 1.0
	v_div_scale_f32 v160, s[38:39], v156, v156, 1.0
	v_div_scale_f32 v161, s[38:39], v157, v157, 1.0
	v_div_scale_f32 v162, s[38:39], v158, v158, 1.0
	v_div_scale_f32 v163, s[38:39], v159, v159, 1.0
	v_rcp_f32_e32 v164, v160
	v_rcp_f32_e32 v165, v161
	v_rcp_f32_e32 v166, v162
	v_rcp_f32_e32 v167, v163
	v_pk_fma_f32 v[148:149], v[160:161], v[164:165], 1.0 op_sel_hi:[1,1,0] neg_lo:[1,0,0] neg_hi:[1,0,0]
	v_pk_fma_f32 v[150:151], v[162:163], v[166:167], 1.0 op_sel_hi:[1,1,0] neg_lo:[1,0,0] neg_hi:[1,0,0]
	v_pk_fma_f32 v[164:165], v[148:149], v[164:165], v[164:165]
	v_pk_fma_f32 v[166:167], v[150:151], v[166:167], v[166:167]
	v_div_scale_f32 v168, s[2:3], 1.0, v156, 1.0
	v_div_scale_f32 v169, s[26:27], 1.0, v157, 1.0
	v_div_scale_f32 v170, s[28:29], 1.0, v158, 1.0
	v_div_scale_f32 v171, vcc, 1.0, v159, 1.0
	v_pk_mul_f32 v[128:129], v[168:169], v[164:165]
	v_pk_mul_f32 v[130:131], v[170:171], v[166:167]
	v_pk_fma_f32 v[148:149], v[160:161], v[128:129], v[168:169] neg_lo:[1,0,0] neg_hi:[1,0,0]
	v_pk_fma_f32 v[150:151], v[162:163], v[130:131], v[170:171] neg_lo:[1,0,0] neg_hi:[1,0,0]
	v_pk_fma_f32 v[128:129], v[148:149], v[164:165], v[128:129]
	v_pk_fma_f32 v[130:131], v[150:151], v[166:167], v[130:131]
	v_pk_fma_f32 v[160:161], v[160:161], v[128:129], v[168:169] neg_lo:[1,0,0] neg_hi:[1,0,0]
	v_pk_fma_f32 v[162:163], v[162:163], v[130:131], v[170:171] neg_lo:[1,0,0] neg_hi:[1,0,0]
	v_div_fmas_f32 v163, v163, v167, v131
	s_mov_b64 vcc, s[28:29]
	v_div_fmas_f32 v162, v162, v166, v130
	s_mov_b64 vcc, s[26:27]
	v_div_fmas_f32 v161, v161, v165, v129
	s_mov_b64 vcc, s[2:3]
	v_div_fmas_f32 v160, v160, v164, v128
	v_div_fixup_f32 v156, v160, v156, 1.0
	v_div_fixup_f32 v157, v161, v157, 1.0
	v_div_fixup_f32 v158, v162, v158, 1.0
	v_div_fixup_f32 v159, v163, v159, 1.0
	v_lshlrev_b32_e32 v166, 16, v80
	v_and_b32_e32 v167, 0xffff0000, v80
	v_pk_fma_f32 v[152:153], v[52:53], v[152:153], v[166:167]
	v_lshlrev_b32_e32 v166, 16, v81
	v_and_b32_e32 v167, 0xffff0000, v81
	v_pk_fma_f32 v[154:155], v[54:55], v[154:155], v[166:167]
	v_lshlrev_b32_e32 v166, 16, v82
	v_and_b32_e32 v167, 0xffff0000, v82
	v_pk_fma_f32 v[156:157], v[48:49], v[156:157], v[166:167]
	v_lshlrev_b32_e32 v166, 16, v83
	v_and_b32_e32 v167, 0xffff0000, v83
	v_pk_fma_f32 v[158:159], v[50:51], v[158:159], v[166:167]
	v_cvt_pk_bf16_f32 v168, v152, v153
	v_cvt_pk_bf16_f32 v169, v154, v155
	v_cvt_pk_bf16_f32 v170, v156, v157
	v_cvt_pk_bf16_f32 v171, v158, v159
	global_store_dwordx4 v188, v[168:171], s[66:67] offset:256
	global_load_dwordx4 v[52:55], v182, s[64:65] offset:256
	global_load_dwordx4 v[48:51], v190, s[68:69] offset:256
	s_waitcnt vmcnt(9)
; __device__ __forceinline__ float sigmoidf_(float x) { return 1.f / (1.f + __expf(-x)); }
	v_lshlrev_b32_e32 v152, 16, v76
	v_and_b32_e32 v153, 0xffff0000, v76
	v_lshlrev_b32_e32 v154, 16, v77
	v_and_b32_e32 v155, 0xffff0000, v77
	v_lshlrev_b32_e32 v156, 16, v78
	v_and_b32_e32 v157, 0xffff0000, v78
	v_lshlrev_b32_e32 v158, 16, v79
	v_and_b32_e32 v159, 0xffff0000, v79
	v_mul_f32_e32 v152, 0xbfb8aa3b, v152
	v_mul_f32_e32 v153, 0xbfb8aa3b, v153
	v_mul_f32_e32 v154, 0xbfb8aa3b, v154
	v_mul_f32_e32 v155, 0xbfb8aa3b, v155
	v_mul_f32_e32 v156, 0xbfb8aa3b, v156
	v_mul_f32_e32 v157, 0xbfb8aa3b, v157
	v_mul_f32_e32 v158, 0xbfb8aa3b, v158
	v_mul_f32_e32 v159, 0xbfb8aa3b, v159
	v_exp_f32_e32 v152, v152
	v_exp_f32_e32 v153, v153
	v_exp_f32_e32 v154, v154
	v_exp_f32_e32 v155, v155
	v_exp_f32_e32 v156, v156
	v_exp_f32_e32 v157, v157
	v_exp_f32_e32 v158, v158
	v_exp_f32_e32 v159, v159
	v_pk_add_f32 v[152:153], v[152:153], 1.0 op_sel_hi:[1,0]
	v_pk_add_f32 v[154:155], v[154:155], 1.0 op_sel_hi:[1,0]
	v_pk_add_f32 v[156:157], v[156:157], 1.0 op_sel_hi:[1,0]
	v_pk_add_f32 v[158:159], v[158:159], 1.0 op_sel_hi:[1,0]
	v_div_scale_f32 v160, s[38:39], v152, v152, 1.0
	v_div_scale_f32 v161, s[38:39], v153, v153, 1.0
	v_div_scale_f32 v162, s[38:39], v154, v154, 1.0
	v_div_scale_f32 v163, s[38:39], v155, v155, 1.0
	v_rcp_f32_e32 v164, v160
	v_rcp_f32_e32 v165, v161
	v_rcp_f32_e32 v166, v162
	v_rcp_f32_e32 v167, v163
	v_pk_fma_f32 v[148:149], v[160:161], v[164:165], 1.0 op_sel_hi:[1,1,0] neg_lo:[1,0,0] neg_hi:[1,0,0]
	v_pk_fma_f32 v[150:151], v[162:163], v[166:167], 1.0 op_sel_hi:[1,1,0] neg_lo:[1,0,0] neg_hi:[1,0,0]
	v_pk_fma_f32 v[164:165], v[148:149], v[164:165], v[164:165]
	v_pk_fma_f32 v[166:167], v[150:151], v[166:167], v[166:167]
	v_div_scale_f32 v168, s[2:3], 1.0, v152, 1.0
	v_div_scale_f32 v169, s[26:27], 1.0, v153, 1.0
	v_div_scale_f32 v170, s[28:29], 1.0, v154, 1.0
	v_div_scale_f32 v171, vcc, 1.0, v155, 1.0
	v_pk_mul_f32 v[128:129], v[168:169], v[164:165]
	v_pk_mul_f32 v[130:131], v[170:171], v[166:167]
	v_pk_fma_f32 v[148:149], v[160:161], v[128:129], v[168:169] neg_lo:[1,0,0] neg_hi:[1,0,0]
	v_pk_fma_f32 v[150:151], v[162:163], v[130:131], v[170:171] neg_lo:[1,0,0] neg_hi:[1,0,0]
	v_pk_fma_f32 v[128:129], v[148:149], v[164:165], v[128:129]
	v_pk_fma_f32 v[130:131], v[150:151], v[166:167], v[130:131]
	v_pk_fma_f32 v[160:161], v[160:161], v[128:129], v[168:169] neg_lo:[1,0,0] neg_hi:[1,0,0]
	v_pk_fma_f32 v[162:163], v[162:163], v[130:131], v[170:171] neg_lo:[1,0,0] neg_hi:[1,0,0]
	v_div_fmas_f32 v163, v163, v167, v131
	s_mov_b64 vcc, s[28:29]
	v_div_fmas_f32 v162, v162, v166, v130
	s_mov_b64 vcc, s[26:27]
	v_div_fmas_f32 v161, v161, v165, v129
	s_mov_b64 vcc, s[2:3]
	v_div_fmas_f32 v160, v160, v164, v128
	v_div_fixup_f32 v152, v160, v152, 1.0
	v_div_fixup_f32 v153, v161, v153, 1.0
	v_div_fixup_f32 v154, v162, v154, 1.0
	v_div_fixup_f32 v155, v163, v155, 1.0
	v_div_scale_f32 v160, s[38:39], v156, v156, 1.0
	v_div_scale_f32 v161, s[38:39], v157, v157, 1.0
	v_div_scale_f32 v162, s[38:39], v158, v158, 1.0
	v_div_scale_f32 v163, s[38:39], v159, v159, 1.0
	v_rcp_f32_e32 v164, v160
	v_rcp_f32_e32 v165, v161
	v_rcp_f32_e32 v166, v162
	v_rcp_f32_e32 v167, v163
	v_pk_fma_f32 v[148:149], v[160:161], v[164:165], 1.0 op_sel_hi:[1,1,0] neg_lo:[1,0,0] neg_hi:[1,0,0]
	v_pk_fma_f32 v[150:151], v[162:163], v[166:167], 1.0 op_sel_hi:[1,1,0] neg_lo:[1,0,0] neg_hi:[1,0,0]
	v_pk_fma_f32 v[164:165], v[148:149], v[164:165], v[164:165]
	v_pk_fma_f32 v[166:167], v[150:151], v[166:167], v[166:167]
	v_div_scale_f32 v168, s[2:3], 1.0, v156, 1.0
	v_div_scale_f32 v169, s[26:27], 1.0, v157, 1.0
	v_div_scale_f32 v170, s[28:29], 1.0, v158, 1.0
	v_div_scale_f32 v171, vcc, 1.0, v159, 1.0
	v_pk_mul_f32 v[128:129], v[168:169], v[164:165]
	v_pk_mul_f32 v[130:131], v[170:171], v[166:167]
	v_pk_fma_f32 v[148:149], v[160:161], v[128:129], v[168:169] neg_lo:[1,0,0] neg_hi:[1,0,0]
	v_pk_fma_f32 v[150:151], v[162:163], v[130:131], v[170:171] neg_lo:[1,0,0] neg_hi:[1,0,0]
	v_pk_fma_f32 v[128:129], v[148:149], v[164:165], v[128:129]
	v_pk_fma_f32 v[130:131], v[150:151], v[166:167], v[130:131]
	v_pk_fma_f32 v[160:161], v[160:161], v[128:129], v[168:169] neg_lo:[1,0,0] neg_hi:[1,0,0]
	v_pk_fma_f32 v[162:163], v[162:163], v[130:131], v[170:171] neg_lo:[1,0,0] neg_hi:[1,0,0]
	v_div_fmas_f32 v163, v163, v167, v131
	s_mov_b64 vcc, s[28:29]
	v_div_fmas_f32 v162, v162, v166, v130
	s_mov_b64 vcc, s[26:27]
	v_div_fmas_f32 v161, v161, v165, v129
	s_mov_b64 vcc, s[2:3]
	v_div_fmas_f32 v160, v160, v164, v128
	v_div_fixup_f32 v156, v160, v156, 1.0
	v_div_fixup_f32 v157, v161, v157, 1.0
	v_div_fixup_f32 v158, v162, v158, 1.0
	v_div_fixup_f32 v159, v163, v159, 1.0
	v_lshlrev_b32_e32 v166, 16, v72
	v_and_b32_e32 v167, 0xffff0000, v72
	v_pk_fma_f32 v[152:153], v[44:45], v[152:153], v[166:167]
	v_lshlrev_b32_e32 v166, 16, v73
	v_and_b32_e32 v167, 0xffff0000, v73
	v_pk_fma_f32 v[154:155], v[46:47], v[154:155], v[166:167]
	v_lshlrev_b32_e32 v166, 16, v74
	v_and_b32_e32 v167, 0xffff0000, v74
	v_pk_fma_f32 v[156:157], v[40:41], v[156:157], v[166:167]
	v_lshlrev_b32_e32 v166, 16, v75
	v_and_b32_e32 v167, 0xffff0000, v75
	v_pk_fma_f32 v[158:159], v[42:43], v[158:159], v[166:167]
	v_cvt_pk_bf16_f32 v168, v152, v153
	v_cvt_pk_bf16_f32 v169, v154, v155
	v_cvt_pk_bf16_f32 v170, v156, v157
	v_cvt_pk_bf16_f32 v171, v158, v159
	global_store_dwordx4 v189, v[168:171], s[66:67]
	global_load_dwordx4 v[44:47], v183, s[64:65]
	global_load_dwordx4 v[40:43], v191, s[68:69]
	s_waitcnt vmcnt(9)
; __device__ __forceinline__ float sigmoidf_(float x) { return 1.f / (1.f + __expf(-x)); }
	v_lshlrev_b32_e32 v152, 16, v68
	v_and_b32_e32 v153, 0xffff0000, v68
	v_lshlrev_b32_e32 v154, 16, v69
	v_and_b32_e32 v155, 0xffff0000, v69
	v_lshlrev_b32_e32 v156, 16, v70
	v_and_b32_e32 v157, 0xffff0000, v70
	v_lshlrev_b32_e32 v158, 16, v71
	v_and_b32_e32 v159, 0xffff0000, v71
	v_mul_f32_e32 v152, 0xbfb8aa3b, v152
	v_mul_f32_e32 v153, 0xbfb8aa3b, v153
	v_mul_f32_e32 v154, 0xbfb8aa3b, v154
	v_mul_f32_e32 v155, 0xbfb8aa3b, v155
	v_mul_f32_e32 v156, 0xbfb8aa3b, v156
	v_mul_f32_e32 v157, 0xbfb8aa3b, v157
	v_mul_f32_e32 v158, 0xbfb8aa3b, v158
	v_mul_f32_e32 v159, 0xbfb8aa3b, v159
	v_exp_f32_e32 v152, v152
	v_exp_f32_e32 v153, v153
	v_exp_f32_e32 v154, v154
	v_exp_f32_e32 v155, v155
	v_exp_f32_e32 v156, v156
	v_exp_f32_e32 v157, v157
	v_exp_f32_e32 v158, v158
	v_exp_f32_e32 v159, v159
	v_pk_add_f32 v[152:153], v[152:153], 1.0 op_sel_hi:[1,0]
	v_pk_add_f32 v[154:155], v[154:155], 1.0 op_sel_hi:[1,0]
	v_pk_add_f32 v[156:157], v[156:157], 1.0 op_sel_hi:[1,0]
	v_pk_add_f32 v[158:159], v[158:159], 1.0 op_sel_hi:[1,0]
	v_div_scale_f32 v160, s[38:39], v152, v152, 1.0
	v_div_scale_f32 v161, s[38:39], v153, v153, 1.0
	v_div_scale_f32 v162, s[38:39], v154, v154, 1.0
	v_div_scale_f32 v163, s[38:39], v155, v155, 1.0
	v_rcp_f32_e32 v164, v160
	v_rcp_f32_e32 v165, v161
	v_rcp_f32_e32 v166, v162
	v_rcp_f32_e32 v167, v163
	v_pk_fma_f32 v[148:149], v[160:161], v[164:165], 1.0 op_sel_hi:[1,1,0] neg_lo:[1,0,0] neg_hi:[1,0,0]
	v_pk_fma_f32 v[150:151], v[162:163], v[166:167], 1.0 op_sel_hi:[1,1,0] neg_lo:[1,0,0] neg_hi:[1,0,0]
	v_pk_fma_f32 v[164:165], v[148:149], v[164:165], v[164:165]
	v_pk_fma_f32 v[166:167], v[150:151], v[166:167], v[166:167]
	v_div_scale_f32 v168, s[2:3], 1.0, v152, 1.0
	v_div_scale_f32 v169, s[26:27], 1.0, v153, 1.0
	v_div_scale_f32 v170, s[28:29], 1.0, v154, 1.0
	v_div_scale_f32 v171, vcc, 1.0, v155, 1.0
	v_pk_mul_f32 v[128:129], v[168:169], v[164:165]
	v_pk_mul_f32 v[130:131], v[170:171], v[166:167]
	v_pk_fma_f32 v[148:149], v[160:161], v[128:129], v[168:169] neg_lo:[1,0,0] neg_hi:[1,0,0]
	v_pk_fma_f32 v[150:151], v[162:163], v[130:131], v[170:171] neg_lo:[1,0,0] neg_hi:[1,0,0]
	v_pk_fma_f32 v[128:129], v[148:149], v[164:165], v[128:129]
	v_pk_fma_f32 v[130:131], v[150:151], v[166:167], v[130:131]
	v_pk_fma_f32 v[160:161], v[160:161], v[128:129], v[168:169] neg_lo:[1,0,0] neg_hi:[1,0,0]
	v_pk_fma_f32 v[162:163], v[162:163], v[130:131], v[170:171] neg_lo:[1,0,0] neg_hi:[1,0,0]
	v_div_fmas_f32 v163, v163, v167, v131
	s_mov_b64 vcc, s[28:29]
	v_div_fmas_f32 v162, v162, v166, v130
	s_mov_b64 vcc, s[26:27]
	v_div_fmas_f32 v161, v161, v165, v129
	s_mov_b64 vcc, s[2:3]
	v_div_fmas_f32 v160, v160, v164, v128
	v_div_fixup_f32 v152, v160, v152, 1.0
	v_div_fixup_f32 v153, v161, v153, 1.0
	v_div_fixup_f32 v154, v162, v154, 1.0
	v_div_fixup_f32 v155, v163, v155, 1.0
	v_div_scale_f32 v160, s[38:39], v156, v156, 1.0
	v_div_scale_f32 v161, s[38:39], v157, v157, 1.0
	v_div_scale_f32 v162, s[38:39], v158, v158, 1.0
	v_div_scale_f32 v163, s[38:39], v159, v159, 1.0
	v_rcp_f32_e32 v164, v160
	v_rcp_f32_e32 v165, v161
	v_rcp_f32_e32 v166, v162
	v_rcp_f32_e32 v167, v163
	v_pk_fma_f32 v[148:149], v[160:161], v[164:165], 1.0 op_sel_hi:[1,1,0] neg_lo:[1,0,0] neg_hi:[1,0,0]
	v_pk_fma_f32 v[150:151], v[162:163], v[166:167], 1.0 op_sel_hi:[1,1,0] neg_lo:[1,0,0] neg_hi:[1,0,0]
	v_pk_fma_f32 v[164:165], v[148:149], v[164:165], v[164:165]
	v_pk_fma_f32 v[166:167], v[150:151], v[166:167], v[166:167]
	v_div_scale_f32 v168, s[2:3], 1.0, v156, 1.0
	v_div_scale_f32 v169, s[26:27], 1.0, v157, 1.0
	v_div_scale_f32 v170, s[28:29], 1.0, v158, 1.0
	v_div_scale_f32 v171, vcc, 1.0, v159, 1.0
	v_pk_mul_f32 v[128:129], v[168:169], v[164:165]
	v_pk_mul_f32 v[130:131], v[170:171], v[166:167]
	v_pk_fma_f32 v[148:149], v[160:161], v[128:129], v[168:169] neg_lo:[1,0,0] neg_hi:[1,0,0]
	v_pk_fma_f32 v[150:151], v[162:163], v[130:131], v[170:171] neg_lo:[1,0,0] neg_hi:[1,0,0]
	v_pk_fma_f32 v[128:129], v[148:149], v[164:165], v[128:129]
	v_pk_fma_f32 v[130:131], v[150:151], v[166:167], v[130:131]
	v_pk_fma_f32 v[160:161], v[160:161], v[128:129], v[168:169] neg_lo:[1,0,0] neg_hi:[1,0,0]
	v_pk_fma_f32 v[162:163], v[162:163], v[130:131], v[170:171] neg_lo:[1,0,0] neg_hi:[1,0,0]
	v_div_fmas_f32 v163, v163, v167, v131
	s_mov_b64 vcc, s[28:29]
	v_div_fmas_f32 v162, v162, v166, v130
	s_mov_b64 vcc, s[26:27]
	v_div_fmas_f32 v161, v161, v165, v129
	s_mov_b64 vcc, s[2:3]
	v_div_fmas_f32 v160, v160, v164, v128
	v_div_fixup_f32 v156, v160, v156, 1.0
	v_div_fixup_f32 v157, v161, v157, 1.0
	v_div_fixup_f32 v158, v162, v158, 1.0
	v_div_fixup_f32 v159, v163, v159, 1.0
	v_lshlrev_b32_e32 v166, 16, v64
	v_and_b32_e32 v167, 0xffff0000, v64
	v_pk_fma_f32 v[152:153], v[36:37], v[152:153], v[166:167]
	v_lshlrev_b32_e32 v166, 16, v65
	v_and_b32_e32 v167, 0xffff0000, v65
	v_pk_fma_f32 v[154:155], v[38:39], v[154:155], v[166:167]
	v_lshlrev_b32_e32 v166, 16, v66
	v_and_b32_e32 v167, 0xffff0000, v66
	v_pk_fma_f32 v[156:157], v[32:33], v[156:157], v[166:167]
	v_lshlrev_b32_e32 v166, 16, v67
	v_and_b32_e32 v167, 0xffff0000, v67
	v_pk_fma_f32 v[158:159], v[34:35], v[158:159], v[166:167]
	v_cvt_pk_bf16_f32 v168, v152, v153
	v_cvt_pk_bf16_f32 v169, v154, v155
	v_cvt_pk_bf16_f32 v170, v156, v157
	v_cvt_pk_bf16_f32 v171, v158, v159
	global_store_dwordx4 v189, v[168:171], s[66:67] offset:256
	global_load_dwordx4 v[36:39], v183, s[64:65] offset:256
	global_load_dwordx4 v[32:35], v191, s[68:69] offset:256
	s_waitcnt vmcnt(9)
; __device__ __forceinline__ float sigmoidf_(float x) { return 1.f / (1.f + __expf(-x)); }
	v_lshlrev_b32_e32 v152, 16, v60
	v_and_b32_e32 v153, 0xffff0000, v60
	v_lshlrev_b32_e32 v154, 16, v61
	v_and_b32_e32 v155, 0xffff0000, v61
	v_lshlrev_b32_e32 v156, 16, v62
	v_and_b32_e32 v157, 0xffff0000, v62
	v_lshlrev_b32_e32 v158, 16, v63
	v_and_b32_e32 v159, 0xffff0000, v63
	v_mul_f32_e32 v152, 0xbfb8aa3b, v152
	v_mul_f32_e32 v153, 0xbfb8aa3b, v153
	v_mul_f32_e32 v154, 0xbfb8aa3b, v154
	v_mul_f32_e32 v155, 0xbfb8aa3b, v155
	v_mul_f32_e32 v156, 0xbfb8aa3b, v156
	v_mul_f32_e32 v157, 0xbfb8aa3b, v157
	v_mul_f32_e32 v158, 0xbfb8aa3b, v158
	v_mul_f32_e32 v159, 0xbfb8aa3b, v159
	v_exp_f32_e32 v152, v152
	v_exp_f32_e32 v153, v153
	v_exp_f32_e32 v154, v154
	v_exp_f32_e32 v155, v155
	v_exp_f32_e32 v156, v156
	v_exp_f32_e32 v157, v157
	v_exp_f32_e32 v158, v158
	v_exp_f32_e32 v159, v159
	v_pk_add_f32 v[152:153], v[152:153], 1.0 op_sel_hi:[1,0]
	v_pk_add_f32 v[154:155], v[154:155], 1.0 op_sel_hi:[1,0]
	v_pk_add_f32 v[156:157], v[156:157], 1.0 op_sel_hi:[1,0]
	v_pk_add_f32 v[158:159], v[158:159], 1.0 op_sel_hi:[1,0]
	v_div_scale_f32 v160, s[38:39], v152, v152, 1.0
	v_div_scale_f32 v161, s[38:39], v153, v153, 1.0
	v_div_scale_f32 v162, s[38:39], v154, v154, 1.0
	v_div_scale_f32 v163, s[38:39], v155, v155, 1.0
	v_rcp_f32_e32 v164, v160
	v_rcp_f32_e32 v165, v161
	v_rcp_f32_e32 v166, v162
	v_rcp_f32_e32 v167, v163
	v_pk_fma_f32 v[148:149], v[160:161], v[164:165], 1.0 op_sel_hi:[1,1,0] neg_lo:[1,0,0] neg_hi:[1,0,0]
	v_pk_fma_f32 v[150:151], v[162:163], v[166:167], 1.0 op_sel_hi:[1,1,0] neg_lo:[1,0,0] neg_hi:[1,0,0]
	v_pk_fma_f32 v[164:165], v[148:149], v[164:165], v[164:165]
	v_pk_fma_f32 v[166:167], v[150:151], v[166:167], v[166:167]
	v_div_scale_f32 v168, s[2:3], 1.0, v152, 1.0
	v_div_scale_f32 v169, s[26:27], 1.0, v153, 1.0
	v_div_scale_f32 v170, s[28:29], 1.0, v154, 1.0
	v_div_scale_f32 v171, vcc, 1.0, v155, 1.0
	v_pk_mul_f32 v[128:129], v[168:169], v[164:165]
	v_pk_mul_f32 v[130:131], v[170:171], v[166:167]
	v_pk_fma_f32 v[148:149], v[160:161], v[128:129], v[168:169] neg_lo:[1,0,0] neg_hi:[1,0,0]
	v_pk_fma_f32 v[150:151], v[162:163], v[130:131], v[170:171] neg_lo:[1,0,0] neg_hi:[1,0,0]
	v_pk_fma_f32 v[128:129], v[148:149], v[164:165], v[128:129]
	v_pk_fma_f32 v[130:131], v[150:151], v[166:167], v[130:131]
	v_pk_fma_f32 v[160:161], v[160:161], v[128:129], v[168:169] neg_lo:[1,0,0] neg_hi:[1,0,0]
	v_pk_fma_f32 v[162:163], v[162:163], v[130:131], v[170:171] neg_lo:[1,0,0] neg_hi:[1,0,0]
	v_div_fmas_f32 v163, v163, v167, v131
	s_mov_b64 vcc, s[28:29]
	v_div_fmas_f32 v162, v162, v166, v130
	s_mov_b64 vcc, s[26:27]
	v_div_fmas_f32 v161, v161, v165, v129
	s_mov_b64 vcc, s[2:3]
	v_div_fmas_f32 v160, v160, v164, v128
	v_div_fixup_f32 v152, v160, v152, 1.0
	v_div_fixup_f32 v153, v161, v153, 1.0
	v_div_fixup_f32 v154, v162, v154, 1.0
	v_div_fixup_f32 v155, v163, v155, 1.0
	v_div_scale_f32 v160, s[38:39], v156, v156, 1.0
	v_div_scale_f32 v161, s[38:39], v157, v157, 1.0
	v_div_scale_f32 v162, s[38:39], v158, v158, 1.0
	v_div_scale_f32 v163, s[38:39], v159, v159, 1.0
	v_rcp_f32_e32 v164, v160
	v_rcp_f32_e32 v165, v161
	v_rcp_f32_e32 v166, v162
	v_rcp_f32_e32 v167, v163
	v_pk_fma_f32 v[148:149], v[160:161], v[164:165], 1.0 op_sel_hi:[1,1,0] neg_lo:[1,0,0] neg_hi:[1,0,0]
	v_pk_fma_f32 v[150:151], v[162:163], v[166:167], 1.0 op_sel_hi:[1,1,0] neg_lo:[1,0,0] neg_hi:[1,0,0]
	v_pk_fma_f32 v[164:165], v[148:149], v[164:165], v[164:165]
	v_pk_fma_f32 v[166:167], v[150:151], v[166:167], v[166:167]
	v_div_scale_f32 v168, s[2:3], 1.0, v156, 1.0
	v_div_scale_f32 v169, s[26:27], 1.0, v157, 1.0
	v_div_scale_f32 v170, s[28:29], 1.0, v158, 1.0
	v_div_scale_f32 v171, vcc, 1.0, v159, 1.0
	v_pk_mul_f32 v[128:129], v[168:169], v[164:165]
	v_pk_mul_f32 v[130:131], v[170:171], v[166:167]
	v_pk_fma_f32 v[148:149], v[160:161], v[128:129], v[168:169] neg_lo:[1,0,0] neg_hi:[1,0,0]
	v_pk_fma_f32 v[150:151], v[162:163], v[130:131], v[170:171] neg_lo:[1,0,0] neg_hi:[1,0,0]
	v_pk_fma_f32 v[128:129], v[148:149], v[164:165], v[128:129]
	v_pk_fma_f32 v[130:131], v[150:151], v[166:167], v[130:131]
	v_pk_fma_f32 v[160:161], v[160:161], v[128:129], v[168:169] neg_lo:[1,0,0] neg_hi:[1,0,0]
	v_pk_fma_f32 v[162:163], v[162:163], v[130:131], v[170:171] neg_lo:[1,0,0] neg_hi:[1,0,0]
	v_div_fmas_f32 v163, v163, v167, v131
	s_mov_b64 vcc, s[28:29]
	v_div_fmas_f32 v162, v162, v166, v130
	s_mov_b64 vcc, s[26:27]
	v_div_fmas_f32 v161, v161, v165, v129
	s_mov_b64 vcc, s[2:3]
	v_div_fmas_f32 v160, v160, v164, v128
	v_div_fixup_f32 v156, v160, v156, 1.0
	v_div_fixup_f32 v157, v161, v157, 1.0
	v_div_fixup_f32 v158, v162, v158, 1.0
	v_div_fixup_f32 v159, v163, v159, 1.0
	v_lshlrev_b32_e32 v166, 16, v56
	v_and_b32_e32 v167, 0xffff0000, v56
	v_pk_fma_f32 v[152:153], v[28:29], v[152:153], v[166:167]
	v_lshlrev_b32_e32 v166, 16, v57
	v_and_b32_e32 v167, 0xffff0000, v57
	v_pk_fma_f32 v[154:155], v[30:31], v[154:155], v[166:167]
	v_lshlrev_b32_e32 v166, 16, v58
	v_and_b32_e32 v167, 0xffff0000, v58
	v_pk_fma_f32 v[156:157], v[24:25], v[156:157], v[166:167]
	v_lshlrev_b32_e32 v166, 16, v59
	v_and_b32_e32 v167, 0xffff0000, v59
	v_pk_fma_f32 v[158:159], v[26:27], v[158:159], v[166:167]
	v_cvt_pk_bf16_f32 v168, v152, v153
	v_cvt_pk_bf16_f32 v169, v154, v155
	v_cvt_pk_bf16_f32 v170, v156, v157
	v_cvt_pk_bf16_f32 v171, v158, v159
	global_store_dwordx4 v190, v[168:171], s[66:67]
	s_waitcnt vmcnt(7)
; __device__ __forceinline__ float sigmoidf_(float x) { return 1.f / (1.f + __expf(-x)); }
	v_lshlrev_b32_e32 v152, 16, v52
	v_and_b32_e32 v153, 0xffff0000, v52
	v_lshlrev_b32_e32 v154, 16, v53
	v_and_b32_e32 v155, 0xffff0000, v53
	v_lshlrev_b32_e32 v156, 16, v54
	v_and_b32_e32 v157, 0xffff0000, v54
	v_lshlrev_b32_e32 v158, 16, v55
	v_and_b32_e32 v159, 0xffff0000, v55
	v_mul_f32_e32 v152, 0xbfb8aa3b, v152
	v_mul_f32_e32 v153, 0xbfb8aa3b, v153
	v_mul_f32_e32 v154, 0xbfb8aa3b, v154
	v_mul_f32_e32 v155, 0xbfb8aa3b, v155
	v_mul_f32_e32 v156, 0xbfb8aa3b, v156
	v_mul_f32_e32 v157, 0xbfb8aa3b, v157
	v_mul_f32_e32 v158, 0xbfb8aa3b, v158
	v_mul_f32_e32 v159, 0xbfb8aa3b, v159
	v_exp_f32_e32 v152, v152
	v_exp_f32_e32 v153, v153
	v_exp_f32_e32 v154, v154
	v_exp_f32_e32 v155, v155
	v_exp_f32_e32 v156, v156
	v_exp_f32_e32 v157, v157
	v_exp_f32_e32 v158, v158
	v_exp_f32_e32 v159, v159
	v_pk_add_f32 v[152:153], v[152:153], 1.0 op_sel_hi:[1,0]
	v_pk_add_f32 v[154:155], v[154:155], 1.0 op_sel_hi:[1,0]
	v_pk_add_f32 v[156:157], v[156:157], 1.0 op_sel_hi:[1,0]
	v_pk_add_f32 v[158:159], v[158:159], 1.0 op_sel_hi:[1,0]
	v_div_scale_f32 v160, s[38:39], v152, v152, 1.0
	v_div_scale_f32 v161, s[38:39], v153, v153, 1.0
	v_div_scale_f32 v162, s[38:39], v154, v154, 1.0
	v_div_scale_f32 v163, s[38:39], v155, v155, 1.0
	v_rcp_f32_e32 v164, v160
	v_rcp_f32_e32 v165, v161
	v_rcp_f32_e32 v166, v162
	v_rcp_f32_e32 v167, v163
	v_pk_fma_f32 v[148:149], v[160:161], v[164:165], 1.0 op_sel_hi:[1,1,0] neg_lo:[1,0,0] neg_hi:[1,0,0]
	v_pk_fma_f32 v[150:151], v[162:163], v[166:167], 1.0 op_sel_hi:[1,1,0] neg_lo:[1,0,0] neg_hi:[1,0,0]
	v_pk_fma_f32 v[164:165], v[148:149], v[164:165], v[164:165]
	v_pk_fma_f32 v[166:167], v[150:151], v[166:167], v[166:167]
	v_div_scale_f32 v168, s[2:3], 1.0, v152, 1.0
	v_div_scale_f32 v169, s[26:27], 1.0, v153, 1.0
	v_div_scale_f32 v170, s[28:29], 1.0, v154, 1.0
	v_div_scale_f32 v171, vcc, 1.0, v155, 1.0
	v_pk_mul_f32 v[128:129], v[168:169], v[164:165]
	v_pk_mul_f32 v[130:131], v[170:171], v[166:167]
	v_pk_fma_f32 v[148:149], v[160:161], v[128:129], v[168:169] neg_lo:[1,0,0] neg_hi:[1,0,0]
	v_pk_fma_f32 v[150:151], v[162:163], v[130:131], v[170:171] neg_lo:[1,0,0] neg_hi:[1,0,0]
	v_pk_fma_f32 v[128:129], v[148:149], v[164:165], v[128:129]
	v_pk_fma_f32 v[130:131], v[150:151], v[166:167], v[130:131]
	v_pk_fma_f32 v[160:161], v[160:161], v[128:129], v[168:169] neg_lo:[1,0,0] neg_hi:[1,0,0]
	v_pk_fma_f32 v[162:163], v[162:163], v[130:131], v[170:171] neg_lo:[1,0,0] neg_hi:[1,0,0]
	v_div_fmas_f32 v163, v163, v167, v131
	s_mov_b64 vcc, s[28:29]
	v_div_fmas_f32 v162, v162, v166, v130
	s_mov_b64 vcc, s[26:27]
	v_div_fmas_f32 v161, v161, v165, v129
	s_mov_b64 vcc, s[2:3]
	v_div_fmas_f32 v160, v160, v164, v128
	v_div_fixup_f32 v152, v160, v152, 1.0
	v_div_fixup_f32 v153, v161, v153, 1.0
	v_div_fixup_f32 v154, v162, v154, 1.0
	v_div_fixup_f32 v155, v163, v155, 1.0
	v_div_scale_f32 v160, s[38:39], v156, v156, 1.0
	v_div_scale_f32 v161, s[38:39], v157, v157, 1.0
	v_div_scale_f32 v162, s[38:39], v158, v158, 1.0
	v_div_scale_f32 v163, s[38:39], v159, v159, 1.0
	v_rcp_f32_e32 v164, v160
	v_rcp_f32_e32 v165, v161
	v_rcp_f32_e32 v166, v162
	v_rcp_f32_e32 v167, v163
	v_pk_fma_f32 v[148:149], v[160:161], v[164:165], 1.0 op_sel_hi:[1,1,0] neg_lo:[1,0,0] neg_hi:[1,0,0]
	v_pk_fma_f32 v[150:151], v[162:163], v[166:167], 1.0 op_sel_hi:[1,1,0] neg_lo:[1,0,0] neg_hi:[1,0,0]
	v_pk_fma_f32 v[164:165], v[148:149], v[164:165], v[164:165]
	v_pk_fma_f32 v[166:167], v[150:151], v[166:167], v[166:167]
	v_div_scale_f32 v168, s[2:3], 1.0, v156, 1.0
	v_div_scale_f32 v169, s[26:27], 1.0, v157, 1.0
	v_div_scale_f32 v170, s[28:29], 1.0, v158, 1.0
	v_div_scale_f32 v171, vcc, 1.0, v159, 1.0
	v_pk_mul_f32 v[128:129], v[168:169], v[164:165]
	v_pk_mul_f32 v[130:131], v[170:171], v[166:167]
	v_pk_fma_f32 v[148:149], v[160:161], v[128:129], v[168:169] neg_lo:[1,0,0] neg_hi:[1,0,0]
	v_pk_fma_f32 v[150:151], v[162:163], v[130:131], v[170:171] neg_lo:[1,0,0] neg_hi:[1,0,0]
	v_pk_fma_f32 v[128:129], v[148:149], v[164:165], v[128:129]
	v_pk_fma_f32 v[130:131], v[150:151], v[166:167], v[130:131]
	v_pk_fma_f32 v[160:161], v[160:161], v[128:129], v[168:169] neg_lo:[1,0,0] neg_hi:[1,0,0]
	v_pk_fma_f32 v[162:163], v[162:163], v[130:131], v[170:171] neg_lo:[1,0,0] neg_hi:[1,0,0]
	v_div_fmas_f32 v163, v163, v167, v131
	s_mov_b64 vcc, s[28:29]
	v_div_fmas_f32 v162, v162, v166, v130
	s_mov_b64 vcc, s[26:27]
	v_div_fmas_f32 v161, v161, v165, v129
	s_mov_b64 vcc, s[2:3]
	v_div_fmas_f32 v160, v160, v164, v128
	v_div_fixup_f32 v156, v160, v156, 1.0
	v_div_fixup_f32 v157, v161, v157, 1.0
	v_div_fixup_f32 v158, v162, v158, 1.0
	v_div_fixup_f32 v159, v163, v159, 1.0
	v_lshlrev_b32_e32 v166, 16, v48
	v_and_b32_e32 v167, 0xffff0000, v48
	v_pk_fma_f32 v[152:153], v[20:21], v[152:153], v[166:167]
	v_lshlrev_b32_e32 v166, 16, v49
	v_and_b32_e32 v167, 0xffff0000, v49
	v_pk_fma_f32 v[154:155], v[22:23], v[154:155], v[166:167]
	v_lshlrev_b32_e32 v166, 16, v50
	v_and_b32_e32 v167, 0xffff0000, v50
	v_pk_fma_f32 v[156:157], v[16:17], v[156:157], v[166:167]
	v_lshlrev_b32_e32 v166, 16, v51
	v_and_b32_e32 v167, 0xffff0000, v51
	v_pk_fma_f32 v[158:159], v[18:19], v[158:159], v[166:167]
	v_cvt_pk_bf16_f32 v168, v152, v153
	v_cvt_pk_bf16_f32 v169, v154, v155
	v_cvt_pk_bf16_f32 v170, v156, v157
	v_cvt_pk_bf16_f32 v171, v158, v159
	global_store_dwordx4 v190, v[168:171], s[66:67] offset:256
	s_waitcnt vmcnt(5)
; __device__ __forceinline__ float sigmoidf_(float x) { return 1.f / (1.f + __expf(-x)); }
	v_lshlrev_b32_e32 v152, 16, v44
	v_and_b32_e32 v153, 0xffff0000, v44
	v_lshlrev_b32_e32 v154, 16, v45
	v_and_b32_e32 v155, 0xffff0000, v45
	v_lshlrev_b32_e32 v156, 16, v46
	v_and_b32_e32 v157, 0xffff0000, v46
	v_lshlrev_b32_e32 v158, 16, v47
	v_and_b32_e32 v159, 0xffff0000, v47
	v_mul_f32_e32 v152, 0xbfb8aa3b, v152
	v_mul_f32_e32 v153, 0xbfb8aa3b, v153
	v_mul_f32_e32 v154, 0xbfb8aa3b, v154
	v_mul_f32_e32 v155, 0xbfb8aa3b, v155
	v_mul_f32_e32 v156, 0xbfb8aa3b, v156
	v_mul_f32_e32 v157, 0xbfb8aa3b, v157
	v_mul_f32_e32 v158, 0xbfb8aa3b, v158
	v_mul_f32_e32 v159, 0xbfb8aa3b, v159
	v_exp_f32_e32 v152, v152
	v_exp_f32_e32 v153, v153
	v_exp_f32_e32 v154, v154
	v_exp_f32_e32 v155, v155
	v_exp_f32_e32 v156, v156
	v_exp_f32_e32 v157, v157
	v_exp_f32_e32 v158, v158
	v_exp_f32_e32 v159, v159
	v_pk_add_f32 v[152:153], v[152:153], 1.0 op_sel_hi:[1,0]
	v_pk_add_f32 v[154:155], v[154:155], 1.0 op_sel_hi:[1,0]
	v_pk_add_f32 v[156:157], v[156:157], 1.0 op_sel_hi:[1,0]
	v_pk_add_f32 v[158:159], v[158:159], 1.0 op_sel_hi:[1,0]
	v_div_scale_f32 v160, s[38:39], v152, v152, 1.0
	v_div_scale_f32 v161, s[38:39], v153, v153, 1.0
	v_div_scale_f32 v162, s[38:39], v154, v154, 1.0
	v_div_scale_f32 v163, s[38:39], v155, v155, 1.0
	v_rcp_f32_e32 v164, v160
	v_rcp_f32_e32 v165, v161
	v_rcp_f32_e32 v166, v162
	v_rcp_f32_e32 v167, v163
	v_pk_fma_f32 v[148:149], v[160:161], v[164:165], 1.0 op_sel_hi:[1,1,0] neg_lo:[1,0,0] neg_hi:[1,0,0]
	v_pk_fma_f32 v[150:151], v[162:163], v[166:167], 1.0 op_sel_hi:[1,1,0] neg_lo:[1,0,0] neg_hi:[1,0,0]
	v_pk_fma_f32 v[164:165], v[148:149], v[164:165], v[164:165]
	v_pk_fma_f32 v[166:167], v[150:151], v[166:167], v[166:167]
	v_div_scale_f32 v168, s[2:3], 1.0, v152, 1.0
	v_div_scale_f32 v169, s[26:27], 1.0, v153, 1.0
	v_div_scale_f32 v170, s[28:29], 1.0, v154, 1.0
	v_div_scale_f32 v171, vcc, 1.0, v155, 1.0
	v_pk_mul_f32 v[128:129], v[168:169], v[164:165]
	v_pk_mul_f32 v[130:131], v[170:171], v[166:167]
	v_pk_fma_f32 v[148:149], v[160:161], v[128:129], v[168:169] neg_lo:[1,0,0] neg_hi:[1,0,0]
	v_pk_fma_f32 v[150:151], v[162:163], v[130:131], v[170:171] neg_lo:[1,0,0] neg_hi:[1,0,0]
	v_pk_fma_f32 v[128:129], v[148:149], v[164:165], v[128:129]
	v_pk_fma_f32 v[130:131], v[150:151], v[166:167], v[130:131]
	v_pk_fma_f32 v[160:161], v[160:161], v[128:129], v[168:169] neg_lo:[1,0,0] neg_hi:[1,0,0]
	v_pk_fma_f32 v[162:163], v[162:163], v[130:131], v[170:171] neg_lo:[1,0,0] neg_hi:[1,0,0]
	v_div_fmas_f32 v163, v163, v167, v131
	s_mov_b64 vcc, s[28:29]
	v_div_fmas_f32 v162, v162, v166, v130
	s_mov_b64 vcc, s[26:27]
	v_div_fmas_f32 v161, v161, v165, v129
	s_mov_b64 vcc, s[2:3]
	v_div_fmas_f32 v160, v160, v164, v128
	v_div_fixup_f32 v152, v160, v152, 1.0
	v_div_fixup_f32 v153, v161, v153, 1.0
	v_div_fixup_f32 v154, v162, v154, 1.0
	v_div_fixup_f32 v155, v163, v155, 1.0
	v_div_scale_f32 v160, s[38:39], v156, v156, 1.0
	v_div_scale_f32 v161, s[38:39], v157, v157, 1.0
	v_div_scale_f32 v162, s[38:39], v158, v158, 1.0
	v_div_scale_f32 v163, s[38:39], v159, v159, 1.0
	v_rcp_f32_e32 v164, v160
	v_rcp_f32_e32 v165, v161
	v_rcp_f32_e32 v166, v162
	v_rcp_f32_e32 v167, v163
	v_pk_fma_f32 v[148:149], v[160:161], v[164:165], 1.0 op_sel_hi:[1,1,0] neg_lo:[1,0,0] neg_hi:[1,0,0]
	v_pk_fma_f32 v[150:151], v[162:163], v[166:167], 1.0 op_sel_hi:[1,1,0] neg_lo:[1,0,0] neg_hi:[1,0,0]
	v_pk_fma_f32 v[164:165], v[148:149], v[164:165], v[164:165]
	v_pk_fma_f32 v[166:167], v[150:151], v[166:167], v[166:167]
	v_div_scale_f32 v168, s[2:3], 1.0, v156, 1.0
	v_div_scale_f32 v169, s[26:27], 1.0, v157, 1.0
	v_div_scale_f32 v170, s[28:29], 1.0, v158, 1.0
	v_div_scale_f32 v171, vcc, 1.0, v159, 1.0
	v_pk_mul_f32 v[128:129], v[168:169], v[164:165]
	v_pk_mul_f32 v[130:131], v[170:171], v[166:167]
	v_pk_fma_f32 v[148:149], v[160:161], v[128:129], v[168:169] neg_lo:[1,0,0] neg_hi:[1,0,0]
	v_pk_fma_f32 v[150:151], v[162:163], v[130:131], v[170:171] neg_lo:[1,0,0] neg_hi:[1,0,0]
	v_pk_fma_f32 v[128:129], v[148:149], v[164:165], v[128:129]
	v_pk_fma_f32 v[130:131], v[150:151], v[166:167], v[130:131]
	v_pk_fma_f32 v[160:161], v[160:161], v[128:129], v[168:169] neg_lo:[1,0,0] neg_hi:[1,0,0]
	v_pk_fma_f32 v[162:163], v[162:163], v[130:131], v[170:171] neg_lo:[1,0,0] neg_hi:[1,0,0]
	v_div_fmas_f32 v163, v163, v167, v131
	s_mov_b64 vcc, s[28:29]
	v_div_fmas_f32 v162, v162, v166, v130
	s_mov_b64 vcc, s[26:27]
	v_div_fmas_f32 v161, v161, v165, v129
	s_mov_b64 vcc, s[2:3]
	v_div_fmas_f32 v160, v160, v164, v128
	v_div_fixup_f32 v156, v160, v156, 1.0
	v_div_fixup_f32 v157, v161, v157, 1.0
	v_div_fixup_f32 v158, v162, v158, 1.0
	v_div_fixup_f32 v159, v163, v159, 1.0
	v_lshlrev_b32_e32 v166, 16, v40
	v_and_b32_e32 v167, 0xffff0000, v40
	v_pk_fma_f32 v[152:153], v[12:13], v[152:153], v[166:167]
	v_lshlrev_b32_e32 v166, 16, v41
	v_and_b32_e32 v167, 0xffff0000, v41
	v_pk_fma_f32 v[154:155], v[14:15], v[154:155], v[166:167]
	v_lshlrev_b32_e32 v166, 16, v42
	v_and_b32_e32 v167, 0xffff0000, v42
	v_pk_fma_f32 v[156:157], v[8:9], v[156:157], v[166:167]
	v_lshlrev_b32_e32 v166, 16, v43
	v_and_b32_e32 v167, 0xffff0000, v43
	v_pk_fma_f32 v[158:159], v[10:11], v[158:159], v[166:167]
	v_cvt_pk_bf16_f32 v168, v152, v153
	v_cvt_pk_bf16_f32 v169, v154, v155
	v_cvt_pk_bf16_f32 v170, v156, v157
	v_cvt_pk_bf16_f32 v171, v158, v159
	global_store_dwordx4 v191, v[168:171], s[66:67]
	s_waitcnt vmcnt(3)
; __device__ __forceinline__ float sigmoidf_(float x) { return 1.f / (1.f + __expf(-x)); }
	v_lshlrev_b32_e32 v152, 16, v36
	v_and_b32_e32 v153, 0xffff0000, v36
	v_lshlrev_b32_e32 v154, 16, v37
	v_and_b32_e32 v155, 0xffff0000, v37
	v_lshlrev_b32_e32 v156, 16, v38
	v_and_b32_e32 v157, 0xffff0000, v38
	v_lshlrev_b32_e32 v158, 16, v39
	v_and_b32_e32 v159, 0xffff0000, v39
	v_mul_f32_e32 v152, 0xbfb8aa3b, v152
	v_mul_f32_e32 v153, 0xbfb8aa3b, v153
	v_mul_f32_e32 v154, 0xbfb8aa3b, v154
	v_mul_f32_e32 v155, 0xbfb8aa3b, v155
	v_mul_f32_e32 v156, 0xbfb8aa3b, v156
	v_mul_f32_e32 v157, 0xbfb8aa3b, v157
	v_mul_f32_e32 v158, 0xbfb8aa3b, v158
	v_mul_f32_e32 v159, 0xbfb8aa3b, v159
	v_exp_f32_e32 v152, v152
	v_exp_f32_e32 v153, v153
	v_exp_f32_e32 v154, v154
	v_exp_f32_e32 v155, v155
	v_exp_f32_e32 v156, v156
	v_exp_f32_e32 v157, v157
	v_exp_f32_e32 v158, v158
	v_exp_f32_e32 v159, v159
	v_pk_add_f32 v[152:153], v[152:153], 1.0 op_sel_hi:[1,0]
	v_pk_add_f32 v[154:155], v[154:155], 1.0 op_sel_hi:[1,0]
	v_pk_add_f32 v[156:157], v[156:157], 1.0 op_sel_hi:[1,0]
	v_pk_add_f32 v[158:159], v[158:159], 1.0 op_sel_hi:[1,0]
	v_div_scale_f32 v160, s[38:39], v152, v152, 1.0
	v_div_scale_f32 v161, s[38:39], v153, v153, 1.0
	v_div_scale_f32 v162, s[38:39], v154, v154, 1.0
	v_div_scale_f32 v163, s[38:39], v155, v155, 1.0
	v_rcp_f32_e32 v164, v160
	v_rcp_f32_e32 v165, v161
	v_rcp_f32_e32 v166, v162
	v_rcp_f32_e32 v167, v163
	v_pk_fma_f32 v[148:149], v[160:161], v[164:165], 1.0 op_sel_hi:[1,1,0] neg_lo:[1,0,0] neg_hi:[1,0,0]
	v_pk_fma_f32 v[150:151], v[162:163], v[166:167], 1.0 op_sel_hi:[1,1,0] neg_lo:[1,0,0] neg_hi:[1,0,0]
	v_pk_fma_f32 v[164:165], v[148:149], v[164:165], v[164:165]
	v_pk_fma_f32 v[166:167], v[150:151], v[166:167], v[166:167]
	v_div_scale_f32 v168, s[2:3], 1.0, v152, 1.0
	v_div_scale_f32 v169, s[26:27], 1.0, v153, 1.0
	v_div_scale_f32 v170, s[28:29], 1.0, v154, 1.0
	v_div_scale_f32 v171, vcc, 1.0, v155, 1.0
	v_pk_mul_f32 v[128:129], v[168:169], v[164:165]
	v_pk_mul_f32 v[130:131], v[170:171], v[166:167]
	v_pk_fma_f32 v[148:149], v[160:161], v[128:129], v[168:169] neg_lo:[1,0,0] neg_hi:[1,0,0]
	v_pk_fma_f32 v[150:151], v[162:163], v[130:131], v[170:171] neg_lo:[1,0,0] neg_hi:[1,0,0]
	v_pk_fma_f32 v[128:129], v[148:149], v[164:165], v[128:129]
	v_pk_fma_f32 v[130:131], v[150:151], v[166:167], v[130:131]
	v_pk_fma_f32 v[160:161], v[160:161], v[128:129], v[168:169] neg_lo:[1,0,0] neg_hi:[1,0,0]
	v_pk_fma_f32 v[162:163], v[162:163], v[130:131], v[170:171] neg_lo:[1,0,0] neg_hi:[1,0,0]
	v_div_fmas_f32 v163, v163, v167, v131
	s_mov_b64 vcc, s[28:29]
	v_div_fmas_f32 v162, v162, v166, v130
	s_mov_b64 vcc, s[26:27]
	v_div_fmas_f32 v161, v161, v165, v129
	s_mov_b64 vcc, s[2:3]
	v_div_fmas_f32 v160, v160, v164, v128
	v_div_fixup_f32 v152, v160, v152, 1.0
	v_div_fixup_f32 v153, v161, v153, 1.0
	v_div_fixup_f32 v154, v162, v154, 1.0
	v_div_fixup_f32 v155, v163, v155, 1.0
	v_div_scale_f32 v160, s[38:39], v156, v156, 1.0
	v_div_scale_f32 v161, s[38:39], v157, v157, 1.0
	v_div_scale_f32 v162, s[38:39], v158, v158, 1.0
	v_div_scale_f32 v163, s[38:39], v159, v159, 1.0
	v_rcp_f32_e32 v164, v160
	v_rcp_f32_e32 v165, v161
	v_rcp_f32_e32 v166, v162
	v_rcp_f32_e32 v167, v163
	v_pk_fma_f32 v[148:149], v[160:161], v[164:165], 1.0 op_sel_hi:[1,1,0] neg_lo:[1,0,0] neg_hi:[1,0,0]
	v_pk_fma_f32 v[150:151], v[162:163], v[166:167], 1.0 op_sel_hi:[1,1,0] neg_lo:[1,0,0] neg_hi:[1,0,0]
	v_pk_fma_f32 v[164:165], v[148:149], v[164:165], v[164:165]
	v_pk_fma_f32 v[166:167], v[150:151], v[166:167], v[166:167]
	v_div_scale_f32 v168, s[2:3], 1.0, v156, 1.0
	v_div_scale_f32 v169, s[26:27], 1.0, v157, 1.0
	v_div_scale_f32 v170, s[28:29], 1.0, v158, 1.0
	v_div_scale_f32 v171, vcc, 1.0, v159, 1.0
	v_pk_mul_f32 v[128:129], v[168:169], v[164:165]
	v_pk_mul_f32 v[130:131], v[170:171], v[166:167]
	v_pk_fma_f32 v[148:149], v[160:161], v[128:129], v[168:169] neg_lo:[1,0,0] neg_hi:[1,0,0]
	v_pk_fma_f32 v[150:151], v[162:163], v[130:131], v[170:171] neg_lo:[1,0,0] neg_hi:[1,0,0]
	v_pk_fma_f32 v[128:129], v[148:149], v[164:165], v[128:129]
	v_pk_fma_f32 v[130:131], v[150:151], v[166:167], v[130:131]
	v_pk_fma_f32 v[160:161], v[160:161], v[128:129], v[168:169] neg_lo:[1,0,0] neg_hi:[1,0,0]
	v_pk_fma_f32 v[162:163], v[162:163], v[130:131], v[170:171] neg_lo:[1,0,0] neg_hi:[1,0,0]
	v_div_fmas_f32 v163, v163, v167, v131
	s_mov_b64 vcc, s[28:29]
	v_div_fmas_f32 v162, v162, v166, v130
	s_mov_b64 vcc, s[26:27]
	v_div_fmas_f32 v161, v161, v165, v129
	s_mov_b64 vcc, s[2:3]
	v_div_fmas_f32 v160, v160, v164, v128
	v_div_fixup_f32 v156, v160, v156, 1.0
	v_div_fixup_f32 v157, v161, v157, 1.0
	v_div_fixup_f32 v158, v162, v158, 1.0
	v_div_fixup_f32 v159, v163, v159, 1.0
	v_lshlrev_b32_e32 v166, 16, v32
	v_and_b32_e32 v167, 0xffff0000, v32
	v_pk_fma_f32 v[152:153], v[4:5], v[152:153], v[166:167]
	v_lshlrev_b32_e32 v166, 16, v33
	v_and_b32_e32 v167, 0xffff0000, v33
	v_pk_fma_f32 v[154:155], v[6:7], v[154:155], v[166:167]
	v_lshlrev_b32_e32 v166, 16, v34
	v_and_b32_e32 v167, 0xffff0000, v34
	v_pk_fma_f32 v[156:157], v[0:1], v[156:157], v[166:167]
	v_lshlrev_b32_e32 v166, 16, v35
	v_and_b32_e32 v167, 0xffff0000, v35
	v_pk_fma_f32 v[158:159], v[2:3], v[158:159], v[166:167]
	v_cvt_pk_bf16_f32 v168, v152, v153
	v_cvt_pk_bf16_f32 v169, v154, v155
	v_cvt_pk_bf16_f32 v170, v156, v157
	v_cvt_pk_bf16_f32 v171, v158, v159
	global_store_dwordx4 v191, v[168:171], s[66:67] offset:256
	s_mov_b32 s32, 1
	s_branch .LBB0_567
